# merge phase: no static priority raise for waves 4-7 (s_setprio 0 at tile entry)
# speedup vs baseline: 1.0062x; 1.0062x over previous
.LBB0_1004:
	s_setprio 0
	v_and_b32_e32 v2, 7, v192
	v_lshrrev_b32_e32 v3, 3, v192
	v_bfe_u32 v4, v192, 4, 3
	v_xor_b32_e32 v2, v2, v4
	v_lshlrev_b32_e32 v2, 4, v2
	v_mul_u32_u24_e32 v4, 0x3e00, v3
	v_add_u32_e32 v188, v4, v2
	v_add_u32_e32 v189, 0xf8000, v188
	v_add_u32_e32 v190, 0x1f0000, v188
	v_add_u32_e32 v191, 0x2e8000, v188
	v_and_b32_e32 v4, 35, v3
	v_bfe_u32 v5, v3, 4, 1
	v_lshl_or_b32 v4, v5, 2, v4
	v_bfe_u32 v5, v3, 2, 2
	v_lshl_or_b32 v4, v5, 3, v4
	v_lshl_or_b32 v205, v4, 10, v2
	v_add_u32_e32 v206, 0x10000, v205
	v_bfe_u32 v2, v192, 1, 3
	v_bfe_u32 v3, v192, 4, 2
	v_xor_b32_e32 v2, v2, v3
	v_lshlrev_b32_e32 v2, 4, v2
	v_and_b32_e32 v3, 15, v192
	v_lshrrev_b32_e32 v4, 7, v192
	v_lshl_or_b32 v4, v4, 6, v3
	v_lshl_or_b32 v207, v4, 7, v2
	v_xor_b32_e32 v119, 64, v207
	v_add_u32_e32 v0, 0x10000, v207
	v_add_u32_e32 v255, 0x10000, v119
	v_bfe_u32 v4, v192, 6, 1
	v_lshl_or_b32 v4, v4, 6, v3
	v_lshl_or_b32 v4, v4, 7, v2
	v_add_u32_e32 v90, 0x18000, v4
	v_xor_b32_e32 v91, 64, v90
	v_lshrrev_b32_e32 v5, 6, v192
	s_nop 0
	v_readfirstlane_b32 s67, v5
	s_lshl_b32 s67, s67, 10
	s_add_u32 s80, s46, 0xc00
	s_addc_u32 s81, s47, 0
	s_mov_b32 s96, s48
	s_mov_b32 s97, s49
	v_lshrrev_b32_e32 v2, 4, v192
	v_mul_u32_u24_e32 v2, 0x3e00, v2
	v_and_b32_e32 v3, 15, v192
	v_lshl_or_b32 v93, v3, 6, v2
	s_lshr_b32 s32, s13, 17
	s_mul_i32 s32, s32, 0x7c000
	s_add_u32 s86, s46, s32
	s_addc_u32 s87, s47, 0
	s_add_u32 s98, s86, 0x1000
	s_addc_u32 s99, s87, 0
	global_load_dword v92, v93, s[98:99]
	s_add_i32 m0, s67, 0x0
	s_nop 0
	global_load_lds_dwordx4 v188, s[80:81]
	s_add_i32 m0, s67, 0x2000
	s_nop 0
	global_load_lds_dwordx4 v189, s[80:81]
	s_add_i32 m0, s67, 0x4000
	s_nop 0
	global_load_lds_dwordx4 v190, s[80:81]
	s_add_i32 m0, s67, 0x6000
	s_nop 0
	global_load_lds_dwordx4 v191, s[80:81]
	s_add_i32 m0, s67, 0x18000
	s_nop 0
	global_load_lds_dwordx4 v205, s[96:97]
	s_add_i32 m0, s67, 0x1a000
	s_nop 0
	global_load_lds_dwordx4 v206, s[96:97]
	s_add_u32 s80, s80, 0x80
	s_addc_u32 s81, s81, 0
	s_add_u32 s96, s96, 0x80
	s_addc_u32 s97, s97, 0
	s_add_i32 m0, s67, 0x8000
	s_nop 0
	global_load_lds_dwordx4 v188, s[80:81]
	s_add_i32 m0, s67, 0xa000
	s_nop 0
	global_load_lds_dwordx4 v189, s[80:81]
	s_add_i32 m0, s67, 0xc000
	s_nop 0
	global_load_lds_dwordx4 v190, s[80:81]
	s_add_i32 m0, s67, 0xe000
	s_nop 0
	global_load_lds_dwordx4 v191, s[80:81]
	s_add_i32 m0, s67, 0x1c000
	s_nop 0
	global_load_lds_dwordx4 v205, s[96:97]
	s_add_i32 m0, s67, 0x1e000
	s_nop 0
	global_load_lds_dwordx4 v206, s[96:97]
	s_add_u32 s80, s80, 0x80
	s_addc_u32 s81, s81, 0
	s_add_u32 s96, s96, 0x80
	s_addc_u32 s97, s97, 0
	s_add_i32 m0, s67, 0x10000
	s_nop 0
	global_load_lds_dwordx4 v188, s[80:81]
	s_add_i32 m0, s67, 0x12000
	s_nop 0
	global_load_lds_dwordx4 v189, s[80:81]
	s_add_i32 m0, s67, 0x14000
	s_nop 0
	global_load_lds_dwordx4 v190, s[80:81]
	s_add_i32 m0, s67, 0x16000
	s_nop 0
	global_load_lds_dwordx4 v191, s[80:81]
	s_add_i32 m0, s67, 0x20400
	s_nop 0
	global_load_lds_dwordx4 v205, s[96:97]
	s_add_i32 m0, s67, 0x22400
	s_nop 0
	global_load_lds_dwordx4 v206, s[96:97]
	s_add_u32 s80, s80, 0x80
	s_addc_u32 s81, s81, 0
	s_add_u32 s96, s96, 0x80
	s_addc_u32 s97, s97, 0
	s_waitcnt vmcnt(12)
	s_barrier
	ds_read_b128 v[82:85], v90 offset:0
	ds_read_b128 v[86:89], v90 offset:2048
	ds_read_b128 v[208:211], v90 offset:4096
	ds_read_b128 v[212:215], v90 offset:6144
	ds_read_b128 v[66:69], v207 offset:0
	ds_read_b128 v[70:73], v207 offset:2048
	ds_read_b128 v[74:77], v207 offset:4096
	ds_read_b128 v[78:81], v207 offset:6144
	ds_read_b128 v[216:219], v91 offset:0
	ds_read_b128 v[220:223], v91 offset:2048
	ds_read_b128 v[224:227], v91 offset:4096
	ds_read_b128 v[228:231], v91 offset:6144
	s_waitcnt lgkmcnt(7)
	v_mfma_f32_16x16x32_bf16 v[6:9], v[82:85], v[66:69], 0
	v_mfma_f32_16x16x32_bf16 v[30:33], v[86:89], v[66:69], 0
	v_mfma_f32_16x16x32_bf16 v[38:41], v[208:211], v[66:69], 0
	v_mfma_f32_16x16x32_bf16 v[42:45], v[212:215], v[66:69], 0
	ds_read_b128 v[66:69], v119 offset:0
	s_waitcnt lgkmcnt(7)
	v_mfma_f32_16x16x32_bf16 v[46:49], v[82:85], v[70:73], 0
	v_mfma_f32_16x16x32_bf16 v[26:29], v[86:89], v[70:73], 0
	v_mfma_f32_16x16x32_bf16 v[14:17], v[208:211], v[70:73], 0
	v_mfma_f32_16x16x32_bf16 v[10:13], v[212:215], v[70:73], 0
	ds_read_b128 v[70:73], v119 offset:2048
	s_waitcnt lgkmcnt(7)
	v_mfma_f32_16x16x32_bf16 v[34:37], v[82:85], v[74:77], 0
	v_mfma_f32_16x16x32_bf16 v[22:25], v[86:89], v[74:77], 0
	v_mfma_f32_16x16x32_bf16 v[18:21], v[208:211], v[74:77], 0
	v_mfma_f32_16x16x32_bf16 v[62:65], v[212:215], v[74:77], 0
	ds_read_b128 v[74:77], v119 offset:4096
	s_waitcnt lgkmcnt(7)
	v_mfma_f32_16x16x32_bf16 v[58:61], v[82:85], v[78:81], 0
	v_mfma_f32_16x16x32_bf16 v[54:57], v[86:89], v[78:81], 0
	v_mfma_f32_16x16x32_bf16 v[50:53], v[208:211], v[78:81], 0
	v_mfma_f32_16x16x32_bf16 v[2:5], v[212:215], v[78:81], 0
	ds_read_b128 v[78:81], v119 offset:6144
	s_waitcnt lgkmcnt(3)
	v_mfma_f32_16x16x32_bf16 v[6:9], v[216:219], v[66:69], v[6:9]
	v_mfma_f32_16x16x32_bf16 v[30:33], v[220:223], v[66:69], v[30:33]
	v_mfma_f32_16x16x32_bf16 v[38:41], v[224:227], v[66:69], v[38:41]
	v_mfma_f32_16x16x32_bf16 v[42:45], v[228:231], v[66:69], v[42:45]
	s_waitcnt lgkmcnt(2)
	v_mfma_f32_16x16x32_bf16 v[46:49], v[216:219], v[70:73], v[46:49]
	v_mfma_f32_16x16x32_bf16 v[26:29], v[220:223], v[70:73], v[26:29]
	v_mfma_f32_16x16x32_bf16 v[14:17], v[224:227], v[70:73], v[14:17]
	v_mfma_f32_16x16x32_bf16 v[10:13], v[228:231], v[70:73], v[10:13]
	s_waitcnt vmcnt(6)
	s_waitcnt lgkmcnt(0)
	s_barrier
	s_add_i32 m0, s67, 0x0
	s_nop 0
	global_load_lds_dwordx4 v188, s[80:81]
	s_add_i32 m0, s67, 0x2000
	s_nop 0
	global_load_lds_dwordx4 v189, s[80:81]
	s_add_i32 m0, s67, 0x4000
	s_nop 0
	global_load_lds_dwordx4 v190, s[80:81]
	s_add_i32 m0, s67, 0x6000
	s_nop 0
	global_load_lds_dwordx4 v191, s[80:81]
	s_add_i32 m0, s67, 0x18000
	s_nop 0
	global_load_lds_dwordx4 v205, s[96:97]
	s_add_i32 m0, s67, 0x1a000
	s_nop 0
	global_load_lds_dwordx4 v206, s[96:97]
	s_add_u32 s80, s80, 0x80
	s_addc_u32 s81, s81, 0
	s_add_u32 s96, s96, 0x80
	s_addc_u32 s97, s97, 0
	ds_read_b128 v[82:85], v90 offset:16384
	ds_read_b128 v[86:89], v90 offset:18432
	ds_read_b128 v[208:211], v90 offset:20480
	ds_read_b128 v[212:215], v90 offset:22528
	ds_read_b128 v[66:69], v207 offset:32768
	ds_read_b128 v[70:73], v207 offset:34816
	v_mfma_f32_16x16x32_bf16 v[34:37], v[216:219], v[74:77], v[34:37]
	v_mfma_f32_16x16x32_bf16 v[22:25], v[220:223], v[74:77], v[22:25]
	v_mfma_f32_16x16x32_bf16 v[18:21], v[224:227], v[74:77], v[18:21]
	v_mfma_f32_16x16x32_bf16 v[62:65], v[228:231], v[74:77], v[62:65]
	ds_read_b128 v[74:77], v207 offset:36864
	v_mfma_f32_16x16x32_bf16 v[58:61], v[216:219], v[78:81], v[58:61]
	v_mfma_f32_16x16x32_bf16 v[54:57], v[220:223], v[78:81], v[54:57]
	v_mfma_f32_16x16x32_bf16 v[50:53], v[224:227], v[78:81], v[50:53]
	v_mfma_f32_16x16x32_bf16 v[2:5], v[228:231], v[78:81], v[2:5]
	ds_read_b128 v[78:81], v207 offset:38912
	ds_read_b128 v[216:219], v91 offset:16384
	ds_read_b128 v[220:223], v91 offset:18432
	ds_read_b128 v[224:227], v91 offset:20480
	ds_read_b128 v[228:231], v91 offset:22528
	s_waitcnt lgkmcnt(7)
	v_mfma_f32_16x16x32_bf16 v[6:9], v[82:85], v[66:69], v[6:9]
	v_mfma_f32_16x16x32_bf16 v[30:33], v[86:89], v[66:69], v[30:33]
	v_mfma_f32_16x16x32_bf16 v[38:41], v[208:211], v[66:69], v[38:41]
	v_mfma_f32_16x16x32_bf16 v[42:45], v[212:215], v[66:69], v[42:45]
	ds_read_b128 v[66:69], v119 offset:32768
	s_waitcnt lgkmcnt(7)
	v_mfma_f32_16x16x32_bf16 v[46:49], v[82:85], v[70:73], v[46:49]
	v_mfma_f32_16x16x32_bf16 v[26:29], v[86:89], v[70:73], v[26:29]
	v_mfma_f32_16x16x32_bf16 v[14:17], v[208:211], v[70:73], v[14:17]
	v_mfma_f32_16x16x32_bf16 v[10:13], v[212:215], v[70:73], v[10:13]
	ds_read_b128 v[70:73], v119 offset:34816
	s_waitcnt lgkmcnt(7)
	v_mfma_f32_16x16x32_bf16 v[34:37], v[82:85], v[74:77], v[34:37]
	v_mfma_f32_16x16x32_bf16 v[22:25], v[86:89], v[74:77], v[22:25]
	v_mfma_f32_16x16x32_bf16 v[18:21], v[208:211], v[74:77], v[18:21]
	v_mfma_f32_16x16x32_bf16 v[62:65], v[212:215], v[74:77], v[62:65]
	ds_read_b128 v[74:77], v119 offset:36864
	s_waitcnt lgkmcnt(7)
	v_mfma_f32_16x16x32_bf16 v[58:61], v[82:85], v[78:81], v[58:61]
	v_mfma_f32_16x16x32_bf16 v[54:57], v[86:89], v[78:81], v[54:57]
	v_mfma_f32_16x16x32_bf16 v[50:53], v[208:211], v[78:81], v[50:53]
	v_mfma_f32_16x16x32_bf16 v[2:5], v[212:215], v[78:81], v[2:5]
	ds_read_b128 v[78:81], v119 offset:38912
	s_waitcnt lgkmcnt(3)
	v_mfma_f32_16x16x32_bf16 v[6:9], v[216:219], v[66:69], v[6:9]
	v_mfma_f32_16x16x32_bf16 v[30:33], v[220:223], v[66:69], v[30:33]
	v_mfma_f32_16x16x32_bf16 v[38:41], v[224:227], v[66:69], v[38:41]
	v_mfma_f32_16x16x32_bf16 v[42:45], v[228:231], v[66:69], v[42:45]
	s_waitcnt lgkmcnt(2)
	v_mfma_f32_16x16x32_bf16 v[46:49], v[216:219], v[70:73], v[46:49]
	v_mfma_f32_16x16x32_bf16 v[26:29], v[220:223], v[70:73], v[26:29]
	v_mfma_f32_16x16x32_bf16 v[14:17], v[224:227], v[70:73], v[14:17]
	v_mfma_f32_16x16x32_bf16 v[10:13], v[228:231], v[70:73], v[10:13]
	s_waitcnt vmcnt(6)
	s_waitcnt lgkmcnt(0)
	s_barrier
	s_add_i32 m0, s67, 0x8000
	s_nop 0
	global_load_lds_dwordx4 v188, s[80:81]
	s_add_i32 m0, s67, 0xa000
	s_nop 0
	global_load_lds_dwordx4 v189, s[80:81]
	s_add_i32 m0, s67, 0xc000
	s_nop 0
	global_load_lds_dwordx4 v190, s[80:81]
	s_add_i32 m0, s67, 0xe000
	s_nop 0
	global_load_lds_dwordx4 v191, s[80:81]
	s_add_i32 m0, s67, 0x1c000
	s_nop 0
	global_load_lds_dwordx4 v205, s[96:97]
	s_add_i32 m0, s67, 0x1e000
	s_nop 0
	global_load_lds_dwordx4 v206, s[96:97]
	s_add_u32 s80, s80, 0x80
	s_addc_u32 s81, s81, 0
	s_add_u32 s96, s96, 0x80
	s_addc_u32 s97, s97, 0
	ds_read_b128 v[82:85], v90 offset:33792
	ds_read_b128 v[86:89], v90 offset:35840
	ds_read_b128 v[208:211], v90 offset:37888
	ds_read_b128 v[212:215], v90 offset:39936
	ds_read_b128 v[66:69], v0 offset:0
	ds_read_b128 v[70:73], v0 offset:2048
	v_mfma_f32_16x16x32_bf16 v[34:37], v[216:219], v[74:77], v[34:37]
	v_mfma_f32_16x16x32_bf16 v[22:25], v[220:223], v[74:77], v[22:25]
	v_mfma_f32_16x16x32_bf16 v[18:21], v[224:227], v[74:77], v[18:21]
	v_mfma_f32_16x16x32_bf16 v[62:65], v[228:231], v[74:77], v[62:65]
	ds_read_b128 v[74:77], v0 offset:4096
	v_mfma_f32_16x16x32_bf16 v[58:61], v[216:219], v[78:81], v[58:61]
	v_mfma_f32_16x16x32_bf16 v[54:57], v[220:223], v[78:81], v[54:57]
	v_mfma_f32_16x16x32_bf16 v[50:53], v[224:227], v[78:81], v[50:53]
	v_mfma_f32_16x16x32_bf16 v[2:5], v[228:231], v[78:81], v[2:5]
	ds_read_b128 v[78:81], v0 offset:6144
	ds_read_b128 v[216:219], v91 offset:33792
	ds_read_b128 v[220:223], v91 offset:35840
	ds_read_b128 v[224:227], v91 offset:37888
	ds_read_b128 v[228:231], v91 offset:39936
	s_waitcnt lgkmcnt(7)
	v_mfma_f32_16x16x32_bf16 v[6:9], v[82:85], v[66:69], v[6:9]
	v_mfma_f32_16x16x32_bf16 v[30:33], v[86:89], v[66:69], v[30:33]
	v_mfma_f32_16x16x32_bf16 v[38:41], v[208:211], v[66:69], v[38:41]
	v_mfma_f32_16x16x32_bf16 v[42:45], v[212:215], v[66:69], v[42:45]
	ds_read_b128 v[66:69], v255 offset:0
	s_waitcnt lgkmcnt(7)
	v_mfma_f32_16x16x32_bf16 v[46:49], v[82:85], v[70:73], v[46:49]
	v_mfma_f32_16x16x32_bf16 v[26:29], v[86:89], v[70:73], v[26:29]
	v_mfma_f32_16x16x32_bf16 v[14:17], v[208:211], v[70:73], v[14:17]
	v_mfma_f32_16x16x32_bf16 v[10:13], v[212:215], v[70:73], v[10:13]
	ds_read_b128 v[70:73], v255 offset:2048
	s_waitcnt lgkmcnt(7)
	v_mfma_f32_16x16x32_bf16 v[34:37], v[82:85], v[74:77], v[34:37]
	v_mfma_f32_16x16x32_bf16 v[22:25], v[86:89], v[74:77], v[22:25]
	v_mfma_f32_16x16x32_bf16 v[18:21], v[208:211], v[74:77], v[18:21]
	v_mfma_f32_16x16x32_bf16 v[62:65], v[212:215], v[74:77], v[62:65]
	ds_read_b128 v[74:77], v255 offset:4096
	s_waitcnt lgkmcnt(7)
	v_mfma_f32_16x16x32_bf16 v[58:61], v[82:85], v[78:81], v[58:61]
	v_mfma_f32_16x16x32_bf16 v[54:57], v[86:89], v[78:81], v[54:57]
	v_mfma_f32_16x16x32_bf16 v[50:53], v[208:211], v[78:81], v[50:53]
	v_mfma_f32_16x16x32_bf16 v[2:5], v[212:215], v[78:81], v[2:5]
	ds_read_b128 v[78:81], v255 offset:6144
	s_waitcnt lgkmcnt(3)
	v_mfma_f32_16x16x32_bf16 v[6:9], v[216:219], v[66:69], v[6:9]
	v_mfma_f32_16x16x32_bf16 v[30:33], v[220:223], v[66:69], v[30:33]
	v_mfma_f32_16x16x32_bf16 v[38:41], v[224:227], v[66:69], v[38:41]
	v_mfma_f32_16x16x32_bf16 v[42:45], v[228:231], v[66:69], v[42:45]
	s_waitcnt lgkmcnt(2)
	v_mfma_f32_16x16x32_bf16 v[46:49], v[216:219], v[70:73], v[46:49]
	v_mfma_f32_16x16x32_bf16 v[26:29], v[220:223], v[70:73], v[26:29]
	v_mfma_f32_16x16x32_bf16 v[14:17], v[224:227], v[70:73], v[14:17]
	v_mfma_f32_16x16x32_bf16 v[10:13], v[228:231], v[70:73], v[10:13]
	s_waitcnt vmcnt(6)
	s_waitcnt lgkmcnt(0)
	s_barrier
	s_add_i32 m0, s67, 0x10000
	s_nop 0
	global_load_lds_dwordx4 v188, s[80:81]
	s_add_i32 m0, s67, 0x12000
	s_nop 0
	global_load_lds_dwordx4 v189, s[80:81]
	s_add_i32 m0, s67, 0x14000
	s_nop 0
	global_load_lds_dwordx4 v190, s[80:81]
	s_add_i32 m0, s67, 0x16000
	s_nop 0
	global_load_lds_dwordx4 v191, s[80:81]
	s_add_i32 m0, s67, 0x20400
	s_nop 0
	global_load_lds_dwordx4 v205, s[96:97]
	s_add_i32 m0, s67, 0x22400
	s_nop 0
	global_load_lds_dwordx4 v206, s[96:97]
	s_add_u32 s80, s80, 0x80
	s_addc_u32 s81, s81, 0
	s_add_u32 s96, s96, 0x80
	s_addc_u32 s97, s97, 0
	ds_read_b128 v[82:85], v90 offset:0
	ds_read_b128 v[86:89], v90 offset:2048
	ds_read_b128 v[208:211], v90 offset:4096
	ds_read_b128 v[212:215], v90 offset:6144
	ds_read_b128 v[66:69], v207 offset:0
	ds_read_b128 v[70:73], v207 offset:2048
	v_mfma_f32_16x16x32_bf16 v[34:37], v[216:219], v[74:77], v[34:37]
	v_mfma_f32_16x16x32_bf16 v[22:25], v[220:223], v[74:77], v[22:25]
	v_mfma_f32_16x16x32_bf16 v[18:21], v[224:227], v[74:77], v[18:21]
	v_mfma_f32_16x16x32_bf16 v[62:65], v[228:231], v[74:77], v[62:65]
	ds_read_b128 v[74:77], v207 offset:4096
	v_mfma_f32_16x16x32_bf16 v[58:61], v[216:219], v[78:81], v[58:61]
	v_mfma_f32_16x16x32_bf16 v[54:57], v[220:223], v[78:81], v[54:57]
	v_mfma_f32_16x16x32_bf16 v[50:53], v[224:227], v[78:81], v[50:53]
	v_mfma_f32_16x16x32_bf16 v[2:5], v[228:231], v[78:81], v[2:5]
	ds_read_b128 v[78:81], v207 offset:6144
	ds_read_b128 v[216:219], v91 offset:0
	ds_read_b128 v[220:223], v91 offset:2048
	ds_read_b128 v[224:227], v91 offset:4096
	ds_read_b128 v[228:231], v91 offset:6144
	s_waitcnt lgkmcnt(7)
	v_mfma_f32_16x16x32_bf16 v[6:9], v[82:85], v[66:69], v[6:9]
	v_mfma_f32_16x16x32_bf16 v[30:33], v[86:89], v[66:69], v[30:33]
	v_mfma_f32_16x16x32_bf16 v[38:41], v[208:211], v[66:69], v[38:41]
	v_mfma_f32_16x16x32_bf16 v[42:45], v[212:215], v[66:69], v[42:45]
	ds_read_b128 v[66:69], v119 offset:0
	s_waitcnt lgkmcnt(7)
	v_mfma_f32_16x16x32_bf16 v[46:49], v[82:85], v[70:73], v[46:49]
	v_mfma_f32_16x16x32_bf16 v[26:29], v[86:89], v[70:73], v[26:29]
	v_mfma_f32_16x16x32_bf16 v[14:17], v[208:211], v[70:73], v[14:17]
	v_mfma_f32_16x16x32_bf16 v[10:13], v[212:215], v[70:73], v[10:13]
	ds_read_b128 v[70:73], v119 offset:2048
	s_waitcnt lgkmcnt(7)
	v_mfma_f32_16x16x32_bf16 v[34:37], v[82:85], v[74:77], v[34:37]
	v_mfma_f32_16x16x32_bf16 v[22:25], v[86:89], v[74:77], v[22:25]
	v_mfma_f32_16x16x32_bf16 v[18:21], v[208:211], v[74:77], v[18:21]
	v_mfma_f32_16x16x32_bf16 v[62:65], v[212:215], v[74:77], v[62:65]
	ds_read_b128 v[74:77], v119 offset:4096
	s_waitcnt lgkmcnt(7)
	v_mfma_f32_16x16x32_bf16 v[58:61], v[82:85], v[78:81], v[58:61]
	v_mfma_f32_16x16x32_bf16 v[54:57], v[86:89], v[78:81], v[54:57]
	v_mfma_f32_16x16x32_bf16 v[50:53], v[208:211], v[78:81], v[50:53]
	v_mfma_f32_16x16x32_bf16 v[2:5], v[212:215], v[78:81], v[2:5]
	ds_read_b128 v[78:81], v119 offset:6144
	s_waitcnt lgkmcnt(3)
	v_mfma_f32_16x16x32_bf16 v[6:9], v[216:219], v[66:69], v[6:9]
	v_mfma_f32_16x16x32_bf16 v[30:33], v[220:223], v[66:69], v[30:33]
	v_mfma_f32_16x16x32_bf16 v[38:41], v[224:227], v[66:69], v[38:41]
	v_mfma_f32_16x16x32_bf16 v[42:45], v[228:231], v[66:69], v[42:45]
	s_waitcnt lgkmcnt(2)
	v_mfma_f32_16x16x32_bf16 v[46:49], v[216:219], v[70:73], v[46:49]
	v_mfma_f32_16x16x32_bf16 v[26:29], v[220:223], v[70:73], v[26:29]
	v_mfma_f32_16x16x32_bf16 v[14:17], v[224:227], v[70:73], v[14:17]
	v_mfma_f32_16x16x32_bf16 v[10:13], v[228:231], v[70:73], v[10:13]
	s_waitcnt vmcnt(6)
	s_waitcnt lgkmcnt(0)
	s_barrier
	s_add_i32 m0, s67, 0x0
	s_nop 0
	global_load_lds_dwordx4 v188, s[80:81]
	s_add_i32 m0, s67, 0x2000
	s_nop 0
	global_load_lds_dwordx4 v189, s[80:81]
	s_add_i32 m0, s67, 0x4000
	s_nop 0
	global_load_lds_dwordx4 v190, s[80:81]
	s_add_i32 m0, s67, 0x6000
	s_nop 0
	global_load_lds_dwordx4 v191, s[80:81]
	s_add_i32 m0, s67, 0x18000
	s_nop 0
	global_load_lds_dwordx4 v205, s[96:97]
	s_add_i32 m0, s67, 0x1a000
	s_nop 0
	global_load_lds_dwordx4 v206, s[96:97]
	s_add_u32 s80, s80, 0x80
	s_addc_u32 s81, s81, 0
	s_add_u32 s96, s96, 0x80
	s_addc_u32 s97, s97, 0
	s_movk_i32 s10, 0x0
	s_mov_b32 s11, 0
	v_lshl_add_u64 v[248:249], v[128:129], 0, s[10:11]
	global_load_dwordx2 v[232:233], v[248:249], off
	global_load_dwordx2 v[234:235], v[248:249], off offset:32
	v_lshl_add_u64 v[248:249], v[132:133], 0, s[10:11]
	global_load_dwordx2 v[236:237], v[248:249], off
	global_load_dwordx2 v[238:239], v[248:249], off offset:32
	v_lshl_add_u64 v[248:249], v[152:153], 0, s[10:11]
	global_load_dwordx2 v[240:241], v[248:249], off
	global_load_dwordx2 v[242:243], v[248:249], off offset:32
	v_lshl_add_u64 v[248:249], v[154:155], 0, s[10:11]
	global_load_dwordx2 v[244:245], v[248:249], off
	global_load_dwordx2 v[246:247], v[248:249], off offset:32
	ds_read_b128 v[82:85], v90 offset:16384
	ds_read_b128 v[86:89], v90 offset:18432
	ds_read_b128 v[208:211], v90 offset:20480
	ds_read_b128 v[212:215], v90 offset:22528
	ds_read_b128 v[66:69], v207 offset:32768
	ds_read_b128 v[70:73], v207 offset:34816
	v_mfma_f32_16x16x32_bf16 v[34:37], v[216:219], v[74:77], v[34:37]
	v_mfma_f32_16x16x32_bf16 v[22:25], v[220:223], v[74:77], v[22:25]
	v_mfma_f32_16x16x32_bf16 v[18:21], v[224:227], v[74:77], v[18:21]
	v_mfma_f32_16x16x32_bf16 v[62:65], v[228:231], v[74:77], v[62:65]
	ds_read_b128 v[74:77], v207 offset:36864
	v_mfma_f32_16x16x32_bf16 v[58:61], v[216:219], v[78:81], v[58:61]
	v_mfma_f32_16x16x32_bf16 v[54:57], v[220:223], v[78:81], v[54:57]
	v_mfma_f32_16x16x32_bf16 v[50:53], v[224:227], v[78:81], v[50:53]
	v_mfma_f32_16x16x32_bf16 v[2:5], v[228:231], v[78:81], v[2:5]
	ds_read_b128 v[78:81], v207 offset:38912
	ds_read_b128 v[216:219], v91 offset:16384
	ds_read_b128 v[220:223], v91 offset:18432
	ds_read_b128 v[224:227], v91 offset:20480
	ds_read_b128 v[228:231], v91 offset:22528
	s_waitcnt lgkmcnt(7)
	v_mfma_f32_16x16x32_bf16 v[6:9], v[82:85], v[66:69], v[6:9]
	v_mfma_f32_16x16x32_bf16 v[30:33], v[86:89], v[66:69], v[30:33]
	v_mfma_f32_16x16x32_bf16 v[38:41], v[208:211], v[66:69], v[38:41]
	v_mfma_f32_16x16x32_bf16 v[42:45], v[212:215], v[66:69], v[42:45]
	ds_read_b128 v[66:69], v119 offset:32768
	s_waitcnt lgkmcnt(7)
	v_mfma_f32_16x16x32_bf16 v[46:49], v[82:85], v[70:73], v[46:49]
	v_mfma_f32_16x16x32_bf16 v[26:29], v[86:89], v[70:73], v[26:29]
	v_mfma_f32_16x16x32_bf16 v[14:17], v[208:211], v[70:73], v[14:17]
	v_mfma_f32_16x16x32_bf16 v[10:13], v[212:215], v[70:73], v[10:13]
	ds_read_b128 v[70:73], v119 offset:34816
	s_waitcnt lgkmcnt(7)
	v_mfma_f32_16x16x32_bf16 v[34:37], v[82:85], v[74:77], v[34:37]
	v_mfma_f32_16x16x32_bf16 v[22:25], v[86:89], v[74:77], v[22:25]
	v_mfma_f32_16x16x32_bf16 v[18:21], v[208:211], v[74:77], v[18:21]
	v_mfma_f32_16x16x32_bf16 v[62:65], v[212:215], v[74:77], v[62:65]
	ds_read_b128 v[74:77], v119 offset:36864
	s_waitcnt lgkmcnt(7)
	v_mfma_f32_16x16x32_bf16 v[58:61], v[82:85], v[78:81], v[58:61]
	v_mfma_f32_16x16x32_bf16 v[54:57], v[86:89], v[78:81], v[54:57]
	v_mfma_f32_16x16x32_bf16 v[50:53], v[208:211], v[78:81], v[50:53]
	v_mfma_f32_16x16x32_bf16 v[2:5], v[212:215], v[78:81], v[2:5]
	ds_read_b128 v[78:81], v119 offset:38912
	s_waitcnt lgkmcnt(3)
	v_mfma_f32_16x16x32_bf16 v[6:9], v[216:219], v[66:69], v[6:9]
	v_mfma_f32_16x16x32_bf16 v[30:33], v[220:223], v[66:69], v[30:33]
	v_mfma_f32_16x16x32_bf16 v[38:41], v[224:227], v[66:69], v[38:41]
	v_mfma_f32_16x16x32_bf16 v[42:45], v[228:231], v[66:69], v[42:45]
	s_waitcnt lgkmcnt(2)
	v_mfma_f32_16x16x32_bf16 v[46:49], v[216:219], v[70:73], v[46:49]
	v_mfma_f32_16x16x32_bf16 v[26:29], v[220:223], v[70:73], v[26:29]
	v_mfma_f32_16x16x32_bf16 v[14:17], v[224:227], v[70:73], v[14:17]
	v_mfma_f32_16x16x32_bf16 v[10:13], v[228:231], v[70:73], v[10:13]
	s_waitcnt vmcnt(14)
	s_waitcnt lgkmcnt(0)
	s_barrier
	s_add_i32 m0, s67, 0x8000
	s_nop 0
	global_load_lds_dwordx4 v188, s[80:81]
	s_add_i32 m0, s67, 0xa000
	s_nop 0
	global_load_lds_dwordx4 v189, s[80:81]
	s_add_i32 m0, s67, 0xc000
	s_nop 0
	global_load_lds_dwordx4 v190, s[80:81]
	s_add_i32 m0, s67, 0xe000
	s_nop 0
	global_load_lds_dwordx4 v191, s[80:81]
	s_add_i32 m0, s67, 0x1c000
	s_nop 0
	global_load_lds_dwordx4 v205, s[96:97]
	s_add_i32 m0, s67, 0x1e000
	s_nop 0
	global_load_lds_dwordx4 v206, s[96:97]
	s_add_u32 s80, s80, 0x80
	s_addc_u32 s81, s81, 0
	s_add_u32 s96, s96, 0xffc80
	s_addc_u32 s97, s97, 0
	ds_read_b128 v[82:85], v90 offset:33792
	ds_read_b128 v[86:89], v90 offset:35840
	ds_read_b128 v[208:211], v90 offset:37888
	ds_read_b128 v[212:215], v90 offset:39936
	ds_read_b128 v[66:69], v0 offset:0
	ds_read_b128 v[70:73], v0 offset:2048
	v_mfma_f32_16x16x32_bf16 v[34:37], v[216:219], v[74:77], v[34:37]
	v_mfma_f32_16x16x32_bf16 v[22:25], v[220:223], v[74:77], v[22:25]
	v_mfma_f32_16x16x32_bf16 v[18:21], v[224:227], v[74:77], v[18:21]
	v_mfma_f32_16x16x32_bf16 v[62:65], v[228:231], v[74:77], v[62:65]
	ds_read_b128 v[74:77], v0 offset:4096
	v_mfma_f32_16x16x32_bf16 v[58:61], v[216:219], v[78:81], v[58:61]
	v_mfma_f32_16x16x32_bf16 v[54:57], v[220:223], v[78:81], v[54:57]
	v_mfma_f32_16x16x32_bf16 v[50:53], v[224:227], v[78:81], v[50:53]
	v_mfma_f32_16x16x32_bf16 v[2:5], v[228:231], v[78:81], v[2:5]
	ds_read_b128 v[78:81], v0 offset:6144
	ds_read_b128 v[216:219], v91 offset:33792
	ds_read_b128 v[220:223], v91 offset:35840
	ds_read_b128 v[224:227], v91 offset:37888
	ds_read_b128 v[228:231], v91 offset:39936
	s_waitcnt lgkmcnt(7)
	v_mfma_f32_16x16x32_bf16 v[6:9], v[82:85], v[66:69], v[6:9]
	v_mfma_f32_16x16x32_bf16 v[30:33], v[86:89], v[66:69], v[30:33]
	v_mfma_f32_16x16x32_bf16 v[38:41], v[208:211], v[66:69], v[38:41]
	v_mfma_f32_16x16x32_bf16 v[42:45], v[212:215], v[66:69], v[42:45]
	ds_read_b128 v[66:69], v255 offset:0
	s_waitcnt lgkmcnt(7)
	v_mfma_f32_16x16x32_bf16 v[46:49], v[82:85], v[70:73], v[46:49]
	v_mfma_f32_16x16x32_bf16 v[26:29], v[86:89], v[70:73], v[26:29]
	v_mfma_f32_16x16x32_bf16 v[14:17], v[208:211], v[70:73], v[14:17]
	v_mfma_f32_16x16x32_bf16 v[10:13], v[212:215], v[70:73], v[10:13]
	ds_read_b128 v[70:73], v255 offset:2048
	s_waitcnt lgkmcnt(7)
	v_mfma_f32_16x16x32_bf16 v[34:37], v[82:85], v[74:77], v[34:37]
	v_mfma_f32_16x16x32_bf16 v[22:25], v[86:89], v[74:77], v[22:25]
	v_mfma_f32_16x16x32_bf16 v[18:21], v[208:211], v[74:77], v[18:21]
	v_mfma_f32_16x16x32_bf16 v[62:65], v[212:215], v[74:77], v[62:65]
	ds_read_b128 v[74:77], v255 offset:4096
	s_waitcnt lgkmcnt(7)
	v_mfma_f32_16x16x32_bf16 v[58:61], v[82:85], v[78:81], v[58:61]
	v_mfma_f32_16x16x32_bf16 v[54:57], v[86:89], v[78:81], v[54:57]
	v_mfma_f32_16x16x32_bf16 v[50:53], v[208:211], v[78:81], v[50:53]
	v_mfma_f32_16x16x32_bf16 v[2:5], v[212:215], v[78:81], v[2:5]
	ds_read_b128 v[78:81], v255 offset:6144
	s_waitcnt lgkmcnt(3)
	v_mfma_f32_16x16x32_bf16 v[6:9], v[216:219], v[66:69], v[6:9]
	v_mfma_f32_16x16x32_bf16 v[30:33], v[220:223], v[66:69], v[30:33]
	v_mfma_f32_16x16x32_bf16 v[38:41], v[224:227], v[66:69], v[38:41]
	v_mfma_f32_16x16x32_bf16 v[42:45], v[228:231], v[66:69], v[42:45]
	s_waitcnt lgkmcnt(2)
	v_mfma_f32_16x16x32_bf16 v[46:49], v[216:219], v[70:73], v[46:49]
	v_mfma_f32_16x16x32_bf16 v[26:29], v[220:223], v[70:73], v[26:29]
	v_mfma_f32_16x16x32_bf16 v[14:17], v[224:227], v[70:73], v[14:17]
	v_mfma_f32_16x16x32_bf16 v[10:13], v[228:231], v[70:73], v[10:13]
	s_waitcnt vmcnt(14)
	s_waitcnt lgkmcnt(0)
	s_barrier
	s_add_i32 m0, s67, 0x10000
	s_nop 0
	global_load_lds_dwordx4 v188, s[80:81]
	s_add_i32 m0, s67, 0x12000
	s_nop 0
	global_load_lds_dwordx4 v189, s[80:81]
	s_add_i32 m0, s67, 0x14000
	s_nop 0
	global_load_lds_dwordx4 v190, s[80:81]
	s_add_i32 m0, s67, 0x16000
	s_nop 0
	global_load_lds_dwordx4 v191, s[80:81]
	s_add_i32 m0, s67, 0x20400
	s_nop 0
	global_load_lds_dwordx4 v205, s[96:97]
	s_add_i32 m0, s67, 0x22400
	s_nop 0
	global_load_lds_dwordx4 v206, s[96:97]
	s_add_u32 s80, s80, 0x80
	s_addc_u32 s81, s81, 0
	s_add_u32 s96, s96, 0x80
	s_addc_u32 s97, s97, 0
	ds_read_b128 v[82:85], v90 offset:0
	ds_read_b128 v[86:89], v90 offset:2048
	ds_read_b128 v[208:211], v90 offset:4096
	ds_read_b128 v[212:215], v90 offset:6144
	ds_read_b128 v[66:69], v207 offset:0
	ds_read_b128 v[70:73], v207 offset:2048
	v_mfma_f32_16x16x32_bf16 v[34:37], v[216:219], v[74:77], v[34:37]
	v_mfma_f32_16x16x32_bf16 v[22:25], v[220:223], v[74:77], v[22:25]
	v_mfma_f32_16x16x32_bf16 v[18:21], v[224:227], v[74:77], v[18:21]
	v_mfma_f32_16x16x32_bf16 v[62:65], v[228:231], v[74:77], v[62:65]
	ds_read_b128 v[74:77], v207 offset:4096
	v_mfma_f32_16x16x32_bf16 v[58:61], v[216:219], v[78:81], v[58:61]
	v_mfma_f32_16x16x32_bf16 v[54:57], v[220:223], v[78:81], v[54:57]
	v_mfma_f32_16x16x32_bf16 v[50:53], v[224:227], v[78:81], v[50:53]
	v_mfma_f32_16x16x32_bf16 v[2:5], v[228:231], v[78:81], v[2:5]
	ds_read_b128 v[78:81], v207 offset:6144
	ds_read_b128 v[216:219], v91 offset:0
	ds_read_b128 v[220:223], v91 offset:2048
	ds_read_b128 v[224:227], v91 offset:4096
	ds_read_b128 v[228:231], v91 offset:6144
	s_waitcnt lgkmcnt(7)
	v_mfma_f32_16x16x32_bf16 v[6:9], v[82:85], v[66:69], v[6:9]
	v_mfma_f32_16x16x32_bf16 v[30:33], v[86:89], v[66:69], v[30:33]
	v_mfma_f32_16x16x32_bf16 v[38:41], v[208:211], v[66:69], v[38:41]
	v_mfma_f32_16x16x32_bf16 v[42:45], v[212:215], v[66:69], v[42:45]
	ds_read_b128 v[66:69], v119 offset:0
	s_waitcnt lgkmcnt(7)
	v_mfma_f32_16x16x32_bf16 v[46:49], v[82:85], v[70:73], v[46:49]
	v_mfma_f32_16x16x32_bf16 v[26:29], v[86:89], v[70:73], v[26:29]
	v_mfma_f32_16x16x32_bf16 v[14:17], v[208:211], v[70:73], v[14:17]
	v_mfma_f32_16x16x32_bf16 v[10:13], v[212:215], v[70:73], v[10:13]
	ds_read_b128 v[70:73], v119 offset:2048
	s_waitcnt lgkmcnt(7)
	v_mfma_f32_16x16x32_bf16 v[34:37], v[82:85], v[74:77], v[34:37]
	v_mfma_f32_16x16x32_bf16 v[22:25], v[86:89], v[74:77], v[22:25]
	v_mfma_f32_16x16x32_bf16 v[18:21], v[208:211], v[74:77], v[18:21]
	v_mfma_f32_16x16x32_bf16 v[62:65], v[212:215], v[74:77], v[62:65]
	ds_read_b128 v[74:77], v119 offset:4096
	s_waitcnt lgkmcnt(7)
	v_mfma_f32_16x16x32_bf16 v[58:61], v[82:85], v[78:81], v[58:61]
	v_mfma_f32_16x16x32_bf16 v[54:57], v[86:89], v[78:81], v[54:57]
	v_mfma_f32_16x16x32_bf16 v[50:53], v[208:211], v[78:81], v[50:53]
	v_mfma_f32_16x16x32_bf16 v[2:5], v[212:215], v[78:81], v[2:5]
	ds_read_b128 v[78:81], v119 offset:6144
	s_waitcnt lgkmcnt(3)
	v_mfma_f32_16x16x32_bf16 v[6:9], v[216:219], v[66:69], v[6:9]
	v_mfma_f32_16x16x32_bf16 v[30:33], v[220:223], v[66:69], v[30:33]
	v_mfma_f32_16x16x32_bf16 v[38:41], v[224:227], v[66:69], v[38:41]
	v_mfma_f32_16x16x32_bf16 v[42:45], v[228:231], v[66:69], v[42:45]
	s_waitcnt lgkmcnt(2)
	v_mfma_f32_16x16x32_bf16 v[46:49], v[216:219], v[70:73], v[46:49]
	v_mfma_f32_16x16x32_bf16 v[26:29], v[220:223], v[70:73], v[26:29]
	v_mfma_f32_16x16x32_bf16 v[14:17], v[224:227], v[70:73], v[14:17]
	v_mfma_f32_16x16x32_bf16 v[10:13], v[228:231], v[70:73], v[10:13]
	s_waitcnt vmcnt(6)
	s_waitcnt lgkmcnt(0)
	s_barrier
	s_add_i32 m0, s67, 0x0
	s_nop 0
	global_load_lds_dwordx4 v188, s[80:81]
	s_add_i32 m0, s67, 0x2000
	s_nop 0
	global_load_lds_dwordx4 v189, s[80:81]
	s_add_i32 m0, s67, 0x4000
	s_nop 0
	global_load_lds_dwordx4 v190, s[80:81]
	s_add_i32 m0, s67, 0x6000
	s_nop 0
	global_load_lds_dwordx4 v191, s[80:81]
	s_add_i32 m0, s67, 0x18000
	s_nop 0
	global_load_lds_dwordx4 v205, s[96:97]
	s_add_i32 m0, s67, 0x1a000
	s_nop 0
	global_load_lds_dwordx4 v206, s[96:97]
	s_add_u32 s80, s80, 0x80
	s_addc_u32 s81, s81, 0
	s_add_u32 s96, s96, 0x80
	s_addc_u32 s97, s97, 0
	ds_read_b128 v[82:85], v90 offset:16384
	ds_read_b128 v[86:89], v90 offset:18432
	ds_read_b128 v[208:211], v90 offset:20480
	ds_read_b128 v[212:215], v90 offset:22528
	ds_read_b128 v[66:69], v207 offset:32768
	ds_read_b128 v[70:73], v207 offset:34816
	v_mfma_f32_16x16x32_bf16 v[34:37], v[216:219], v[74:77], v[34:37]
	v_mfma_f32_16x16x32_bf16 v[22:25], v[220:223], v[74:77], v[22:25]
	v_mfma_f32_16x16x32_bf16 v[18:21], v[224:227], v[74:77], v[18:21]
	v_mfma_f32_16x16x32_bf16 v[62:65], v[228:231], v[74:77], v[62:65]
	ds_read_b128 v[74:77], v207 offset:36864
	v_mfma_f32_16x16x32_bf16 v[58:61], v[216:219], v[78:81], v[58:61]
	v_mfma_f32_16x16x32_bf16 v[54:57], v[220:223], v[78:81], v[54:57]
	v_mfma_f32_16x16x32_bf16 v[50:53], v[224:227], v[78:81], v[50:53]
	v_mfma_f32_16x16x32_bf16 v[2:5], v[228:231], v[78:81], v[2:5]
	ds_read_b128 v[78:81], v207 offset:38912
	ds_read_b128 v[216:219], v91 offset:16384
	ds_read_b128 v[220:223], v91 offset:18432
	ds_read_b128 v[224:227], v91 offset:20480
	ds_read_b128 v[228:231], v91 offset:22528
	s_waitcnt lgkmcnt(7)
	v_mfma_f32_16x16x32_bf16 v[6:9], v[82:85], v[66:69], v[6:9]
	v_mfma_f32_16x16x32_bf16 v[30:33], v[86:89], v[66:69], v[30:33]
	v_mfma_f32_16x16x32_bf16 v[38:41], v[208:211], v[66:69], v[38:41]
	v_mfma_f32_16x16x32_bf16 v[42:45], v[212:215], v[66:69], v[42:45]
	ds_read_b128 v[66:69], v119 offset:32768
	s_waitcnt lgkmcnt(7)
	v_mfma_f32_16x16x32_bf16 v[46:49], v[82:85], v[70:73], v[46:49]
	v_mfma_f32_16x16x32_bf16 v[26:29], v[86:89], v[70:73], v[26:29]
	v_mfma_f32_16x16x32_bf16 v[14:17], v[208:211], v[70:73], v[14:17]
	v_mfma_f32_16x16x32_bf16 v[10:13], v[212:215], v[70:73], v[10:13]
	ds_read_b128 v[70:73], v119 offset:34816
	s_waitcnt lgkmcnt(7)
	v_mfma_f32_16x16x32_bf16 v[34:37], v[82:85], v[74:77], v[34:37]
	v_mfma_f32_16x16x32_bf16 v[22:25], v[86:89], v[74:77], v[22:25]
	v_mfma_f32_16x16x32_bf16 v[18:21], v[208:211], v[74:77], v[18:21]
	v_mfma_f32_16x16x32_bf16 v[62:65], v[212:215], v[74:77], v[62:65]
	ds_read_b128 v[74:77], v119 offset:36864
	s_waitcnt lgkmcnt(7)
	v_mfma_f32_16x16x32_bf16 v[58:61], v[82:85], v[78:81], v[58:61]
	v_mfma_f32_16x16x32_bf16 v[54:57], v[86:89], v[78:81], v[54:57]
	v_mfma_f32_16x16x32_bf16 v[50:53], v[208:211], v[78:81], v[50:53]
	v_mfma_f32_16x16x32_bf16 v[2:5], v[212:215], v[78:81], v[2:5]
	ds_read_b128 v[78:81], v119 offset:38912
	s_waitcnt lgkmcnt(3)
	v_mfma_f32_16x16x32_bf16 v[6:9], v[216:219], v[66:69], v[6:9]
	s_waitcnt vmcnt(18)
	v_mfma_f32_16x16x32_bf16 v[30:33], v[220:223], v[66:69], v[30:33]
	v_mfma_f32_16x16x32_bf16 v[38:41], v[224:227], v[66:69], v[38:41]
	v_mfma_f32_16x16x32_bf16 v[42:45], v[228:231], v[66:69], v[42:45]
	v_cvt_f32_ubyte0_e32 v248, v232
	v_cvt_f32_ubyte1_e32 v249, v232
	v_cvt_f32_ubyte2_e32 v250, v232
	v_cvt_f32_ubyte3_e32 v251, v232
	v_mul_f32_e32 v248, s34, v248
	v_mul_f32_e32 v249, s34, v249
	v_mul_f32_e32 v250, s34, v250
	v_mul_f32_e32 v251, s34, v251
	v_fma_f32 v184, v6, v248, v184
	v_fma_f32 v185, v7, v249, v185
	v_fma_f32 v186, v8, v250, v186
	v_fma_f32 v187, v9, v251, v187
	s_waitcnt lgkmcnt(2)
	v_mfma_f32_16x16x32_bf16 v[46:49], v[216:219], v[70:73], v[46:49]
	v_cvt_f32_ubyte0_e32 v248, v233
	v_cvt_f32_ubyte1_e32 v249, v233
	v_cvt_f32_ubyte2_e32 v250, v233
	v_cvt_f32_ubyte3_e32 v251, v233
	v_mul_f32_e32 v248, s34, v248
	v_mul_f32_e32 v249, s34, v249
	v_mul_f32_e32 v250, s34, v250
	v_mul_f32_e32 v251, s34, v251
	v_fma_f32 v180, v30, v248, v180
	v_fma_f32 v181, v31, v249, v181
	v_fma_f32 v182, v32, v250, v182
	v_fma_f32 v183, v33, v251, v183
	v_mfma_f32_16x16x32_bf16 v[26:29], v[220:223], v[70:73], v[26:29]
	v_cvt_f32_ubyte0_e32 v248, v234
	v_cvt_f32_ubyte1_e32 v249, v234
	v_cvt_f32_ubyte2_e32 v250, v234
	v_cvt_f32_ubyte3_e32 v251, v234
	v_mul_f32_e32 v248, s34, v248
	v_mul_f32_e32 v249, s34, v249
	v_mul_f32_e32 v250, s34, v250
	v_mul_f32_e32 v251, s34, v251
	v_fma_f32 v176, v38, v248, v176
	v_fma_f32 v177, v39, v249, v177
	v_fma_f32 v178, v40, v250, v178
	v_fma_f32 v179, v41, v251, v179
	v_mfma_f32_16x16x32_bf16 v[14:17], v[224:227], v[70:73], v[14:17]
	v_cvt_f32_ubyte0_e32 v248, v235
	v_cvt_f32_ubyte1_e32 v249, v235
	v_cvt_f32_ubyte2_e32 v250, v235
	v_cvt_f32_ubyte3_e32 v251, v235
	v_mul_f32_e32 v248, s34, v248
	v_mul_f32_e32 v249, s34, v249
	v_mul_f32_e32 v250, s34, v250
	v_mul_f32_e32 v251, s34, v251
	v_fma_f32 v172, v42, v248, v172
	v_fma_f32 v173, v43, v249, v173
	v_fma_f32 v174, v44, v250, v174
	v_fma_f32 v175, v45, v251, v175
	v_mfma_f32_16x16x32_bf16 v[10:13], v[228:231], v[70:73], v[10:13]
	v_cvt_f32_ubyte0_e32 v248, v236
	v_cvt_f32_ubyte1_e32 v249, v236
	v_cvt_f32_ubyte2_e32 v250, v236
	v_cvt_f32_ubyte3_e32 v251, v236
	v_mul_f32_e32 v248, s34, v248
	v_mul_f32_e32 v249, s34, v249
	v_mul_f32_e32 v250, s34, v250
	v_mul_f32_e32 v251, s34, v251
	v_fma_f32 v168, v46, v248, v168
	v_fma_f32 v169, v47, v249, v169
	v_fma_f32 v170, v48, v250, v170
	v_fma_f32 v171, v49, v251, v171
	s_waitcnt vmcnt(6)
	s_waitcnt lgkmcnt(0)
	s_barrier
	s_add_i32 m0, s67, 0x8000
	s_nop 0
	global_load_lds_dwordx4 v188, s[80:81]
	s_add_i32 m0, s67, 0xa000
	s_nop 0
	global_load_lds_dwordx4 v189, s[80:81]
	s_add_i32 m0, s67, 0xc000
	s_nop 0
	global_load_lds_dwordx4 v190, s[80:81]
	s_add_i32 m0, s67, 0xe000
	s_nop 0
	global_load_lds_dwordx4 v191, s[80:81]
	s_add_i32 m0, s67, 0x1c000
	s_nop 0
	global_load_lds_dwordx4 v205, s[96:97]
	s_add_i32 m0, s67, 0x1e000
	s_nop 0
	global_load_lds_dwordx4 v206, s[96:97]
	s_add_u32 s80, s80, 0x80
	s_addc_u32 s81, s81, 0
	s_add_u32 s96, s96, 0x80
	s_addc_u32 s97, s97, 0
	ds_read_b128 v[82:85], v90 offset:33792
	ds_read_b128 v[86:89], v90 offset:35840
	ds_read_b128 v[208:211], v90 offset:37888
	ds_read_b128 v[212:215], v90 offset:39936
	ds_read_b128 v[66:69], v0 offset:0
	ds_read_b128 v[70:73], v0 offset:2048
	v_mfma_f32_16x16x32_bf16 v[34:37], v[216:219], v[74:77], v[34:37]
	v_cvt_f32_ubyte0_e32 v248, v237
	v_cvt_f32_ubyte1_e32 v249, v237
	v_cvt_f32_ubyte2_e32 v250, v237
	v_cvt_f32_ubyte3_e32 v251, v237
	v_mul_f32_e32 v248, s34, v248
	v_mul_f32_e32 v249, s34, v249
	v_mul_f32_e32 v250, s34, v250
	v_mul_f32_e32 v251, s34, v251
	v_fma_f32 v164, v26, v248, v164
	v_fma_f32 v165, v27, v249, v165
	v_fma_f32 v166, v28, v250, v166
	v_fma_f32 v167, v29, v251, v167
	v_mfma_f32_16x16x32_bf16 v[22:25], v[220:223], v[74:77], v[22:25]
	v_cvt_f32_ubyte0_e32 v248, v238
	v_cvt_f32_ubyte1_e32 v249, v238
	v_cvt_f32_ubyte2_e32 v250, v238
	v_cvt_f32_ubyte3_e32 v251, v238
	v_mul_f32_e32 v248, s34, v248
	v_mul_f32_e32 v249, s34, v249
	v_mul_f32_e32 v250, s34, v250
	v_mul_f32_e32 v251, s34, v251
	v_fma_f32 v160, v14, v248, v160
	v_fma_f32 v161, v15, v249, v161
	v_fma_f32 v162, v16, v250, v162
	v_fma_f32 v163, v17, v251, v163
	v_mfma_f32_16x16x32_bf16 v[18:21], v[224:227], v[74:77], v[18:21]
	v_cvt_f32_ubyte0_e32 v248, v239
	v_cvt_f32_ubyte1_e32 v249, v239
	v_cvt_f32_ubyte2_e32 v250, v239
	v_cvt_f32_ubyte3_e32 v251, v239
	v_mul_f32_e32 v248, s34, v248
	v_mul_f32_e32 v249, s34, v249
	v_mul_f32_e32 v250, s34, v250
	v_mul_f32_e32 v251, s34, v251
	v_fma_f32 v156, v10, v248, v156
	v_fma_f32 v157, v11, v249, v157
	v_fma_f32 v158, v12, v250, v158
	v_fma_f32 v159, v13, v251, v159
	v_mfma_f32_16x16x32_bf16 v[62:65], v[228:231], v[74:77], v[62:65]
	v_cvt_f32_ubyte0_e32 v248, v240
	v_cvt_f32_ubyte1_e32 v249, v240
	v_cvt_f32_ubyte2_e32 v250, v240
	v_cvt_f32_ubyte3_e32 v251, v240
	v_mul_f32_e32 v248, s34, v248
	v_mul_f32_e32 v249, s34, v249
	v_mul_f32_e32 v250, s34, v250
	v_mul_f32_e32 v251, s34, v251
	v_fma_f32 v136, v34, v248, v136
	v_fma_f32 v137, v35, v249, v137
	v_fma_f32 v150, v36, v250, v150
	v_fma_f32 v151, v37, v251, v151
	ds_read_b128 v[74:77], v0 offset:4096
	v_mfma_f32_16x16x32_bf16 v[58:61], v[216:219], v[78:81], v[58:61]
	v_cvt_f32_ubyte0_e32 v248, v241
	v_cvt_f32_ubyte1_e32 v249, v241
	v_cvt_f32_ubyte2_e32 v250, v241
	v_cvt_f32_ubyte3_e32 v251, v241
	v_mul_f32_e32 v248, s34, v248
	v_mul_f32_e32 v249, s34, v249
	v_mul_f32_e32 v250, s34, v250
	v_mul_f32_e32 v251, s34, v251
	v_fma_f32 v130, v22, v248, v130
	v_fma_f32 v131, v23, v249, v131
	v_fma_f32 v134, v24, v250, v134
	v_fma_f32 v135, v25, v251, v135
	v_mfma_f32_16x16x32_bf16 v[54:57], v[220:223], v[78:81], v[54:57]
	v_cvt_f32_ubyte0_e32 v248, v242
	v_cvt_f32_ubyte1_e32 v249, v242
	v_cvt_f32_ubyte2_e32 v250, v242
	v_cvt_f32_ubyte3_e32 v251, v242
	v_mul_f32_e32 v248, s34, v248
	v_mul_f32_e32 v249, s34, v249
	v_mul_f32_e32 v250, s34, v250
	v_mul_f32_e32 v251, s34, v251
	v_fma_f32 v124, v18, v248, v124
	v_fma_f32 v125, v19, v249, v125
	v_fma_f32 v126, v20, v250, v126
	v_fma_f32 v127, v21, v251, v127
	v_mfma_f32_16x16x32_bf16 v[50:53], v[224:227], v[78:81], v[50:53]
	v_cvt_f32_ubyte0_e32 v248, v243
	v_cvt_f32_ubyte1_e32 v249, v243
	v_cvt_f32_ubyte2_e32 v250, v243
	v_cvt_f32_ubyte3_e32 v251, v243
	v_mul_f32_e32 v248, s34, v248
	v_mul_f32_e32 v249, s34, v249
	v_mul_f32_e32 v250, s34, v250
	v_mul_f32_e32 v251, s34, v251
	v_fma_f32 v120, v62, v248, v120
	v_fma_f32 v121, v63, v249, v121
	v_fma_f32 v122, v64, v250, v122
	v_fma_f32 v123, v65, v251, v123
	v_mfma_f32_16x16x32_bf16 v[2:5], v[228:231], v[78:81], v[2:5]
	v_cvt_f32_ubyte0_e32 v248, v244
	v_cvt_f32_ubyte1_e32 v249, v244
	v_cvt_f32_ubyte2_e32 v250, v244
	v_cvt_f32_ubyte3_e32 v251, v244
	v_mul_f32_e32 v248, s34, v248
	v_mul_f32_e32 v249, s34, v249
	v_mul_f32_e32 v250, s34, v250
	v_mul_f32_e32 v251, s34, v251
	v_fma_f32 v114, v58, v248, v114
	v_fma_f32 v115, v59, v249, v115
	v_fma_f32 v116, v60, v250, v116
	v_fma_f32 v117, v61, v251, v117
	ds_read_b128 v[78:81], v0 offset:6144
	s_nop 7
	s_nop 3
	v_cvt_f32_ubyte0_e32 v248, v245
	v_cvt_f32_ubyte1_e32 v249, v245
	v_cvt_f32_ubyte2_e32 v250, v245
	v_cvt_f32_ubyte3_e32 v251, v245
	v_mul_f32_e32 v248, s34, v248
	v_mul_f32_e32 v249, s34, v249
	v_mul_f32_e32 v250, s34, v250
	v_mul_f32_e32 v251, s34, v251
	v_fma_f32 v106, v54, v248, v106
	v_fma_f32 v107, v55, v249, v107
	v_fma_f32 v108, v56, v250, v108
	v_fma_f32 v109, v57, v251, v109
	v_cvt_f32_ubyte0_e32 v248, v246
	v_cvt_f32_ubyte1_e32 v249, v246
	v_cvt_f32_ubyte2_e32 v250, v246
	v_cvt_f32_ubyte3_e32 v251, v246
	v_mul_f32_e32 v248, s34, v248
	v_mul_f32_e32 v249, s34, v249
	v_mul_f32_e32 v250, s34, v250
	v_mul_f32_e32 v251, s34, v251
	v_fma_f32 v100, v50, v248, v100
	v_fma_f32 v101, v51, v249, v101
	v_fma_f32 v102, v52, v250, v102
	v_fma_f32 v103, v53, v251, v103
	v_cvt_f32_ubyte0_e32 v248, v247
	v_cvt_f32_ubyte1_e32 v249, v247
	v_cvt_f32_ubyte2_e32 v250, v247
	v_cvt_f32_ubyte3_e32 v251, v247
	v_mul_f32_e32 v248, s34, v248
	v_mul_f32_e32 v249, s34, v249
	v_mul_f32_e32 v250, s34, v250
	v_mul_f32_e32 v251, s34, v251
	v_fma_f32 v96, v2, v248, v96
	v_fma_f32 v97, v3, v249, v97
	v_fma_f32 v98, v4, v250, v98
	v_fma_f32 v99, v5, v251, v99
	s_add_u32 s98, s86, 0x1600
	s_addc_u32 s99, s87, 0
	global_load_dword v92, v93, s[98:99]
	ds_read_b128 v[216:219], v91 offset:33792
	ds_read_b128 v[220:223], v91 offset:35840
	ds_read_b128 v[224:227], v91 offset:37888
	ds_read_b128 v[228:231], v91 offset:39936
	s_waitcnt lgkmcnt(7)
	v_mfma_f32_16x16x32_bf16 v[6:9], v[82:85], v[66:69], 0
	v_mfma_f32_16x16x32_bf16 v[30:33], v[86:89], v[66:69], 0
	v_mfma_f32_16x16x32_bf16 v[38:41], v[208:211], v[66:69], 0
	v_mfma_f32_16x16x32_bf16 v[42:45], v[212:215], v[66:69], 0
	ds_read_b128 v[66:69], v255 offset:0
	s_waitcnt lgkmcnt(7)
	v_mfma_f32_16x16x32_bf16 v[46:49], v[82:85], v[70:73], 0
	v_mfma_f32_16x16x32_bf16 v[26:29], v[86:89], v[70:73], 0
	v_mfma_f32_16x16x32_bf16 v[14:17], v[208:211], v[70:73], 0
	v_mfma_f32_16x16x32_bf16 v[10:13], v[212:215], v[70:73], 0
	ds_read_b128 v[70:73], v255 offset:2048
	s_waitcnt lgkmcnt(7)
	v_mfma_f32_16x16x32_bf16 v[34:37], v[82:85], v[74:77], 0
	v_mfma_f32_16x16x32_bf16 v[22:25], v[86:89], v[74:77], 0
	v_mfma_f32_16x16x32_bf16 v[18:21], v[208:211], v[74:77], 0
	v_mfma_f32_16x16x32_bf16 v[62:65], v[212:215], v[74:77], 0
	ds_read_b128 v[74:77], v255 offset:4096
	s_waitcnt lgkmcnt(7)
	v_mfma_f32_16x16x32_bf16 v[58:61], v[82:85], v[78:81], 0
	v_mfma_f32_16x16x32_bf16 v[54:57], v[86:89], v[78:81], 0
	v_mfma_f32_16x16x32_bf16 v[50:53], v[208:211], v[78:81], 0
	v_mfma_f32_16x16x32_bf16 v[2:5], v[212:215], v[78:81], 0
	ds_read_b128 v[78:81], v255 offset:6144
	s_waitcnt lgkmcnt(3)
	v_mfma_f32_16x16x32_bf16 v[6:9], v[216:219], v[66:69], v[6:9]
	v_mfma_f32_16x16x32_bf16 v[30:33], v[220:223], v[66:69], v[30:33]
	v_mfma_f32_16x16x32_bf16 v[38:41], v[224:227], v[66:69], v[38:41]
	v_mfma_f32_16x16x32_bf16 v[42:45], v[228:231], v[66:69], v[42:45]
	s_waitcnt lgkmcnt(2)
	v_mfma_f32_16x16x32_bf16 v[46:49], v[216:219], v[70:73], v[46:49]
	v_mfma_f32_16x16x32_bf16 v[26:29], v[220:223], v[70:73], v[26:29]
	v_mfma_f32_16x16x32_bf16 v[14:17], v[224:227], v[70:73], v[14:17]
	v_mfma_f32_16x16x32_bf16 v[10:13], v[228:231], v[70:73], v[10:13]
	s_waitcnt vmcnt(7)
	s_waitcnt lgkmcnt(0)
	s_barrier
	s_add_i32 m0, s67, 0x10000
	s_nop 0
	global_load_lds_dwordx4 v188, s[80:81]
	s_add_i32 m0, s67, 0x12000
	s_nop 0
	global_load_lds_dwordx4 v189, s[80:81]
	s_add_i32 m0, s67, 0x14000
	s_nop 0
	global_load_lds_dwordx4 v190, s[80:81]
	s_add_i32 m0, s67, 0x16000
	s_nop 0
	global_load_lds_dwordx4 v191, s[80:81]
	s_add_i32 m0, s67, 0x20400
	s_nop 0
	global_load_lds_dwordx4 v205, s[96:97]
	s_add_i32 m0, s67, 0x22400
	s_nop 0
	global_load_lds_dwordx4 v206, s[96:97]
	s_add_u32 s80, s80, 0x80
	s_addc_u32 s81, s81, 0
	s_add_u32 s96, s96, 0x80
	s_addc_u32 s97, s97, 0
	ds_read_b128 v[82:85], v90 offset:0
	ds_read_b128 v[86:89], v90 offset:2048
	ds_read_b128 v[208:211], v90 offset:4096
	ds_read_b128 v[212:215], v90 offset:6144
	ds_read_b128 v[66:69], v207 offset:0
	ds_read_b128 v[70:73], v207 offset:2048
	v_mfma_f32_16x16x32_bf16 v[34:37], v[216:219], v[74:77], v[34:37]
	v_mfma_f32_16x16x32_bf16 v[22:25], v[220:223], v[74:77], v[22:25]
	v_mfma_f32_16x16x32_bf16 v[18:21], v[224:227], v[74:77], v[18:21]
	v_mfma_f32_16x16x32_bf16 v[62:65], v[228:231], v[74:77], v[62:65]
	ds_read_b128 v[74:77], v207 offset:4096
	v_mfma_f32_16x16x32_bf16 v[58:61], v[216:219], v[78:81], v[58:61]
	v_mfma_f32_16x16x32_bf16 v[54:57], v[220:223], v[78:81], v[54:57]
	v_mfma_f32_16x16x32_bf16 v[50:53], v[224:227], v[78:81], v[50:53]
	v_mfma_f32_16x16x32_bf16 v[2:5], v[228:231], v[78:81], v[2:5]
	ds_read_b128 v[78:81], v207 offset:6144
	ds_read_b128 v[216:219], v91 offset:0
	ds_read_b128 v[220:223], v91 offset:2048
	ds_read_b128 v[224:227], v91 offset:4096
	ds_read_b128 v[228:231], v91 offset:6144
	s_waitcnt lgkmcnt(7)
	v_mfma_f32_16x16x32_bf16 v[6:9], v[82:85], v[66:69], v[6:9]
	v_mfma_f32_16x16x32_bf16 v[30:33], v[86:89], v[66:69], v[30:33]
	v_mfma_f32_16x16x32_bf16 v[38:41], v[208:211], v[66:69], v[38:41]
	v_mfma_f32_16x16x32_bf16 v[42:45], v[212:215], v[66:69], v[42:45]
	ds_read_b128 v[66:69], v119 offset:0
	s_waitcnt lgkmcnt(7)
	v_mfma_f32_16x16x32_bf16 v[46:49], v[82:85], v[70:73], v[46:49]
	v_mfma_f32_16x16x32_bf16 v[26:29], v[86:89], v[70:73], v[26:29]
	v_mfma_f32_16x16x32_bf16 v[14:17], v[208:211], v[70:73], v[14:17]
	v_mfma_f32_16x16x32_bf16 v[10:13], v[212:215], v[70:73], v[10:13]
	ds_read_b128 v[70:73], v119 offset:2048
	s_waitcnt lgkmcnt(7)
	v_mfma_f32_16x16x32_bf16 v[34:37], v[82:85], v[74:77], v[34:37]
	v_mfma_f32_16x16x32_bf16 v[22:25], v[86:89], v[74:77], v[22:25]
	v_mfma_f32_16x16x32_bf16 v[18:21], v[208:211], v[74:77], v[18:21]
	v_mfma_f32_16x16x32_bf16 v[62:65], v[212:215], v[74:77], v[62:65]
	ds_read_b128 v[74:77], v119 offset:4096
	s_waitcnt lgkmcnt(7)
	v_mfma_f32_16x16x32_bf16 v[58:61], v[82:85], v[78:81], v[58:61]
	v_mfma_f32_16x16x32_bf16 v[54:57], v[86:89], v[78:81], v[54:57]
	v_mfma_f32_16x16x32_bf16 v[50:53], v[208:211], v[78:81], v[50:53]
	v_mfma_f32_16x16x32_bf16 v[2:5], v[212:215], v[78:81], v[2:5]
	ds_read_b128 v[78:81], v119 offset:6144
	s_waitcnt lgkmcnt(3)
	v_mfma_f32_16x16x32_bf16 v[6:9], v[216:219], v[66:69], v[6:9]
	v_mfma_f32_16x16x32_bf16 v[30:33], v[220:223], v[66:69], v[30:33]
	v_mfma_f32_16x16x32_bf16 v[38:41], v[224:227], v[66:69], v[38:41]
	v_mfma_f32_16x16x32_bf16 v[42:45], v[228:231], v[66:69], v[42:45]
	s_waitcnt lgkmcnt(2)
	v_mfma_f32_16x16x32_bf16 v[46:49], v[216:219], v[70:73], v[46:49]
	v_mfma_f32_16x16x32_bf16 v[26:29], v[220:223], v[70:73], v[26:29]
	v_mfma_f32_16x16x32_bf16 v[14:17], v[224:227], v[70:73], v[14:17]
	v_mfma_f32_16x16x32_bf16 v[10:13], v[228:231], v[70:73], v[10:13]
	s_waitcnt vmcnt(7)
	s_waitcnt lgkmcnt(0)
	s_barrier
	s_add_i32 m0, s67, 0x0
	s_nop 0
	global_load_lds_dwordx4 v188, s[80:81]
	s_add_i32 m0, s67, 0x2000
	s_nop 0
	global_load_lds_dwordx4 v189, s[80:81]
	s_add_i32 m0, s67, 0x4000
	s_nop 0
	global_load_lds_dwordx4 v190, s[80:81]
	s_add_i32 m0, s67, 0x6000
	s_nop 0
	global_load_lds_dwordx4 v191, s[80:81]
	s_add_i32 m0, s67, 0x18000
	s_nop 0
	global_load_lds_dwordx4 v205, s[96:97]
	s_add_i32 m0, s67, 0x1a000
	s_nop 0
	global_load_lds_dwordx4 v206, s[96:97]
	s_add_u32 s80, s80, 0x80
	s_addc_u32 s81, s81, 0
	s_add_u32 s96, s96, 0x80
	s_addc_u32 s97, s97, 0
	ds_read_b128 v[82:85], v90 offset:16384
	ds_read_b128 v[86:89], v90 offset:18432
	ds_read_b128 v[208:211], v90 offset:20480
	ds_read_b128 v[212:215], v90 offset:22528
	ds_read_b128 v[66:69], v207 offset:32768
	ds_read_b128 v[70:73], v207 offset:34816
	v_mfma_f32_16x16x32_bf16 v[34:37], v[216:219], v[74:77], v[34:37]
	v_mfma_f32_16x16x32_bf16 v[22:25], v[220:223], v[74:77], v[22:25]
	v_mfma_f32_16x16x32_bf16 v[18:21], v[224:227], v[74:77], v[18:21]
	v_mfma_f32_16x16x32_bf16 v[62:65], v[228:231], v[74:77], v[62:65]
	ds_read_b128 v[74:77], v207 offset:36864
	v_mfma_f32_16x16x32_bf16 v[58:61], v[216:219], v[78:81], v[58:61]
	v_mfma_f32_16x16x32_bf16 v[54:57], v[220:223], v[78:81], v[54:57]
	v_mfma_f32_16x16x32_bf16 v[50:53], v[224:227], v[78:81], v[50:53]
	v_mfma_f32_16x16x32_bf16 v[2:5], v[228:231], v[78:81], v[2:5]
	ds_read_b128 v[78:81], v207 offset:38912
	ds_read_b128 v[216:219], v91 offset:16384
	ds_read_b128 v[220:223], v91 offset:18432
	ds_read_b128 v[224:227], v91 offset:20480
	ds_read_b128 v[228:231], v91 offset:22528
	s_waitcnt lgkmcnt(7)
	v_mfma_f32_16x16x32_bf16 v[6:9], v[82:85], v[66:69], v[6:9]
	v_mfma_f32_16x16x32_bf16 v[30:33], v[86:89], v[66:69], v[30:33]
	v_mfma_f32_16x16x32_bf16 v[38:41], v[208:211], v[66:69], v[38:41]
	v_mfma_f32_16x16x32_bf16 v[42:45], v[212:215], v[66:69], v[42:45]
	ds_read_b128 v[66:69], v119 offset:32768
	s_waitcnt lgkmcnt(7)
	v_mfma_f32_16x16x32_bf16 v[46:49], v[82:85], v[70:73], v[46:49]
	v_mfma_f32_16x16x32_bf16 v[26:29], v[86:89], v[70:73], v[26:29]
	v_mfma_f32_16x16x32_bf16 v[14:17], v[208:211], v[70:73], v[14:17]
	v_mfma_f32_16x16x32_bf16 v[10:13], v[212:215], v[70:73], v[10:13]
	ds_read_b128 v[70:73], v119 offset:34816
	s_waitcnt lgkmcnt(7)
	v_mfma_f32_16x16x32_bf16 v[34:37], v[82:85], v[74:77], v[34:37]
	v_mfma_f32_16x16x32_bf16 v[22:25], v[86:89], v[74:77], v[22:25]
	v_mfma_f32_16x16x32_bf16 v[18:21], v[208:211], v[74:77], v[18:21]
	v_mfma_f32_16x16x32_bf16 v[62:65], v[212:215], v[74:77], v[62:65]
	ds_read_b128 v[74:77], v119 offset:36864
	s_waitcnt lgkmcnt(7)
	v_mfma_f32_16x16x32_bf16 v[58:61], v[82:85], v[78:81], v[58:61]
	v_mfma_f32_16x16x32_bf16 v[54:57], v[86:89], v[78:81], v[54:57]
	v_mfma_f32_16x16x32_bf16 v[50:53], v[208:211], v[78:81], v[50:53]
	v_mfma_f32_16x16x32_bf16 v[2:5], v[212:215], v[78:81], v[2:5]
	ds_read_b128 v[78:81], v119 offset:38912
	s_waitcnt lgkmcnt(3)
	v_mfma_f32_16x16x32_bf16 v[6:9], v[216:219], v[66:69], v[6:9]
	v_mfma_f32_16x16x32_bf16 v[30:33], v[220:223], v[66:69], v[30:33]
	v_mfma_f32_16x16x32_bf16 v[38:41], v[224:227], v[66:69], v[38:41]
	v_mfma_f32_16x16x32_bf16 v[42:45], v[228:231], v[66:69], v[42:45]
	s_waitcnt lgkmcnt(2)
	v_mfma_f32_16x16x32_bf16 v[46:49], v[216:219], v[70:73], v[46:49]
	v_mfma_f32_16x16x32_bf16 v[26:29], v[220:223], v[70:73], v[26:29]
	v_mfma_f32_16x16x32_bf16 v[14:17], v[224:227], v[70:73], v[14:17]
	v_mfma_f32_16x16x32_bf16 v[10:13], v[228:231], v[70:73], v[10:13]
	s_waitcnt vmcnt(6)
	s_waitcnt lgkmcnt(0)
	s_barrier
	s_add_i32 m0, s67, 0x8000
	s_nop 0
	global_load_lds_dwordx4 v188, s[80:81]
	s_add_i32 m0, s67, 0xa000
	s_nop 0
	global_load_lds_dwordx4 v189, s[80:81]
	s_add_i32 m0, s67, 0xc000
	s_nop 0
	global_load_lds_dwordx4 v190, s[80:81]
	s_add_i32 m0, s67, 0xe000
	s_nop 0
	global_load_lds_dwordx4 v191, s[80:81]
	s_add_i32 m0, s67, 0x1c000
	s_nop 0
	global_load_lds_dwordx4 v205, s[96:97]
	s_add_i32 m0, s67, 0x1e000
	s_nop 0
	global_load_lds_dwordx4 v206, s[96:97]
	s_add_u32 s80, s80, 0x80
	s_addc_u32 s81, s81, 0
	s_add_u32 s96, s96, 0x80
	s_addc_u32 s97, s97, 0
	ds_read_b128 v[82:85], v90 offset:33792
	ds_read_b128 v[86:89], v90 offset:35840
	ds_read_b128 v[208:211], v90 offset:37888
	ds_read_b128 v[212:215], v90 offset:39936
	ds_read_b128 v[66:69], v0 offset:0
	ds_read_b128 v[70:73], v0 offset:2048
	v_mfma_f32_16x16x32_bf16 v[34:37], v[216:219], v[74:77], v[34:37]
	v_mfma_f32_16x16x32_bf16 v[22:25], v[220:223], v[74:77], v[22:25]
	v_mfma_f32_16x16x32_bf16 v[18:21], v[224:227], v[74:77], v[18:21]
	v_mfma_f32_16x16x32_bf16 v[62:65], v[228:231], v[74:77], v[62:65]
	ds_read_b128 v[74:77], v0 offset:4096
	v_mfma_f32_16x16x32_bf16 v[58:61], v[216:219], v[78:81], v[58:61]
	v_mfma_f32_16x16x32_bf16 v[54:57], v[220:223], v[78:81], v[54:57]
	v_mfma_f32_16x16x32_bf16 v[50:53], v[224:227], v[78:81], v[50:53]
	v_mfma_f32_16x16x32_bf16 v[2:5], v[228:231], v[78:81], v[2:5]
	ds_read_b128 v[78:81], v0 offset:6144
	ds_read_b128 v[216:219], v91 offset:33792
	ds_read_b128 v[220:223], v91 offset:35840
	ds_read_b128 v[224:227], v91 offset:37888
	ds_read_b128 v[228:231], v91 offset:39936
	s_waitcnt lgkmcnt(7)
	v_mfma_f32_16x16x32_bf16 v[6:9], v[82:85], v[66:69], v[6:9]
	v_mfma_f32_16x16x32_bf16 v[30:33], v[86:89], v[66:69], v[30:33]
	v_mfma_f32_16x16x32_bf16 v[38:41], v[208:211], v[66:69], v[38:41]
	v_mfma_f32_16x16x32_bf16 v[42:45], v[212:215], v[66:69], v[42:45]
	ds_read_b128 v[66:69], v255 offset:0
	s_waitcnt lgkmcnt(7)
	v_mfma_f32_16x16x32_bf16 v[46:49], v[82:85], v[70:73], v[46:49]
	v_mfma_f32_16x16x32_bf16 v[26:29], v[86:89], v[70:73], v[26:29]
	v_mfma_f32_16x16x32_bf16 v[14:17], v[208:211], v[70:73], v[14:17]
	v_mfma_f32_16x16x32_bf16 v[10:13], v[212:215], v[70:73], v[10:13]
	ds_read_b128 v[70:73], v255 offset:2048
	s_waitcnt lgkmcnt(7)
	v_mfma_f32_16x16x32_bf16 v[34:37], v[82:85], v[74:77], v[34:37]
	v_mfma_f32_16x16x32_bf16 v[22:25], v[86:89], v[74:77], v[22:25]
	v_mfma_f32_16x16x32_bf16 v[18:21], v[208:211], v[74:77], v[18:21]
	v_mfma_f32_16x16x32_bf16 v[62:65], v[212:215], v[74:77], v[62:65]
	ds_read_b128 v[74:77], v255 offset:4096
	s_waitcnt lgkmcnt(7)
	v_mfma_f32_16x16x32_bf16 v[58:61], v[82:85], v[78:81], v[58:61]
	v_mfma_f32_16x16x32_bf16 v[54:57], v[86:89], v[78:81], v[54:57]
	v_mfma_f32_16x16x32_bf16 v[50:53], v[208:211], v[78:81], v[50:53]
	v_mfma_f32_16x16x32_bf16 v[2:5], v[212:215], v[78:81], v[2:5]
	ds_read_b128 v[78:81], v255 offset:6144
	s_waitcnt lgkmcnt(3)
	v_mfma_f32_16x16x32_bf16 v[6:9], v[216:219], v[66:69], v[6:9]
	v_mfma_f32_16x16x32_bf16 v[30:33], v[220:223], v[66:69], v[30:33]
	v_mfma_f32_16x16x32_bf16 v[38:41], v[224:227], v[66:69], v[38:41]
	v_mfma_f32_16x16x32_bf16 v[42:45], v[228:231], v[66:69], v[42:45]
	s_waitcnt lgkmcnt(2)
	v_mfma_f32_16x16x32_bf16 v[46:49], v[216:219], v[70:73], v[46:49]
	v_mfma_f32_16x16x32_bf16 v[26:29], v[220:223], v[70:73], v[26:29]
	v_mfma_f32_16x16x32_bf16 v[14:17], v[224:227], v[70:73], v[14:17]
	v_mfma_f32_16x16x32_bf16 v[10:13], v[228:231], v[70:73], v[10:13]
	s_waitcnt vmcnt(6)
	s_waitcnt lgkmcnt(0)
	s_barrier
	s_add_i32 m0, s67, 0x10000
	s_nop 0
	global_load_lds_dwordx4 v188, s[80:81]
	s_add_i32 m0, s67, 0x12000
	s_nop 0
	global_load_lds_dwordx4 v189, s[80:81]
	s_add_i32 m0, s67, 0x14000
	s_nop 0
	global_load_lds_dwordx4 v190, s[80:81]
	s_add_i32 m0, s67, 0x16000
	s_nop 0
	global_load_lds_dwordx4 v191, s[80:81]
	s_add_i32 m0, s67, 0x20400
	s_nop 0
	global_load_lds_dwordx4 v205, s[96:97]
	s_add_i32 m0, s67, 0x22400
	s_nop 0
	global_load_lds_dwordx4 v206, s[96:97]
	s_add_u32 s80, s80, 0x80
	s_addc_u32 s81, s81, 0
	s_add_u32 s96, s96, 0x80
	s_addc_u32 s97, s97, 0
	s_movk_i32 s10, 0x400
	s_mov_b32 s11, 0
	v_lshl_add_u64 v[248:249], v[128:129], 0, s[10:11]
	global_load_dwordx2 v[232:233], v[248:249], off
	global_load_dwordx2 v[234:235], v[248:249], off offset:32
	v_lshl_add_u64 v[248:249], v[132:133], 0, s[10:11]
	global_load_dwordx2 v[236:237], v[248:249], off
	global_load_dwordx2 v[238:239], v[248:249], off offset:32
	v_lshl_add_u64 v[248:249], v[152:153], 0, s[10:11]
	global_load_dwordx2 v[240:241], v[248:249], off
	global_load_dwordx2 v[242:243], v[248:249], off offset:32
	v_lshl_add_u64 v[248:249], v[154:155], 0, s[10:11]
	global_load_dwordx2 v[244:245], v[248:249], off
	global_load_dwordx2 v[246:247], v[248:249], off offset:32
	ds_read_b128 v[82:85], v90 offset:0
	ds_read_b128 v[86:89], v90 offset:2048
	ds_read_b128 v[208:211], v90 offset:4096
	ds_read_b128 v[212:215], v90 offset:6144
	ds_read_b128 v[66:69], v207 offset:0
	ds_read_b128 v[70:73], v207 offset:2048
	v_mfma_f32_16x16x32_bf16 v[34:37], v[216:219], v[74:77], v[34:37]
	v_mfma_f32_16x16x32_bf16 v[22:25], v[220:223], v[74:77], v[22:25]
	v_mfma_f32_16x16x32_bf16 v[18:21], v[224:227], v[74:77], v[18:21]
	v_mfma_f32_16x16x32_bf16 v[62:65], v[228:231], v[74:77], v[62:65]
	ds_read_b128 v[74:77], v207 offset:4096
	v_mfma_f32_16x16x32_bf16 v[58:61], v[216:219], v[78:81], v[58:61]
	v_mfma_f32_16x16x32_bf16 v[54:57], v[220:223], v[78:81], v[54:57]
	v_mfma_f32_16x16x32_bf16 v[50:53], v[224:227], v[78:81], v[50:53]
	v_mfma_f32_16x16x32_bf16 v[2:5], v[228:231], v[78:81], v[2:5]
	ds_read_b128 v[78:81], v207 offset:6144
	ds_read_b128 v[216:219], v91 offset:0
	ds_read_b128 v[220:223], v91 offset:2048
	ds_read_b128 v[224:227], v91 offset:4096
	ds_read_b128 v[228:231], v91 offset:6144
	s_waitcnt lgkmcnt(7)
	v_mfma_f32_16x16x32_bf16 v[6:9], v[82:85], v[66:69], v[6:9]
	v_mfma_f32_16x16x32_bf16 v[30:33], v[86:89], v[66:69], v[30:33]
	v_mfma_f32_16x16x32_bf16 v[38:41], v[208:211], v[66:69], v[38:41]
	v_mfma_f32_16x16x32_bf16 v[42:45], v[212:215], v[66:69], v[42:45]
	ds_read_b128 v[66:69], v119 offset:0
	s_waitcnt lgkmcnt(7)
	v_mfma_f32_16x16x32_bf16 v[46:49], v[82:85], v[70:73], v[46:49]
	v_mfma_f32_16x16x32_bf16 v[26:29], v[86:89], v[70:73], v[26:29]
	v_mfma_f32_16x16x32_bf16 v[14:17], v[208:211], v[70:73], v[14:17]
	v_mfma_f32_16x16x32_bf16 v[10:13], v[212:215], v[70:73], v[10:13]
	ds_read_b128 v[70:73], v119 offset:2048
	s_waitcnt lgkmcnt(7)
	v_mfma_f32_16x16x32_bf16 v[34:37], v[82:85], v[74:77], v[34:37]
	v_mfma_f32_16x16x32_bf16 v[22:25], v[86:89], v[74:77], v[22:25]
	v_mfma_f32_16x16x32_bf16 v[18:21], v[208:211], v[74:77], v[18:21]
	v_mfma_f32_16x16x32_bf16 v[62:65], v[212:215], v[74:77], v[62:65]
	ds_read_b128 v[74:77], v119 offset:4096
	s_waitcnt lgkmcnt(7)
	v_mfma_f32_16x16x32_bf16 v[58:61], v[82:85], v[78:81], v[58:61]
	v_mfma_f32_16x16x32_bf16 v[54:57], v[86:89], v[78:81], v[54:57]
	v_mfma_f32_16x16x32_bf16 v[50:53], v[208:211], v[78:81], v[50:53]
	v_mfma_f32_16x16x32_bf16 v[2:5], v[212:215], v[78:81], v[2:5]
	ds_read_b128 v[78:81], v119 offset:6144
	s_waitcnt lgkmcnt(3)
	v_mfma_f32_16x16x32_bf16 v[6:9], v[216:219], v[66:69], v[6:9]
	v_mfma_f32_16x16x32_bf16 v[30:33], v[220:223], v[66:69], v[30:33]
	v_mfma_f32_16x16x32_bf16 v[38:41], v[224:227], v[66:69], v[38:41]
	v_mfma_f32_16x16x32_bf16 v[42:45], v[228:231], v[66:69], v[42:45]
	s_waitcnt lgkmcnt(2)
	v_mfma_f32_16x16x32_bf16 v[46:49], v[216:219], v[70:73], v[46:49]
	v_mfma_f32_16x16x32_bf16 v[26:29], v[220:223], v[70:73], v[26:29]
	v_mfma_f32_16x16x32_bf16 v[14:17], v[224:227], v[70:73], v[14:17]
	v_mfma_f32_16x16x32_bf16 v[10:13], v[228:231], v[70:73], v[10:13]
	s_waitcnt vmcnt(14)
	s_waitcnt lgkmcnt(0)
	s_barrier
	s_add_i32 m0, s67, 0x0
	s_nop 0
	global_load_lds_dwordx4 v188, s[80:81]
	s_add_i32 m0, s67, 0x2000
	s_nop 0
	global_load_lds_dwordx4 v189, s[80:81]
	s_add_i32 m0, s67, 0x4000
	s_nop 0
	global_load_lds_dwordx4 v190, s[80:81]
	s_add_i32 m0, s67, 0x6000
	s_nop 0
	global_load_lds_dwordx4 v191, s[80:81]
	s_add_i32 m0, s67, 0x18000
	s_nop 0
	global_load_lds_dwordx4 v205, s[96:97]
	s_add_i32 m0, s67, 0x1a000
	s_nop 0
	global_load_lds_dwordx4 v206, s[96:97]
	s_add_u32 s80, s80, 0x280
	s_addc_u32 s81, s81, 0
	s_add_u32 s96, s96, 0xffc80
	s_addc_u32 s97, s97, 0
	ds_read_b128 v[82:85], v90 offset:16384
	ds_read_b128 v[86:89], v90 offset:18432
	ds_read_b128 v[208:211], v90 offset:20480
	ds_read_b128 v[212:215], v90 offset:22528
	ds_read_b128 v[66:69], v207 offset:32768
	ds_read_b128 v[70:73], v207 offset:34816
	v_mfma_f32_16x16x32_bf16 v[34:37], v[216:219], v[74:77], v[34:37]
	v_mfma_f32_16x16x32_bf16 v[22:25], v[220:223], v[74:77], v[22:25]
	v_mfma_f32_16x16x32_bf16 v[18:21], v[224:227], v[74:77], v[18:21]
	v_mfma_f32_16x16x32_bf16 v[62:65], v[228:231], v[74:77], v[62:65]
	ds_read_b128 v[74:77], v207 offset:36864
	v_mfma_f32_16x16x32_bf16 v[58:61], v[216:219], v[78:81], v[58:61]
	v_mfma_f32_16x16x32_bf16 v[54:57], v[220:223], v[78:81], v[54:57]
	v_mfma_f32_16x16x32_bf16 v[50:53], v[224:227], v[78:81], v[50:53]
	v_mfma_f32_16x16x32_bf16 v[2:5], v[228:231], v[78:81], v[2:5]
	ds_read_b128 v[78:81], v207 offset:38912
	ds_read_b128 v[216:219], v91 offset:16384
	ds_read_b128 v[220:223], v91 offset:18432
	ds_read_b128 v[224:227], v91 offset:20480
	ds_read_b128 v[228:231], v91 offset:22528
	s_waitcnt lgkmcnt(7)
	v_mfma_f32_16x16x32_bf16 v[6:9], v[82:85], v[66:69], v[6:9]
	v_mfma_f32_16x16x32_bf16 v[30:33], v[86:89], v[66:69], v[30:33]
	v_mfma_f32_16x16x32_bf16 v[38:41], v[208:211], v[66:69], v[38:41]
	v_mfma_f32_16x16x32_bf16 v[42:45], v[212:215], v[66:69], v[42:45]
	ds_read_b128 v[66:69], v119 offset:32768
	s_waitcnt lgkmcnt(7)
	v_mfma_f32_16x16x32_bf16 v[46:49], v[82:85], v[70:73], v[46:49]
	v_mfma_f32_16x16x32_bf16 v[26:29], v[86:89], v[70:73], v[26:29]
	v_mfma_f32_16x16x32_bf16 v[14:17], v[208:211], v[70:73], v[14:17]
	v_mfma_f32_16x16x32_bf16 v[10:13], v[212:215], v[70:73], v[10:13]
	ds_read_b128 v[70:73], v119 offset:34816
	s_waitcnt lgkmcnt(7)
	v_mfma_f32_16x16x32_bf16 v[34:37], v[82:85], v[74:77], v[34:37]
	v_mfma_f32_16x16x32_bf16 v[22:25], v[86:89], v[74:77], v[22:25]
	v_mfma_f32_16x16x32_bf16 v[18:21], v[208:211], v[74:77], v[18:21]
	v_mfma_f32_16x16x32_bf16 v[62:65], v[212:215], v[74:77], v[62:65]
	ds_read_b128 v[74:77], v119 offset:36864
	s_waitcnt lgkmcnt(7)
	v_mfma_f32_16x16x32_bf16 v[58:61], v[82:85], v[78:81], v[58:61]
	v_mfma_f32_16x16x32_bf16 v[54:57], v[86:89], v[78:81], v[54:57]
	v_mfma_f32_16x16x32_bf16 v[50:53], v[208:211], v[78:81], v[50:53]
	v_mfma_f32_16x16x32_bf16 v[2:5], v[212:215], v[78:81], v[2:5]
	ds_read_b128 v[78:81], v119 offset:38912
	s_waitcnt lgkmcnt(3)
	v_mfma_f32_16x16x32_bf16 v[6:9], v[216:219], v[66:69], v[6:9]
	v_mfma_f32_16x16x32_bf16 v[30:33], v[220:223], v[66:69], v[30:33]
	v_mfma_f32_16x16x32_bf16 v[38:41], v[224:227], v[66:69], v[38:41]
	v_mfma_f32_16x16x32_bf16 v[42:45], v[228:231], v[66:69], v[42:45]
	s_waitcnt lgkmcnt(2)
	v_mfma_f32_16x16x32_bf16 v[46:49], v[216:219], v[70:73], v[46:49]
	v_mfma_f32_16x16x32_bf16 v[26:29], v[220:223], v[70:73], v[26:29]
	v_mfma_f32_16x16x32_bf16 v[14:17], v[224:227], v[70:73], v[14:17]
	v_mfma_f32_16x16x32_bf16 v[10:13], v[228:231], v[70:73], v[10:13]
	s_waitcnt vmcnt(14)
	s_waitcnt lgkmcnt(0)
	s_barrier
	s_add_i32 m0, s67, 0x8000
	s_nop 0
	global_load_lds_dwordx4 v188, s[80:81]
	s_add_i32 m0, s67, 0xa000
	s_nop 0
	global_load_lds_dwordx4 v189, s[80:81]
	s_add_i32 m0, s67, 0xc000
	s_nop 0
	global_load_lds_dwordx4 v190, s[80:81]
	s_add_i32 m0, s67, 0xe000
	s_nop 0
	global_load_lds_dwordx4 v191, s[80:81]
	s_add_i32 m0, s67, 0x1c000
	s_nop 0
	global_load_lds_dwordx4 v205, s[96:97]
	s_add_i32 m0, s67, 0x1e000
	s_nop 0
	global_load_lds_dwordx4 v206, s[96:97]
	s_add_u32 s80, s80, 0x80
	s_addc_u32 s81, s81, 0
	s_add_u32 s96, s96, 0x80
	s_addc_u32 s97, s97, 0
	ds_read_b128 v[82:85], v90 offset:33792
	ds_read_b128 v[86:89], v90 offset:35840
	ds_read_b128 v[208:211], v90 offset:37888
	ds_read_b128 v[212:215], v90 offset:39936
	ds_read_b128 v[66:69], v0 offset:0
	ds_read_b128 v[70:73], v0 offset:2048
	v_mfma_f32_16x16x32_bf16 v[34:37], v[216:219], v[74:77], v[34:37]
	v_mfma_f32_16x16x32_bf16 v[22:25], v[220:223], v[74:77], v[22:25]
	v_mfma_f32_16x16x32_bf16 v[18:21], v[224:227], v[74:77], v[18:21]
	v_mfma_f32_16x16x32_bf16 v[62:65], v[228:231], v[74:77], v[62:65]
	ds_read_b128 v[74:77], v0 offset:4096
	v_mfma_f32_16x16x32_bf16 v[58:61], v[216:219], v[78:81], v[58:61]
	v_mfma_f32_16x16x32_bf16 v[54:57], v[220:223], v[78:81], v[54:57]
	v_mfma_f32_16x16x32_bf16 v[50:53], v[224:227], v[78:81], v[50:53]
	v_mfma_f32_16x16x32_bf16 v[2:5], v[228:231], v[78:81], v[2:5]
	ds_read_b128 v[78:81], v0 offset:6144
	ds_read_b128 v[216:219], v91 offset:33792
	ds_read_b128 v[220:223], v91 offset:35840
	ds_read_b128 v[224:227], v91 offset:37888
	ds_read_b128 v[228:231], v91 offset:39936
	s_waitcnt lgkmcnt(7)
	v_mfma_f32_16x16x32_bf16 v[6:9], v[82:85], v[66:69], v[6:9]
	v_mfma_f32_16x16x32_bf16 v[30:33], v[86:89], v[66:69], v[30:33]
	v_mfma_f32_16x16x32_bf16 v[38:41], v[208:211], v[66:69], v[38:41]
	v_mfma_f32_16x16x32_bf16 v[42:45], v[212:215], v[66:69], v[42:45]
	ds_read_b128 v[66:69], v255 offset:0
	s_waitcnt lgkmcnt(7)
	v_mfma_f32_16x16x32_bf16 v[46:49], v[82:85], v[70:73], v[46:49]
	v_mfma_f32_16x16x32_bf16 v[26:29], v[86:89], v[70:73], v[26:29]
	v_mfma_f32_16x16x32_bf16 v[14:17], v[208:211], v[70:73], v[14:17]
	v_mfma_f32_16x16x32_bf16 v[10:13], v[212:215], v[70:73], v[10:13]
	ds_read_b128 v[70:73], v255 offset:2048
	s_waitcnt lgkmcnt(7)
	v_mfma_f32_16x16x32_bf16 v[34:37], v[82:85], v[74:77], v[34:37]
	v_mfma_f32_16x16x32_bf16 v[22:25], v[86:89], v[74:77], v[22:25]
	v_mfma_f32_16x16x32_bf16 v[18:21], v[208:211], v[74:77], v[18:21]
	v_mfma_f32_16x16x32_bf16 v[62:65], v[212:215], v[74:77], v[62:65]
	ds_read_b128 v[74:77], v255 offset:4096
	s_waitcnt lgkmcnt(7)
	v_mfma_f32_16x16x32_bf16 v[58:61], v[82:85], v[78:81], v[58:61]
	v_mfma_f32_16x16x32_bf16 v[54:57], v[86:89], v[78:81], v[54:57]
	v_mfma_f32_16x16x32_bf16 v[50:53], v[208:211], v[78:81], v[50:53]
	v_mfma_f32_16x16x32_bf16 v[2:5], v[212:215], v[78:81], v[2:5]
	ds_read_b128 v[78:81], v255 offset:6144
	s_waitcnt lgkmcnt(3)
	v_mfma_f32_16x16x32_bf16 v[6:9], v[216:219], v[66:69], v[6:9]
	v_mfma_f32_16x16x32_bf16 v[30:33], v[220:223], v[66:69], v[30:33]
	v_mfma_f32_16x16x32_bf16 v[38:41], v[224:227], v[66:69], v[38:41]
	v_mfma_f32_16x16x32_bf16 v[42:45], v[228:231], v[66:69], v[42:45]
	s_waitcnt lgkmcnt(2)
	v_mfma_f32_16x16x32_bf16 v[46:49], v[216:219], v[70:73], v[46:49]
	v_mfma_f32_16x16x32_bf16 v[26:29], v[220:223], v[70:73], v[26:29]
	v_mfma_f32_16x16x32_bf16 v[14:17], v[224:227], v[70:73], v[14:17]
	v_mfma_f32_16x16x32_bf16 v[10:13], v[228:231], v[70:73], v[10:13]
	s_waitcnt vmcnt(6)
	s_waitcnt lgkmcnt(0)
	s_barrier
	s_add_i32 m0, s67, 0x10000
	s_nop 0
	global_load_lds_dwordx4 v188, s[80:81]
	s_add_i32 m0, s67, 0x12000
	s_nop 0
	global_load_lds_dwordx4 v189, s[80:81]
	s_add_i32 m0, s67, 0x14000
	s_nop 0
	global_load_lds_dwordx4 v190, s[80:81]
	s_add_i32 m0, s67, 0x16000
	s_nop 0
	global_load_lds_dwordx4 v191, s[80:81]
	s_add_i32 m0, s67, 0x20400
	s_nop 0
	global_load_lds_dwordx4 v205, s[96:97]
	s_add_i32 m0, s67, 0x22400
	s_nop 0
	global_load_lds_dwordx4 v206, s[96:97]
	s_add_u32 s80, s80, 0x80
	s_addc_u32 s81, s81, 0
	s_add_u32 s96, s96, 0x80
	s_addc_u32 s97, s97, 0
	ds_read_b128 v[82:85], v90 offset:0
	ds_read_b128 v[86:89], v90 offset:2048
	ds_read_b128 v[208:211], v90 offset:4096
	ds_read_b128 v[212:215], v90 offset:6144
	ds_read_b128 v[66:69], v207 offset:0
	ds_read_b128 v[70:73], v207 offset:2048
	v_mfma_f32_16x16x32_bf16 v[34:37], v[216:219], v[74:77], v[34:37]
	v_mfma_f32_16x16x32_bf16 v[22:25], v[220:223], v[74:77], v[22:25]
	v_mfma_f32_16x16x32_bf16 v[18:21], v[224:227], v[74:77], v[18:21]
	v_mfma_f32_16x16x32_bf16 v[62:65], v[228:231], v[74:77], v[62:65]
	ds_read_b128 v[74:77], v207 offset:4096
	v_mfma_f32_16x16x32_bf16 v[58:61], v[216:219], v[78:81], v[58:61]
	v_mfma_f32_16x16x32_bf16 v[54:57], v[220:223], v[78:81], v[54:57]
	v_mfma_f32_16x16x32_bf16 v[50:53], v[224:227], v[78:81], v[50:53]
	v_mfma_f32_16x16x32_bf16 v[2:5], v[228:231], v[78:81], v[2:5]
	ds_read_b128 v[78:81], v207 offset:6144
	ds_read_b128 v[216:219], v91 offset:0
	ds_read_b128 v[220:223], v91 offset:2048
	ds_read_b128 v[224:227], v91 offset:4096
	ds_read_b128 v[228:231], v91 offset:6144
	s_waitcnt lgkmcnt(7)
	v_mfma_f32_16x16x32_bf16 v[6:9], v[82:85], v[66:69], v[6:9]
	v_mfma_f32_16x16x32_bf16 v[30:33], v[86:89], v[66:69], v[30:33]
	v_mfma_f32_16x16x32_bf16 v[38:41], v[208:211], v[66:69], v[38:41]
	v_mfma_f32_16x16x32_bf16 v[42:45], v[212:215], v[66:69], v[42:45]
	ds_read_b128 v[66:69], v119 offset:0
	s_waitcnt lgkmcnt(7)
	v_mfma_f32_16x16x32_bf16 v[46:49], v[82:85], v[70:73], v[46:49]
	v_mfma_f32_16x16x32_bf16 v[26:29], v[86:89], v[70:73], v[26:29]
	v_mfma_f32_16x16x32_bf16 v[14:17], v[208:211], v[70:73], v[14:17]
	v_mfma_f32_16x16x32_bf16 v[10:13], v[212:215], v[70:73], v[10:13]
	ds_read_b128 v[70:73], v119 offset:2048
	s_waitcnt lgkmcnt(7)
	v_mfma_f32_16x16x32_bf16 v[34:37], v[82:85], v[74:77], v[34:37]
	v_mfma_f32_16x16x32_bf16 v[22:25], v[86:89], v[74:77], v[22:25]
	v_mfma_f32_16x16x32_bf16 v[18:21], v[208:211], v[74:77], v[18:21]
	v_mfma_f32_16x16x32_bf16 v[62:65], v[212:215], v[74:77], v[62:65]
	ds_read_b128 v[74:77], v119 offset:4096
	s_waitcnt lgkmcnt(7)
	v_mfma_f32_16x16x32_bf16 v[58:61], v[82:85], v[78:81], v[58:61]
	v_mfma_f32_16x16x32_bf16 v[54:57], v[86:89], v[78:81], v[54:57]
	v_mfma_f32_16x16x32_bf16 v[50:53], v[208:211], v[78:81], v[50:53]
	v_mfma_f32_16x16x32_bf16 v[2:5], v[212:215], v[78:81], v[2:5]
	ds_read_b128 v[78:81], v119 offset:6144
	s_waitcnt lgkmcnt(3)
	v_mfma_f32_16x16x32_bf16 v[6:9], v[216:219], v[66:69], v[6:9]
	s_waitcnt vmcnt(18)
	v_mfma_f32_16x16x32_bf16 v[30:33], v[220:223], v[66:69], v[30:33]
	v_mfma_f32_16x16x32_bf16 v[38:41], v[224:227], v[66:69], v[38:41]
	v_mfma_f32_16x16x32_bf16 v[42:45], v[228:231], v[66:69], v[42:45]
	v_cvt_f32_ubyte0_e32 v248, v232
	v_cvt_f32_ubyte1_e32 v249, v232
	v_cvt_f32_ubyte2_e32 v250, v232
	v_cvt_f32_ubyte3_e32 v251, v232
	v_mul_f32_e32 v248, s34, v248
	v_mul_f32_e32 v249, s34, v249
	v_mul_f32_e32 v250, s34, v250
	v_mul_f32_e32 v251, s34, v251
	v_fma_f32 v184, v6, v248, v184
	v_fma_f32 v185, v7, v249, v185
	v_fma_f32 v186, v8, v250, v186
	v_fma_f32 v187, v9, v251, v187
	s_waitcnt lgkmcnt(2)
	v_mfma_f32_16x16x32_bf16 v[46:49], v[216:219], v[70:73], v[46:49]
	v_cvt_f32_ubyte0_e32 v248, v233
	v_cvt_f32_ubyte1_e32 v249, v233
	v_cvt_f32_ubyte2_e32 v250, v233
	v_cvt_f32_ubyte3_e32 v251, v233
	v_mul_f32_e32 v248, s34, v248
	v_mul_f32_e32 v249, s34, v249
	v_mul_f32_e32 v250, s34, v250
	v_mul_f32_e32 v251, s34, v251
	v_fma_f32 v180, v30, v248, v180
	v_fma_f32 v181, v31, v249, v181
	v_fma_f32 v182, v32, v250, v182
	v_fma_f32 v183, v33, v251, v183
	v_mfma_f32_16x16x32_bf16 v[26:29], v[220:223], v[70:73], v[26:29]
	v_cvt_f32_ubyte0_e32 v248, v234
	v_cvt_f32_ubyte1_e32 v249, v234
	v_cvt_f32_ubyte2_e32 v250, v234
	v_cvt_f32_ubyte3_e32 v251, v234
	v_mul_f32_e32 v248, s34, v248
	v_mul_f32_e32 v249, s34, v249
	v_mul_f32_e32 v250, s34, v250
	v_mul_f32_e32 v251, s34, v251
	v_fma_f32 v176, v38, v248, v176
	v_fma_f32 v177, v39, v249, v177
	v_fma_f32 v178, v40, v250, v178
	v_fma_f32 v179, v41, v251, v179
	v_mfma_f32_16x16x32_bf16 v[14:17], v[224:227], v[70:73], v[14:17]
	v_cvt_f32_ubyte0_e32 v248, v235
	v_cvt_f32_ubyte1_e32 v249, v235
	v_cvt_f32_ubyte2_e32 v250, v235
	v_cvt_f32_ubyte3_e32 v251, v235
	v_mul_f32_e32 v248, s34, v248
	v_mul_f32_e32 v249, s34, v249
	v_mul_f32_e32 v250, s34, v250
	v_mul_f32_e32 v251, s34, v251
	v_fma_f32 v172, v42, v248, v172
	v_fma_f32 v173, v43, v249, v173
	v_fma_f32 v174, v44, v250, v174
	v_fma_f32 v175, v45, v251, v175
	v_mfma_f32_16x16x32_bf16 v[10:13], v[228:231], v[70:73], v[10:13]
	v_cvt_f32_ubyte0_e32 v248, v236
	v_cvt_f32_ubyte1_e32 v249, v236
	v_cvt_f32_ubyte2_e32 v250, v236
	v_cvt_f32_ubyte3_e32 v251, v236
	v_mul_f32_e32 v248, s34, v248
	v_mul_f32_e32 v249, s34, v249
	v_mul_f32_e32 v250, s34, v250
	v_mul_f32_e32 v251, s34, v251
	v_fma_f32 v168, v46, v248, v168
	v_fma_f32 v169, v47, v249, v169
	v_fma_f32 v170, v48, v250, v170
	v_fma_f32 v171, v49, v251, v171
	s_waitcnt vmcnt(6)
	s_waitcnt lgkmcnt(0)
	s_barrier
	s_add_i32 m0, s67, 0x0
	s_nop 0
	global_load_lds_dwordx4 v188, s[80:81]
	s_add_i32 m0, s67, 0x2000
	s_nop 0
	global_load_lds_dwordx4 v189, s[80:81]
	s_add_i32 m0, s67, 0x4000
	s_nop 0
	global_load_lds_dwordx4 v190, s[80:81]
	s_add_i32 m0, s67, 0x6000
	s_nop 0
	global_load_lds_dwordx4 v191, s[80:81]
	s_add_i32 m0, s67, 0x18000
	s_nop 0
	global_load_lds_dwordx4 v205, s[96:97]
	s_add_i32 m0, s67, 0x1a000
	s_nop 0
	global_load_lds_dwordx4 v206, s[96:97]
	s_add_u32 s80, s80, 0x80
	s_addc_u32 s81, s81, 0
	s_add_u32 s96, s96, 0x80
	s_addc_u32 s97, s97, 0
	ds_read_b128 v[82:85], v90 offset:16384
	ds_read_b128 v[86:89], v90 offset:18432
	ds_read_b128 v[208:211], v90 offset:20480
	ds_read_b128 v[212:215], v90 offset:22528
	ds_read_b128 v[66:69], v207 offset:32768
	ds_read_b128 v[70:73], v207 offset:34816
	v_mfma_f32_16x16x32_bf16 v[34:37], v[216:219], v[74:77], v[34:37]
	v_cvt_f32_ubyte0_e32 v248, v237
	v_cvt_f32_ubyte1_e32 v249, v237
	v_cvt_f32_ubyte2_e32 v250, v237
	v_cvt_f32_ubyte3_e32 v251, v237
	v_mul_f32_e32 v248, s34, v248
	v_mul_f32_e32 v249, s34, v249
	v_mul_f32_e32 v250, s34, v250
	v_mul_f32_e32 v251, s34, v251
	v_fma_f32 v164, v26, v248, v164
	v_fma_f32 v165, v27, v249, v165
	v_fma_f32 v166, v28, v250, v166
	v_fma_f32 v167, v29, v251, v167
	v_mfma_f32_16x16x32_bf16 v[22:25], v[220:223], v[74:77], v[22:25]
	v_cvt_f32_ubyte0_e32 v248, v238
	v_cvt_f32_ubyte1_e32 v249, v238
	v_cvt_f32_ubyte2_e32 v250, v238
	v_cvt_f32_ubyte3_e32 v251, v238
	v_mul_f32_e32 v248, s34, v248
	v_mul_f32_e32 v249, s34, v249
	v_mul_f32_e32 v250, s34, v250
	v_mul_f32_e32 v251, s34, v251
	v_fma_f32 v160, v14, v248, v160
	v_fma_f32 v161, v15, v249, v161
	v_fma_f32 v162, v16, v250, v162
	v_fma_f32 v163, v17, v251, v163
	v_mfma_f32_16x16x32_bf16 v[18:21], v[224:227], v[74:77], v[18:21]
	v_cvt_f32_ubyte0_e32 v248, v239
	v_cvt_f32_ubyte1_e32 v249, v239
	v_cvt_f32_ubyte2_e32 v250, v239
	v_cvt_f32_ubyte3_e32 v251, v239
	v_mul_f32_e32 v248, s34, v248
	v_mul_f32_e32 v249, s34, v249
	v_mul_f32_e32 v250, s34, v250
	v_mul_f32_e32 v251, s34, v251
	v_fma_f32 v156, v10, v248, v156
	v_fma_f32 v157, v11, v249, v157
	v_fma_f32 v158, v12, v250, v158
	v_fma_f32 v159, v13, v251, v159
	v_mfma_f32_16x16x32_bf16 v[62:65], v[228:231], v[74:77], v[62:65]
	v_cvt_f32_ubyte0_e32 v248, v240
	v_cvt_f32_ubyte1_e32 v249, v240
	v_cvt_f32_ubyte2_e32 v250, v240
	v_cvt_f32_ubyte3_e32 v251, v240
	v_mul_f32_e32 v248, s34, v248
	v_mul_f32_e32 v249, s34, v249
	v_mul_f32_e32 v250, s34, v250
	v_mul_f32_e32 v251, s34, v251
	v_fma_f32 v136, v34, v248, v136
	v_fma_f32 v137, v35, v249, v137
	v_fma_f32 v150, v36, v250, v150
	v_fma_f32 v151, v37, v251, v151
	ds_read_b128 v[74:77], v207 offset:36864
	v_mfma_f32_16x16x32_bf16 v[58:61], v[216:219], v[78:81], v[58:61]
	v_cvt_f32_ubyte0_e32 v248, v241
	v_cvt_f32_ubyte1_e32 v249, v241
	v_cvt_f32_ubyte2_e32 v250, v241
	v_cvt_f32_ubyte3_e32 v251, v241
	v_mul_f32_e32 v248, s34, v248
	v_mul_f32_e32 v249, s34, v249
	v_mul_f32_e32 v250, s34, v250
	v_mul_f32_e32 v251, s34, v251
	v_fma_f32 v130, v22, v248, v130
	v_fma_f32 v131, v23, v249, v131
	v_fma_f32 v134, v24, v250, v134
	v_fma_f32 v135, v25, v251, v135
	v_mfma_f32_16x16x32_bf16 v[54:57], v[220:223], v[78:81], v[54:57]
	v_cvt_f32_ubyte0_e32 v248, v242
	v_cvt_f32_ubyte1_e32 v249, v242
	v_cvt_f32_ubyte2_e32 v250, v242
	v_cvt_f32_ubyte3_e32 v251, v242
	v_mul_f32_e32 v248, s34, v248
	v_mul_f32_e32 v249, s34, v249
	v_mul_f32_e32 v250, s34, v250
	v_mul_f32_e32 v251, s34, v251
	v_fma_f32 v124, v18, v248, v124
	v_fma_f32 v125, v19, v249, v125
	v_fma_f32 v126, v20, v250, v126
	v_fma_f32 v127, v21, v251, v127
	v_mfma_f32_16x16x32_bf16 v[50:53], v[224:227], v[78:81], v[50:53]
	v_cvt_f32_ubyte0_e32 v248, v243
	v_cvt_f32_ubyte1_e32 v249, v243
	v_cvt_f32_ubyte2_e32 v250, v243
	v_cvt_f32_ubyte3_e32 v251, v243
	v_mul_f32_e32 v248, s34, v248
	v_mul_f32_e32 v249, s34, v249
	v_mul_f32_e32 v250, s34, v250
	v_mul_f32_e32 v251, s34, v251
	v_fma_f32 v120, v62, v248, v120
	v_fma_f32 v121, v63, v249, v121
	v_fma_f32 v122, v64, v250, v122
	v_fma_f32 v123, v65, v251, v123
	v_mfma_f32_16x16x32_bf16 v[2:5], v[228:231], v[78:81], v[2:5]
	v_cvt_f32_ubyte0_e32 v248, v244
	v_cvt_f32_ubyte1_e32 v249, v244
	v_cvt_f32_ubyte2_e32 v250, v244
	v_cvt_f32_ubyte3_e32 v251, v244
	v_mul_f32_e32 v248, s34, v248
	v_mul_f32_e32 v249, s34, v249
	v_mul_f32_e32 v250, s34, v250
	v_mul_f32_e32 v251, s34, v251
	v_fma_f32 v114, v58, v248, v114
	v_fma_f32 v115, v59, v249, v115
	v_fma_f32 v116, v60, v250, v116
	v_fma_f32 v117, v61, v251, v117
	ds_read_b128 v[78:81], v207 offset:38912
	s_nop 7
	s_nop 3
	v_cvt_f32_ubyte0_e32 v248, v245
	v_cvt_f32_ubyte1_e32 v249, v245
	v_cvt_f32_ubyte2_e32 v250, v245
	v_cvt_f32_ubyte3_e32 v251, v245
	v_mul_f32_e32 v248, s34, v248
	v_mul_f32_e32 v249, s34, v249
	v_mul_f32_e32 v250, s34, v250
	v_mul_f32_e32 v251, s34, v251
	v_fma_f32 v106, v54, v248, v106
	v_fma_f32 v107, v55, v249, v107
	v_fma_f32 v108, v56, v250, v108
	v_fma_f32 v109, v57, v251, v109
	v_cvt_f32_ubyte0_e32 v248, v246
	v_cvt_f32_ubyte1_e32 v249, v246
	v_cvt_f32_ubyte2_e32 v250, v246
	v_cvt_f32_ubyte3_e32 v251, v246
	v_mul_f32_e32 v248, s34, v248
	v_mul_f32_e32 v249, s34, v249
	v_mul_f32_e32 v250, s34, v250
	v_mul_f32_e32 v251, s34, v251
	v_fma_f32 v100, v50, v248, v100
	v_fma_f32 v101, v51, v249, v101
	v_fma_f32 v102, v52, v250, v102
	v_fma_f32 v103, v53, v251, v103
	v_cvt_f32_ubyte0_e32 v248, v247
	v_cvt_f32_ubyte1_e32 v249, v247
	v_cvt_f32_ubyte2_e32 v250, v247
	v_cvt_f32_ubyte3_e32 v251, v247
	v_mul_f32_e32 v248, s34, v248
	v_mul_f32_e32 v249, s34, v249
	v_mul_f32_e32 v250, s34, v250
	v_mul_f32_e32 v251, s34, v251
	v_fma_f32 v96, v2, v248, v96
	v_fma_f32 v97, v3, v249, v97
	v_fma_f32 v98, v4, v250, v98
	v_fma_f32 v99, v5, v251, v99
	s_add_u32 s98, s86, 0x2200
	s_addc_u32 s99, s87, 0
	global_load_dword v92, v93, s[98:99]
	ds_read_b128 v[216:219], v91 offset:16384
	ds_read_b128 v[220:223], v91 offset:18432
	ds_read_b128 v[224:227], v91 offset:20480
	ds_read_b128 v[228:231], v91 offset:22528
	s_waitcnt lgkmcnt(7)
	v_mfma_f32_16x16x32_bf16 v[6:9], v[82:85], v[66:69], 0
	v_mfma_f32_16x16x32_bf16 v[30:33], v[86:89], v[66:69], 0
	v_mfma_f32_16x16x32_bf16 v[38:41], v[208:211], v[66:69], 0
	v_mfma_f32_16x16x32_bf16 v[42:45], v[212:215], v[66:69], 0
	ds_read_b128 v[66:69], v119 offset:32768
	s_waitcnt lgkmcnt(7)
	v_mfma_f32_16x16x32_bf16 v[46:49], v[82:85], v[70:73], 0
	v_mfma_f32_16x16x32_bf16 v[26:29], v[86:89], v[70:73], 0
	v_mfma_f32_16x16x32_bf16 v[14:17], v[208:211], v[70:73], 0
	v_mfma_f32_16x16x32_bf16 v[10:13], v[212:215], v[70:73], 0
	ds_read_b128 v[70:73], v119 offset:34816
	s_waitcnt lgkmcnt(7)
	v_mfma_f32_16x16x32_bf16 v[34:37], v[82:85], v[74:77], 0
	v_mfma_f32_16x16x32_bf16 v[22:25], v[86:89], v[74:77], 0
	v_mfma_f32_16x16x32_bf16 v[18:21], v[208:211], v[74:77], 0
	v_mfma_f32_16x16x32_bf16 v[62:65], v[212:215], v[74:77], 0
	ds_read_b128 v[74:77], v119 offset:36864
	s_waitcnt lgkmcnt(7)
	v_mfma_f32_16x16x32_bf16 v[58:61], v[82:85], v[78:81], 0
	v_mfma_f32_16x16x32_bf16 v[54:57], v[86:89], v[78:81], 0
	v_mfma_f32_16x16x32_bf16 v[50:53], v[208:211], v[78:81], 0
	v_mfma_f32_16x16x32_bf16 v[2:5], v[212:215], v[78:81], 0
	ds_read_b128 v[78:81], v119 offset:38912
	s_waitcnt lgkmcnt(3)
	v_mfma_f32_16x16x32_bf16 v[6:9], v[216:219], v[66:69], v[6:9]
	v_mfma_f32_16x16x32_bf16 v[30:33], v[220:223], v[66:69], v[30:33]
	v_mfma_f32_16x16x32_bf16 v[38:41], v[224:227], v[66:69], v[38:41]
	v_mfma_f32_16x16x32_bf16 v[42:45], v[228:231], v[66:69], v[42:45]
	s_waitcnt lgkmcnt(2)
	v_mfma_f32_16x16x32_bf16 v[46:49], v[216:219], v[70:73], v[46:49]
	v_mfma_f32_16x16x32_bf16 v[26:29], v[220:223], v[70:73], v[26:29]
	v_mfma_f32_16x16x32_bf16 v[14:17], v[224:227], v[70:73], v[14:17]
	v_mfma_f32_16x16x32_bf16 v[10:13], v[228:231], v[70:73], v[10:13]
	s_waitcnt vmcnt(7)
	s_waitcnt lgkmcnt(0)
	s_barrier
	s_add_i32 m0, s67, 0x8000
	s_nop 0
	global_load_lds_dwordx4 v188, s[80:81]
	s_add_i32 m0, s67, 0xa000
	s_nop 0
	global_load_lds_dwordx4 v189, s[80:81]
	s_add_i32 m0, s67, 0xc000
	s_nop 0
	global_load_lds_dwordx4 v190, s[80:81]
	s_add_i32 m0, s67, 0xe000
	s_nop 0
	global_load_lds_dwordx4 v191, s[80:81]
	s_add_i32 m0, s67, 0x1c000
	s_nop 0
	global_load_lds_dwordx4 v205, s[96:97]
	s_add_i32 m0, s67, 0x1e000
	s_nop 0
	global_load_lds_dwordx4 v206, s[96:97]
	s_add_u32 s80, s80, 0x80
	s_addc_u32 s81, s81, 0
	s_add_u32 s96, s96, 0x80
	s_addc_u32 s97, s97, 0
	ds_read_b128 v[82:85], v90 offset:33792
	ds_read_b128 v[86:89], v90 offset:35840
	ds_read_b128 v[208:211], v90 offset:37888
	ds_read_b128 v[212:215], v90 offset:39936
	ds_read_b128 v[66:69], v0 offset:0
	ds_read_b128 v[70:73], v0 offset:2048
	v_mfma_f32_16x16x32_bf16 v[34:37], v[216:219], v[74:77], v[34:37]
	v_mfma_f32_16x16x32_bf16 v[22:25], v[220:223], v[74:77], v[22:25]
	v_mfma_f32_16x16x32_bf16 v[18:21], v[224:227], v[74:77], v[18:21]
	v_mfma_f32_16x16x32_bf16 v[62:65], v[228:231], v[74:77], v[62:65]
	ds_read_b128 v[74:77], v0 offset:4096
	v_mfma_f32_16x16x32_bf16 v[58:61], v[216:219], v[78:81], v[58:61]
	v_mfma_f32_16x16x32_bf16 v[54:57], v[220:223], v[78:81], v[54:57]
	v_mfma_f32_16x16x32_bf16 v[50:53], v[224:227], v[78:81], v[50:53]
	v_mfma_f32_16x16x32_bf16 v[2:5], v[228:231], v[78:81], v[2:5]
	ds_read_b128 v[78:81], v0 offset:6144
	ds_read_b128 v[216:219], v91 offset:33792
	ds_read_b128 v[220:223], v91 offset:35840
	ds_read_b128 v[224:227], v91 offset:37888
	ds_read_b128 v[228:231], v91 offset:39936
	s_waitcnt lgkmcnt(7)
	v_mfma_f32_16x16x32_bf16 v[6:9], v[82:85], v[66:69], v[6:9]
	v_mfma_f32_16x16x32_bf16 v[30:33], v[86:89], v[66:69], v[30:33]
	v_mfma_f32_16x16x32_bf16 v[38:41], v[208:211], v[66:69], v[38:41]
	v_mfma_f32_16x16x32_bf16 v[42:45], v[212:215], v[66:69], v[42:45]
	ds_read_b128 v[66:69], v255 offset:0
	s_waitcnt lgkmcnt(7)
	v_mfma_f32_16x16x32_bf16 v[46:49], v[82:85], v[70:73], v[46:49]
	v_mfma_f32_16x16x32_bf16 v[26:29], v[86:89], v[70:73], v[26:29]
	v_mfma_f32_16x16x32_bf16 v[14:17], v[208:211], v[70:73], v[14:17]
	v_mfma_f32_16x16x32_bf16 v[10:13], v[212:215], v[70:73], v[10:13]
	ds_read_b128 v[70:73], v255 offset:2048
	s_waitcnt lgkmcnt(7)
	v_mfma_f32_16x16x32_bf16 v[34:37], v[82:85], v[74:77], v[34:37]
	v_mfma_f32_16x16x32_bf16 v[22:25], v[86:89], v[74:77], v[22:25]
	v_mfma_f32_16x16x32_bf16 v[18:21], v[208:211], v[74:77], v[18:21]
	v_mfma_f32_16x16x32_bf16 v[62:65], v[212:215], v[74:77], v[62:65]
	ds_read_b128 v[74:77], v255 offset:4096
	s_waitcnt lgkmcnt(7)
	v_mfma_f32_16x16x32_bf16 v[58:61], v[82:85], v[78:81], v[58:61]
	v_mfma_f32_16x16x32_bf16 v[54:57], v[86:89], v[78:81], v[54:57]
	v_mfma_f32_16x16x32_bf16 v[50:53], v[208:211], v[78:81], v[50:53]
	v_mfma_f32_16x16x32_bf16 v[2:5], v[212:215], v[78:81], v[2:5]
	ds_read_b128 v[78:81], v255 offset:6144
	s_waitcnt lgkmcnt(3)
	v_mfma_f32_16x16x32_bf16 v[6:9], v[216:219], v[66:69], v[6:9]
	v_mfma_f32_16x16x32_bf16 v[30:33], v[220:223], v[66:69], v[30:33]
	v_mfma_f32_16x16x32_bf16 v[38:41], v[224:227], v[66:69], v[38:41]
	v_mfma_f32_16x16x32_bf16 v[42:45], v[228:231], v[66:69], v[42:45]
	s_waitcnt lgkmcnt(2)
	v_mfma_f32_16x16x32_bf16 v[46:49], v[216:219], v[70:73], v[46:49]
	v_mfma_f32_16x16x32_bf16 v[26:29], v[220:223], v[70:73], v[26:29]
	v_mfma_f32_16x16x32_bf16 v[14:17], v[224:227], v[70:73], v[14:17]
	v_mfma_f32_16x16x32_bf16 v[10:13], v[228:231], v[70:73], v[10:13]
	s_waitcnt vmcnt(7)
	s_waitcnt lgkmcnt(0)
	s_barrier
	s_add_i32 m0, s67, 0x10000
	s_nop 0
	global_load_lds_dwordx4 v188, s[80:81]
	s_add_i32 m0, s67, 0x12000
	s_nop 0
	global_load_lds_dwordx4 v189, s[80:81]
	s_add_i32 m0, s67, 0x14000
	s_nop 0
	global_load_lds_dwordx4 v190, s[80:81]
	s_add_i32 m0, s67, 0x16000
	s_nop 0
	global_load_lds_dwordx4 v191, s[80:81]
	s_add_i32 m0, s67, 0x20400
	s_nop 0
	global_load_lds_dwordx4 v205, s[96:97]
	s_add_i32 m0, s67, 0x22400
	s_nop 0
	global_load_lds_dwordx4 v206, s[96:97]
	s_add_u32 s80, s80, 0x80
	s_addc_u32 s81, s81, 0
	s_add_u32 s96, s96, 0x80
	s_addc_u32 s97, s97, 0
	ds_read_b128 v[82:85], v90 offset:0
	ds_read_b128 v[86:89], v90 offset:2048
	ds_read_b128 v[208:211], v90 offset:4096
	ds_read_b128 v[212:215], v90 offset:6144
	ds_read_b128 v[66:69], v207 offset:0
	ds_read_b128 v[70:73], v207 offset:2048
	v_mfma_f32_16x16x32_bf16 v[34:37], v[216:219], v[74:77], v[34:37]
	v_mfma_f32_16x16x32_bf16 v[22:25], v[220:223], v[74:77], v[22:25]
	v_mfma_f32_16x16x32_bf16 v[18:21], v[224:227], v[74:77], v[18:21]
	v_mfma_f32_16x16x32_bf16 v[62:65], v[228:231], v[74:77], v[62:65]
	ds_read_b128 v[74:77], v207 offset:4096
	v_mfma_f32_16x16x32_bf16 v[58:61], v[216:219], v[78:81], v[58:61]
	v_mfma_f32_16x16x32_bf16 v[54:57], v[220:223], v[78:81], v[54:57]
	v_mfma_f32_16x16x32_bf16 v[50:53], v[224:227], v[78:81], v[50:53]
	v_mfma_f32_16x16x32_bf16 v[2:5], v[228:231], v[78:81], v[2:5]
	ds_read_b128 v[78:81], v207 offset:6144
	ds_read_b128 v[216:219], v91 offset:0
	ds_read_b128 v[220:223], v91 offset:2048
	ds_read_b128 v[224:227], v91 offset:4096
	ds_read_b128 v[228:231], v91 offset:6144
	s_waitcnt lgkmcnt(7)
	v_mfma_f32_16x16x32_bf16 v[6:9], v[82:85], v[66:69], v[6:9]
	v_mfma_f32_16x16x32_bf16 v[30:33], v[86:89], v[66:69], v[30:33]
	v_mfma_f32_16x16x32_bf16 v[38:41], v[208:211], v[66:69], v[38:41]
	v_mfma_f32_16x16x32_bf16 v[42:45], v[212:215], v[66:69], v[42:45]
	ds_read_b128 v[66:69], v119 offset:0
	s_waitcnt lgkmcnt(7)
	v_mfma_f32_16x16x32_bf16 v[46:49], v[82:85], v[70:73], v[46:49]
	v_mfma_f32_16x16x32_bf16 v[26:29], v[86:89], v[70:73], v[26:29]
	v_mfma_f32_16x16x32_bf16 v[14:17], v[208:211], v[70:73], v[14:17]
	v_mfma_f32_16x16x32_bf16 v[10:13], v[212:215], v[70:73], v[10:13]
	ds_read_b128 v[70:73], v119 offset:2048
	s_waitcnt lgkmcnt(7)
	v_mfma_f32_16x16x32_bf16 v[34:37], v[82:85], v[74:77], v[34:37]
	v_mfma_f32_16x16x32_bf16 v[22:25], v[86:89], v[74:77], v[22:25]
	v_mfma_f32_16x16x32_bf16 v[18:21], v[208:211], v[74:77], v[18:21]
	v_mfma_f32_16x16x32_bf16 v[62:65], v[212:215], v[74:77], v[62:65]
	ds_read_b128 v[74:77], v119 offset:4096
	s_waitcnt lgkmcnt(7)
	v_mfma_f32_16x16x32_bf16 v[58:61], v[82:85], v[78:81], v[58:61]
	v_mfma_f32_16x16x32_bf16 v[54:57], v[86:89], v[78:81], v[54:57]
	v_mfma_f32_16x16x32_bf16 v[50:53], v[208:211], v[78:81], v[50:53]
	v_mfma_f32_16x16x32_bf16 v[2:5], v[212:215], v[78:81], v[2:5]
	ds_read_b128 v[78:81], v119 offset:6144
	s_waitcnt lgkmcnt(3)
	v_mfma_f32_16x16x32_bf16 v[6:9], v[216:219], v[66:69], v[6:9]
	v_mfma_f32_16x16x32_bf16 v[30:33], v[220:223], v[66:69], v[30:33]
	v_mfma_f32_16x16x32_bf16 v[38:41], v[224:227], v[66:69], v[38:41]
	v_mfma_f32_16x16x32_bf16 v[42:45], v[228:231], v[66:69], v[42:45]
	s_waitcnt lgkmcnt(2)
	v_mfma_f32_16x16x32_bf16 v[46:49], v[216:219], v[70:73], v[46:49]
	v_mfma_f32_16x16x32_bf16 v[26:29], v[220:223], v[70:73], v[26:29]
	v_mfma_f32_16x16x32_bf16 v[14:17], v[224:227], v[70:73], v[14:17]
	v_mfma_f32_16x16x32_bf16 v[10:13], v[228:231], v[70:73], v[10:13]
	s_waitcnt vmcnt(6)
	s_waitcnt lgkmcnt(0)
	s_barrier
	s_add_i32 m0, s67, 0x0
	s_nop 0
	global_load_lds_dwordx4 v188, s[80:81]
	s_add_i32 m0, s67, 0x2000
	s_nop 0
	global_load_lds_dwordx4 v189, s[80:81]
	s_add_i32 m0, s67, 0x4000
	s_nop 0
	global_load_lds_dwordx4 v190, s[80:81]
	s_add_i32 m0, s67, 0x6000
	s_nop 0
	global_load_lds_dwordx4 v191, s[80:81]
	s_add_i32 m0, s67, 0x18000
	s_nop 0
	global_load_lds_dwordx4 v205, s[96:97]
	s_add_i32 m0, s67, 0x1a000
	s_nop 0
	global_load_lds_dwordx4 v206, s[96:97]
	s_add_u32 s80, s80, 0x80
	s_addc_u32 s81, s81, 0
	s_add_u32 s96, s96, 0x80
	s_addc_u32 s97, s97, 0
	ds_read_b128 v[82:85], v90 offset:16384
	ds_read_b128 v[86:89], v90 offset:18432
	ds_read_b128 v[208:211], v90 offset:20480
	ds_read_b128 v[212:215], v90 offset:22528
	ds_read_b128 v[66:69], v207 offset:32768
	ds_read_b128 v[70:73], v207 offset:34816
	v_mfma_f32_16x16x32_bf16 v[34:37], v[216:219], v[74:77], v[34:37]
	v_mfma_f32_16x16x32_bf16 v[22:25], v[220:223], v[74:77], v[22:25]
	v_mfma_f32_16x16x32_bf16 v[18:21], v[224:227], v[74:77], v[18:21]
	v_mfma_f32_16x16x32_bf16 v[62:65], v[228:231], v[74:77], v[62:65]
	ds_read_b128 v[74:77], v207 offset:36864
	v_mfma_f32_16x16x32_bf16 v[58:61], v[216:219], v[78:81], v[58:61]
	v_mfma_f32_16x16x32_bf16 v[54:57], v[220:223], v[78:81], v[54:57]
	v_mfma_f32_16x16x32_bf16 v[50:53], v[224:227], v[78:81], v[50:53]
	v_mfma_f32_16x16x32_bf16 v[2:5], v[228:231], v[78:81], v[2:5]
	ds_read_b128 v[78:81], v207 offset:38912
	ds_read_b128 v[216:219], v91 offset:16384
	ds_read_b128 v[220:223], v91 offset:18432
	ds_read_b128 v[224:227], v91 offset:20480
	ds_read_b128 v[228:231], v91 offset:22528
	s_waitcnt lgkmcnt(7)
	v_mfma_f32_16x16x32_bf16 v[6:9], v[82:85], v[66:69], v[6:9]
	v_mfma_f32_16x16x32_bf16 v[30:33], v[86:89], v[66:69], v[30:33]
	v_mfma_f32_16x16x32_bf16 v[38:41], v[208:211], v[66:69], v[38:41]
	v_mfma_f32_16x16x32_bf16 v[42:45], v[212:215], v[66:69], v[42:45]
	ds_read_b128 v[66:69], v119 offset:32768
	s_waitcnt lgkmcnt(7)
	v_mfma_f32_16x16x32_bf16 v[46:49], v[82:85], v[70:73], v[46:49]
	v_mfma_f32_16x16x32_bf16 v[26:29], v[86:89], v[70:73], v[26:29]
	v_mfma_f32_16x16x32_bf16 v[14:17], v[208:211], v[70:73], v[14:17]
	v_mfma_f32_16x16x32_bf16 v[10:13], v[212:215], v[70:73], v[10:13]
	ds_read_b128 v[70:73], v119 offset:34816
	s_waitcnt lgkmcnt(7)
	v_mfma_f32_16x16x32_bf16 v[34:37], v[82:85], v[74:77], v[34:37]
	v_mfma_f32_16x16x32_bf16 v[22:25], v[86:89], v[74:77], v[22:25]
	v_mfma_f32_16x16x32_bf16 v[18:21], v[208:211], v[74:77], v[18:21]
	v_mfma_f32_16x16x32_bf16 v[62:65], v[212:215], v[74:77], v[62:65]
	ds_read_b128 v[74:77], v119 offset:36864
	s_waitcnt lgkmcnt(7)
	v_mfma_f32_16x16x32_bf16 v[58:61], v[82:85], v[78:81], v[58:61]
	v_mfma_f32_16x16x32_bf16 v[54:57], v[86:89], v[78:81], v[54:57]
	v_mfma_f32_16x16x32_bf16 v[50:53], v[208:211], v[78:81], v[50:53]
	v_mfma_f32_16x16x32_bf16 v[2:5], v[212:215], v[78:81], v[2:5]
	ds_read_b128 v[78:81], v119 offset:38912
	s_waitcnt lgkmcnt(3)
	v_mfma_f32_16x16x32_bf16 v[6:9], v[216:219], v[66:69], v[6:9]
	v_mfma_f32_16x16x32_bf16 v[30:33], v[220:223], v[66:69], v[30:33]
	v_mfma_f32_16x16x32_bf16 v[38:41], v[224:227], v[66:69], v[38:41]
	v_mfma_f32_16x16x32_bf16 v[42:45], v[228:231], v[66:69], v[42:45]
	s_waitcnt lgkmcnt(2)
	v_mfma_f32_16x16x32_bf16 v[46:49], v[216:219], v[70:73], v[46:49]
	v_mfma_f32_16x16x32_bf16 v[26:29], v[220:223], v[70:73], v[26:29]
	v_mfma_f32_16x16x32_bf16 v[14:17], v[224:227], v[70:73], v[14:17]
	v_mfma_f32_16x16x32_bf16 v[10:13], v[228:231], v[70:73], v[10:13]
	s_waitcnt vmcnt(6)
	s_waitcnt lgkmcnt(0)
	s_barrier
	s_add_i32 m0, s67, 0x8000
	s_nop 0
	global_load_lds_dwordx4 v188, s[80:81]
	s_add_i32 m0, s67, 0xa000
	s_nop 0
	global_load_lds_dwordx4 v189, s[80:81]
	s_add_i32 m0, s67, 0xc000
	s_nop 0
	global_load_lds_dwordx4 v190, s[80:81]
	s_add_i32 m0, s67, 0xe000
	s_nop 0
	global_load_lds_dwordx4 v191, s[80:81]
	s_add_i32 m0, s67, 0x1c000
	s_nop 0
	global_load_lds_dwordx4 v205, s[96:97]
	s_add_i32 m0, s67, 0x1e000
	s_nop 0
	global_load_lds_dwordx4 v206, s[96:97]
	s_add_u32 s80, s80, 0x80
	s_addc_u32 s81, s81, 0
	s_add_u32 s96, s96, 0x80
	s_addc_u32 s97, s97, 0
	s_movk_i32 s10, 0x800
	s_mov_b32 s11, 0
	v_lshl_add_u64 v[248:249], v[128:129], 0, s[10:11]
	global_load_dwordx2 v[232:233], v[248:249], off
	global_load_dwordx2 v[234:235], v[248:249], off offset:32
	v_lshl_add_u64 v[248:249], v[132:133], 0, s[10:11]
	global_load_dwordx2 v[236:237], v[248:249], off
	global_load_dwordx2 v[238:239], v[248:249], off offset:32
	v_lshl_add_u64 v[248:249], v[152:153], 0, s[10:11]
	global_load_dwordx2 v[240:241], v[248:249], off
	global_load_dwordx2 v[242:243], v[248:249], off offset:32
	v_lshl_add_u64 v[248:249], v[154:155], 0, s[10:11]
	global_load_dwordx2 v[244:245], v[248:249], off
	global_load_dwordx2 v[246:247], v[248:249], off offset:32
	ds_read_b128 v[82:85], v90 offset:33792
	ds_read_b128 v[86:89], v90 offset:35840
	ds_read_b128 v[208:211], v90 offset:37888
	ds_read_b128 v[212:215], v90 offset:39936
	ds_read_b128 v[66:69], v0 offset:0
	ds_read_b128 v[70:73], v0 offset:2048
	v_mfma_f32_16x16x32_bf16 v[34:37], v[216:219], v[74:77], v[34:37]
	v_mfma_f32_16x16x32_bf16 v[22:25], v[220:223], v[74:77], v[22:25]
	v_mfma_f32_16x16x32_bf16 v[18:21], v[224:227], v[74:77], v[18:21]
	v_mfma_f32_16x16x32_bf16 v[62:65], v[228:231], v[74:77], v[62:65]
	ds_read_b128 v[74:77], v0 offset:4096
	v_mfma_f32_16x16x32_bf16 v[58:61], v[216:219], v[78:81], v[58:61]
	v_mfma_f32_16x16x32_bf16 v[54:57], v[220:223], v[78:81], v[54:57]
	v_mfma_f32_16x16x32_bf16 v[50:53], v[224:227], v[78:81], v[50:53]
	v_mfma_f32_16x16x32_bf16 v[2:5], v[228:231], v[78:81], v[2:5]
	ds_read_b128 v[78:81], v0 offset:6144
	ds_read_b128 v[216:219], v91 offset:33792
	ds_read_b128 v[220:223], v91 offset:35840
	ds_read_b128 v[224:227], v91 offset:37888
	ds_read_b128 v[228:231], v91 offset:39936
	s_waitcnt lgkmcnt(7)
	v_mfma_f32_16x16x32_bf16 v[6:9], v[82:85], v[66:69], v[6:9]
	v_mfma_f32_16x16x32_bf16 v[30:33], v[86:89], v[66:69], v[30:33]
	v_mfma_f32_16x16x32_bf16 v[38:41], v[208:211], v[66:69], v[38:41]
	v_mfma_f32_16x16x32_bf16 v[42:45], v[212:215], v[66:69], v[42:45]
	ds_read_b128 v[66:69], v255 offset:0
	s_waitcnt lgkmcnt(7)
	v_mfma_f32_16x16x32_bf16 v[46:49], v[82:85], v[70:73], v[46:49]
	v_mfma_f32_16x16x32_bf16 v[26:29], v[86:89], v[70:73], v[26:29]
	v_mfma_f32_16x16x32_bf16 v[14:17], v[208:211], v[70:73], v[14:17]
	v_mfma_f32_16x16x32_bf16 v[10:13], v[212:215], v[70:73], v[10:13]
	ds_read_b128 v[70:73], v255 offset:2048
	s_waitcnt lgkmcnt(7)
	v_mfma_f32_16x16x32_bf16 v[34:37], v[82:85], v[74:77], v[34:37]
	v_mfma_f32_16x16x32_bf16 v[22:25], v[86:89], v[74:77], v[22:25]
	v_mfma_f32_16x16x32_bf16 v[18:21], v[208:211], v[74:77], v[18:21]
	v_mfma_f32_16x16x32_bf16 v[62:65], v[212:215], v[74:77], v[62:65]
	ds_read_b128 v[74:77], v255 offset:4096
	s_waitcnt lgkmcnt(7)
	v_mfma_f32_16x16x32_bf16 v[58:61], v[82:85], v[78:81], v[58:61]
	v_mfma_f32_16x16x32_bf16 v[54:57], v[86:89], v[78:81], v[54:57]
	v_mfma_f32_16x16x32_bf16 v[50:53], v[208:211], v[78:81], v[50:53]
	v_mfma_f32_16x16x32_bf16 v[2:5], v[212:215], v[78:81], v[2:5]
	ds_read_b128 v[78:81], v255 offset:6144
	s_waitcnt lgkmcnt(3)
	v_mfma_f32_16x16x32_bf16 v[6:9], v[216:219], v[66:69], v[6:9]
	v_mfma_f32_16x16x32_bf16 v[30:33], v[220:223], v[66:69], v[30:33]
	v_mfma_f32_16x16x32_bf16 v[38:41], v[224:227], v[66:69], v[38:41]
	v_mfma_f32_16x16x32_bf16 v[42:45], v[228:231], v[66:69], v[42:45]
	s_waitcnt lgkmcnt(2)
	v_mfma_f32_16x16x32_bf16 v[46:49], v[216:219], v[70:73], v[46:49]
	v_mfma_f32_16x16x32_bf16 v[26:29], v[220:223], v[70:73], v[26:29]
	v_mfma_f32_16x16x32_bf16 v[14:17], v[224:227], v[70:73], v[14:17]
	v_mfma_f32_16x16x32_bf16 v[10:13], v[228:231], v[70:73], v[10:13]
	s_waitcnt vmcnt(14)
	s_waitcnt lgkmcnt(0)
	s_barrier
	s_add_i32 m0, s67, 0x10000
	s_nop 0
	global_load_lds_dwordx4 v188, s[80:81]
	s_add_i32 m0, s67, 0x12000
	s_nop 0
	global_load_lds_dwordx4 v189, s[80:81]
	s_add_i32 m0, s67, 0x14000
	s_nop 0
	global_load_lds_dwordx4 v190, s[80:81]
	s_add_i32 m0, s67, 0x16000
	s_nop 0
	global_load_lds_dwordx4 v191, s[80:81]
	s_add_i32 m0, s67, 0x20400
	s_nop 0
	global_load_lds_dwordx4 v205, s[96:97]
	s_add_i32 m0, s67, 0x22400
	s_nop 0
	global_load_lds_dwordx4 v206, s[96:97]
	s_add_u32 s80, s80, 0x880
	s_addc_u32 s81, s81, 0
	s_add_u32 s96, s96, 0xffc80
	s_addc_u32 s97, s97, 0
	ds_read_b128 v[82:85], v90 offset:0
	ds_read_b128 v[86:89], v90 offset:2048
	ds_read_b128 v[208:211], v90 offset:4096
	ds_read_b128 v[212:215], v90 offset:6144
	ds_read_b128 v[66:69], v207 offset:0
	ds_read_b128 v[70:73], v207 offset:2048
	v_mfma_f32_16x16x32_bf16 v[34:37], v[216:219], v[74:77], v[34:37]
	v_mfma_f32_16x16x32_bf16 v[22:25], v[220:223], v[74:77], v[22:25]
	v_mfma_f32_16x16x32_bf16 v[18:21], v[224:227], v[74:77], v[18:21]
	v_mfma_f32_16x16x32_bf16 v[62:65], v[228:231], v[74:77], v[62:65]
	ds_read_b128 v[74:77], v207 offset:4096
	v_mfma_f32_16x16x32_bf16 v[58:61], v[216:219], v[78:81], v[58:61]
	v_mfma_f32_16x16x32_bf16 v[54:57], v[220:223], v[78:81], v[54:57]
	v_mfma_f32_16x16x32_bf16 v[50:53], v[224:227], v[78:81], v[50:53]
	v_mfma_f32_16x16x32_bf16 v[2:5], v[228:231], v[78:81], v[2:5]
	ds_read_b128 v[78:81], v207 offset:6144
	ds_read_b128 v[216:219], v91 offset:0
	ds_read_b128 v[220:223], v91 offset:2048
	ds_read_b128 v[224:227], v91 offset:4096
	ds_read_b128 v[228:231], v91 offset:6144
	s_waitcnt lgkmcnt(7)
	v_mfma_f32_16x16x32_bf16 v[6:9], v[82:85], v[66:69], v[6:9]
	v_mfma_f32_16x16x32_bf16 v[30:33], v[86:89], v[66:69], v[30:33]
	v_mfma_f32_16x16x32_bf16 v[38:41], v[208:211], v[66:69], v[38:41]
	v_mfma_f32_16x16x32_bf16 v[42:45], v[212:215], v[66:69], v[42:45]
	ds_read_b128 v[66:69], v119 offset:0
	s_waitcnt lgkmcnt(7)
	v_mfma_f32_16x16x32_bf16 v[46:49], v[82:85], v[70:73], v[46:49]
	v_mfma_f32_16x16x32_bf16 v[26:29], v[86:89], v[70:73], v[26:29]
	v_mfma_f32_16x16x32_bf16 v[14:17], v[208:211], v[70:73], v[14:17]
	v_mfma_f32_16x16x32_bf16 v[10:13], v[212:215], v[70:73], v[10:13]
	ds_read_b128 v[70:73], v119 offset:2048
	s_waitcnt lgkmcnt(7)
	v_mfma_f32_16x16x32_bf16 v[34:37], v[82:85], v[74:77], v[34:37]
	v_mfma_f32_16x16x32_bf16 v[22:25], v[86:89], v[74:77], v[22:25]
	v_mfma_f32_16x16x32_bf16 v[18:21], v[208:211], v[74:77], v[18:21]
	v_mfma_f32_16x16x32_bf16 v[62:65], v[212:215], v[74:77], v[62:65]
	ds_read_b128 v[74:77], v119 offset:4096
	s_waitcnt lgkmcnt(7)
	v_mfma_f32_16x16x32_bf16 v[58:61], v[82:85], v[78:81], v[58:61]
	v_mfma_f32_16x16x32_bf16 v[54:57], v[86:89], v[78:81], v[54:57]
	v_mfma_f32_16x16x32_bf16 v[50:53], v[208:211], v[78:81], v[50:53]
	v_mfma_f32_16x16x32_bf16 v[2:5], v[212:215], v[78:81], v[2:5]
	ds_read_b128 v[78:81], v119 offset:6144
	s_waitcnt lgkmcnt(3)
	v_mfma_f32_16x16x32_bf16 v[6:9], v[216:219], v[66:69], v[6:9]
	v_mfma_f32_16x16x32_bf16 v[30:33], v[220:223], v[66:69], v[30:33]
	v_mfma_f32_16x16x32_bf16 v[38:41], v[224:227], v[66:69], v[38:41]
	v_mfma_f32_16x16x32_bf16 v[42:45], v[228:231], v[66:69], v[42:45]
	s_waitcnt lgkmcnt(2)
	v_mfma_f32_16x16x32_bf16 v[46:49], v[216:219], v[70:73], v[46:49]
	v_mfma_f32_16x16x32_bf16 v[26:29], v[220:223], v[70:73], v[26:29]
	v_mfma_f32_16x16x32_bf16 v[14:17], v[224:227], v[70:73], v[14:17]
	v_mfma_f32_16x16x32_bf16 v[10:13], v[228:231], v[70:73], v[10:13]
	s_waitcnt vmcnt(14)
	s_waitcnt lgkmcnt(0)
	s_barrier
	s_add_i32 m0, s67, 0x0
	s_nop 0
	global_load_lds_dwordx4 v188, s[80:81]
	s_add_i32 m0, s67, 0x2000
	s_nop 0
	global_load_lds_dwordx4 v189, s[80:81]
	s_add_i32 m0, s67, 0x4000
	s_nop 0
	global_load_lds_dwordx4 v190, s[80:81]
	s_add_i32 m0, s67, 0x6000
	s_nop 0
	global_load_lds_dwordx4 v191, s[80:81]
	s_add_i32 m0, s67, 0x18000
	s_nop 0
	global_load_lds_dwordx4 v205, s[96:97]
	s_add_i32 m0, s67, 0x1a000
	s_nop 0
	global_load_lds_dwordx4 v206, s[96:97]
	s_add_u32 s80, s80, 0x80
	s_addc_u32 s81, s81, 0
	s_add_u32 s96, s96, 0x80
	s_addc_u32 s97, s97, 0
	ds_read_b128 v[82:85], v90 offset:16384
	ds_read_b128 v[86:89], v90 offset:18432
	ds_read_b128 v[208:211], v90 offset:20480
	ds_read_b128 v[212:215], v90 offset:22528
	ds_read_b128 v[66:69], v207 offset:32768
	ds_read_b128 v[70:73], v207 offset:34816
	v_mfma_f32_16x16x32_bf16 v[34:37], v[216:219], v[74:77], v[34:37]
	v_mfma_f32_16x16x32_bf16 v[22:25], v[220:223], v[74:77], v[22:25]
	v_mfma_f32_16x16x32_bf16 v[18:21], v[224:227], v[74:77], v[18:21]
	v_mfma_f32_16x16x32_bf16 v[62:65], v[228:231], v[74:77], v[62:65]
	ds_read_b128 v[74:77], v207 offset:36864
	v_mfma_f32_16x16x32_bf16 v[58:61], v[216:219], v[78:81], v[58:61]
	v_mfma_f32_16x16x32_bf16 v[54:57], v[220:223], v[78:81], v[54:57]
	v_mfma_f32_16x16x32_bf16 v[50:53], v[224:227], v[78:81], v[50:53]
	v_mfma_f32_16x16x32_bf16 v[2:5], v[228:231], v[78:81], v[2:5]
	ds_read_b128 v[78:81], v207 offset:38912
	ds_read_b128 v[216:219], v91 offset:16384
	ds_read_b128 v[220:223], v91 offset:18432
	ds_read_b128 v[224:227], v91 offset:20480
	ds_read_b128 v[228:231], v91 offset:22528
	s_waitcnt lgkmcnt(7)
	v_mfma_f32_16x16x32_bf16 v[6:9], v[82:85], v[66:69], v[6:9]
	v_mfma_f32_16x16x32_bf16 v[30:33], v[86:89], v[66:69], v[30:33]
	v_mfma_f32_16x16x32_bf16 v[38:41], v[208:211], v[66:69], v[38:41]
	v_mfma_f32_16x16x32_bf16 v[42:45], v[212:215], v[66:69], v[42:45]
	ds_read_b128 v[66:69], v119 offset:32768
	s_waitcnt lgkmcnt(7)
	v_mfma_f32_16x16x32_bf16 v[46:49], v[82:85], v[70:73], v[46:49]
	v_mfma_f32_16x16x32_bf16 v[26:29], v[86:89], v[70:73], v[26:29]
	v_mfma_f32_16x16x32_bf16 v[14:17], v[208:211], v[70:73], v[14:17]
	v_mfma_f32_16x16x32_bf16 v[10:13], v[212:215], v[70:73], v[10:13]
	ds_read_b128 v[70:73], v119 offset:34816
	s_waitcnt lgkmcnt(7)
	v_mfma_f32_16x16x32_bf16 v[34:37], v[82:85], v[74:77], v[34:37]
	v_mfma_f32_16x16x32_bf16 v[22:25], v[86:89], v[74:77], v[22:25]
	v_mfma_f32_16x16x32_bf16 v[18:21], v[208:211], v[74:77], v[18:21]
	v_mfma_f32_16x16x32_bf16 v[62:65], v[212:215], v[74:77], v[62:65]
	ds_read_b128 v[74:77], v119 offset:36864
	s_waitcnt lgkmcnt(7)
	v_mfma_f32_16x16x32_bf16 v[58:61], v[82:85], v[78:81], v[58:61]
	v_mfma_f32_16x16x32_bf16 v[54:57], v[86:89], v[78:81], v[54:57]
	v_mfma_f32_16x16x32_bf16 v[50:53], v[208:211], v[78:81], v[50:53]
	v_mfma_f32_16x16x32_bf16 v[2:5], v[212:215], v[78:81], v[2:5]
	ds_read_b128 v[78:81], v119 offset:38912
	s_waitcnt lgkmcnt(3)
	v_mfma_f32_16x16x32_bf16 v[6:9], v[216:219], v[66:69], v[6:9]
	v_mfma_f32_16x16x32_bf16 v[30:33], v[220:223], v[66:69], v[30:33]
	v_mfma_f32_16x16x32_bf16 v[38:41], v[224:227], v[66:69], v[38:41]
	v_mfma_f32_16x16x32_bf16 v[42:45], v[228:231], v[66:69], v[42:45]
	s_waitcnt lgkmcnt(2)
	v_mfma_f32_16x16x32_bf16 v[46:49], v[216:219], v[70:73], v[46:49]
	v_mfma_f32_16x16x32_bf16 v[26:29], v[220:223], v[70:73], v[26:29]
	v_mfma_f32_16x16x32_bf16 v[14:17], v[224:227], v[70:73], v[14:17]
	v_mfma_f32_16x16x32_bf16 v[10:13], v[228:231], v[70:73], v[10:13]
	s_waitcnt vmcnt(6)
	s_waitcnt lgkmcnt(0)
	s_barrier
	s_add_i32 m0, s67, 0x8000
	s_nop 0
	global_load_lds_dwordx4 v188, s[80:81]
	s_add_i32 m0, s67, 0xa000
	s_nop 0
	global_load_lds_dwordx4 v189, s[80:81]
	s_add_i32 m0, s67, 0xc000
	s_nop 0
	global_load_lds_dwordx4 v190, s[80:81]
	s_add_i32 m0, s67, 0xe000
	s_nop 0
	global_load_lds_dwordx4 v191, s[80:81]
	s_add_i32 m0, s67, 0x1c000
	s_nop 0
	global_load_lds_dwordx4 v205, s[96:97]
	s_add_i32 m0, s67, 0x1e000
	s_nop 0
	global_load_lds_dwordx4 v206, s[96:97]
	s_add_u32 s80, s80, 0x80
	s_addc_u32 s81, s81, 0
	s_add_u32 s96, s96, 0x80
	s_addc_u32 s97, s97, 0
	ds_read_b128 v[82:85], v90 offset:33792
	ds_read_b128 v[86:89], v90 offset:35840
	ds_read_b128 v[208:211], v90 offset:37888
	ds_read_b128 v[212:215], v90 offset:39936
	ds_read_b128 v[66:69], v0 offset:0
	ds_read_b128 v[70:73], v0 offset:2048
	v_mfma_f32_16x16x32_bf16 v[34:37], v[216:219], v[74:77], v[34:37]
	v_mfma_f32_16x16x32_bf16 v[22:25], v[220:223], v[74:77], v[22:25]
	v_mfma_f32_16x16x32_bf16 v[18:21], v[224:227], v[74:77], v[18:21]
	v_mfma_f32_16x16x32_bf16 v[62:65], v[228:231], v[74:77], v[62:65]
	ds_read_b128 v[74:77], v0 offset:4096
	v_mfma_f32_16x16x32_bf16 v[58:61], v[216:219], v[78:81], v[58:61]
	v_mfma_f32_16x16x32_bf16 v[54:57], v[220:223], v[78:81], v[54:57]
	v_mfma_f32_16x16x32_bf16 v[50:53], v[224:227], v[78:81], v[50:53]
	v_mfma_f32_16x16x32_bf16 v[2:5], v[228:231], v[78:81], v[2:5]
	ds_read_b128 v[78:81], v0 offset:6144
	ds_read_b128 v[216:219], v91 offset:33792
	ds_read_b128 v[220:223], v91 offset:35840
	ds_read_b128 v[224:227], v91 offset:37888
	ds_read_b128 v[228:231], v91 offset:39936
	s_waitcnt lgkmcnt(7)
	v_mfma_f32_16x16x32_bf16 v[6:9], v[82:85], v[66:69], v[6:9]
	v_mfma_f32_16x16x32_bf16 v[30:33], v[86:89], v[66:69], v[30:33]
	v_mfma_f32_16x16x32_bf16 v[38:41], v[208:211], v[66:69], v[38:41]
	v_mfma_f32_16x16x32_bf16 v[42:45], v[212:215], v[66:69], v[42:45]
	ds_read_b128 v[66:69], v255 offset:0
	s_waitcnt lgkmcnt(7)
	v_mfma_f32_16x16x32_bf16 v[46:49], v[82:85], v[70:73], v[46:49]
	v_mfma_f32_16x16x32_bf16 v[26:29], v[86:89], v[70:73], v[26:29]
	v_mfma_f32_16x16x32_bf16 v[14:17], v[208:211], v[70:73], v[14:17]
	v_mfma_f32_16x16x32_bf16 v[10:13], v[212:215], v[70:73], v[10:13]
	ds_read_b128 v[70:73], v255 offset:2048
	s_waitcnt lgkmcnt(7)
	v_mfma_f32_16x16x32_bf16 v[34:37], v[82:85], v[74:77], v[34:37]
	v_mfma_f32_16x16x32_bf16 v[22:25], v[86:89], v[74:77], v[22:25]
	v_mfma_f32_16x16x32_bf16 v[18:21], v[208:211], v[74:77], v[18:21]
	v_mfma_f32_16x16x32_bf16 v[62:65], v[212:215], v[74:77], v[62:65]
	ds_read_b128 v[74:77], v255 offset:4096
	s_waitcnt lgkmcnt(7)
	v_mfma_f32_16x16x32_bf16 v[58:61], v[82:85], v[78:81], v[58:61]
	v_mfma_f32_16x16x32_bf16 v[54:57], v[86:89], v[78:81], v[54:57]
	v_mfma_f32_16x16x32_bf16 v[50:53], v[208:211], v[78:81], v[50:53]
	v_mfma_f32_16x16x32_bf16 v[2:5], v[212:215], v[78:81], v[2:5]
	ds_read_b128 v[78:81], v255 offset:6144
	s_waitcnt lgkmcnt(3)
	v_mfma_f32_16x16x32_bf16 v[6:9], v[216:219], v[66:69], v[6:9]
	s_waitcnt vmcnt(18)
	v_mfma_f32_16x16x32_bf16 v[30:33], v[220:223], v[66:69], v[30:33]
	v_mfma_f32_16x16x32_bf16 v[38:41], v[224:227], v[66:69], v[38:41]
	v_mfma_f32_16x16x32_bf16 v[42:45], v[228:231], v[66:69], v[42:45]
	v_cvt_f32_ubyte0_e32 v248, v232
	v_cvt_f32_ubyte1_e32 v249, v232
	v_cvt_f32_ubyte2_e32 v250, v232
	v_cvt_f32_ubyte3_e32 v251, v232
	v_mul_f32_e32 v248, s34, v248
	v_mul_f32_e32 v249, s34, v249
	v_mul_f32_e32 v250, s34, v250
	v_mul_f32_e32 v251, s34, v251
	v_fma_f32 v184, v6, v248, v184
	v_fma_f32 v185, v7, v249, v185
	v_fma_f32 v186, v8, v250, v186
	v_fma_f32 v187, v9, v251, v187
	s_waitcnt lgkmcnt(2)
	v_mfma_f32_16x16x32_bf16 v[46:49], v[216:219], v[70:73], v[46:49]
	v_cvt_f32_ubyte0_e32 v248, v233
	v_cvt_f32_ubyte1_e32 v249, v233
	v_cvt_f32_ubyte2_e32 v250, v233
	v_cvt_f32_ubyte3_e32 v251, v233
	v_mul_f32_e32 v248, s34, v248
	v_mul_f32_e32 v249, s34, v249
	v_mul_f32_e32 v250, s34, v250
	v_mul_f32_e32 v251, s34, v251
	v_fma_f32 v180, v30, v248, v180
	v_fma_f32 v181, v31, v249, v181
	v_fma_f32 v182, v32, v250, v182
	v_fma_f32 v183, v33, v251, v183
	v_mfma_f32_16x16x32_bf16 v[26:29], v[220:223], v[70:73], v[26:29]
	v_cvt_f32_ubyte0_e32 v248, v234
	v_cvt_f32_ubyte1_e32 v249, v234
	v_cvt_f32_ubyte2_e32 v250, v234
	v_cvt_f32_ubyte3_e32 v251, v234
	v_mul_f32_e32 v248, s34, v248
	v_mul_f32_e32 v249, s34, v249
	v_mul_f32_e32 v250, s34, v250
	v_mul_f32_e32 v251, s34, v251
	v_fma_f32 v176, v38, v248, v176
	v_fma_f32 v177, v39, v249, v177
	v_fma_f32 v178, v40, v250, v178
	v_fma_f32 v179, v41, v251, v179
	v_mfma_f32_16x16x32_bf16 v[14:17], v[224:227], v[70:73], v[14:17]
	v_cvt_f32_ubyte0_e32 v248, v235
	v_cvt_f32_ubyte1_e32 v249, v235
	v_cvt_f32_ubyte2_e32 v250, v235
	v_cvt_f32_ubyte3_e32 v251, v235
	v_mul_f32_e32 v248, s34, v248
	v_mul_f32_e32 v249, s34, v249
	v_mul_f32_e32 v250, s34, v250
	v_mul_f32_e32 v251, s34, v251
	v_fma_f32 v172, v42, v248, v172
	v_fma_f32 v173, v43, v249, v173
	v_fma_f32 v174, v44, v250, v174
	v_fma_f32 v175, v45, v251, v175
	v_mfma_f32_16x16x32_bf16 v[10:13], v[228:231], v[70:73], v[10:13]
	v_cvt_f32_ubyte0_e32 v248, v236
	v_cvt_f32_ubyte1_e32 v249, v236
	v_cvt_f32_ubyte2_e32 v250, v236
	v_cvt_f32_ubyte3_e32 v251, v236
	v_mul_f32_e32 v248, s34, v248
	v_mul_f32_e32 v249, s34, v249
	v_mul_f32_e32 v250, s34, v250
	v_mul_f32_e32 v251, s34, v251
	v_fma_f32 v168, v46, v248, v168
	v_fma_f32 v169, v47, v249, v169
	v_fma_f32 v170, v48, v250, v170
	v_fma_f32 v171, v49, v251, v171
	s_waitcnt vmcnt(6)
	s_waitcnt lgkmcnt(0)
	s_barrier
	s_add_i32 m0, s67, 0x10000
	s_nop 0
	global_load_lds_dwordx4 v188, s[80:81]
	s_add_i32 m0, s67, 0x12000
	s_nop 0
	global_load_lds_dwordx4 v189, s[80:81]
	s_add_i32 m0, s67, 0x14000
	s_nop 0
	global_load_lds_dwordx4 v190, s[80:81]
	s_add_i32 m0, s67, 0x16000
	s_nop 0
	global_load_lds_dwordx4 v191, s[80:81]
	s_add_i32 m0, s67, 0x20400
	s_nop 0
	global_load_lds_dwordx4 v205, s[96:97]
	s_add_i32 m0, s67, 0x22400
	s_nop 0
	global_load_lds_dwordx4 v206, s[96:97]
	s_add_u32 s80, s80, 0x80
	s_addc_u32 s81, s81, 0
	s_add_u32 s96, s96, 0x80
	s_addc_u32 s97, s97, 0
	ds_read_b128 v[82:85], v90 offset:0
	ds_read_b128 v[86:89], v90 offset:2048
	ds_read_b128 v[208:211], v90 offset:4096
	ds_read_b128 v[212:215], v90 offset:6144
	ds_read_b128 v[66:69], v207 offset:0
	ds_read_b128 v[70:73], v207 offset:2048
	v_mfma_f32_16x16x32_bf16 v[34:37], v[216:219], v[74:77], v[34:37]
	v_cvt_f32_ubyte0_e32 v248, v237
	v_cvt_f32_ubyte1_e32 v249, v237
	v_cvt_f32_ubyte2_e32 v250, v237
	v_cvt_f32_ubyte3_e32 v251, v237
	v_mul_f32_e32 v248, s34, v248
	v_mul_f32_e32 v249, s34, v249
	v_mul_f32_e32 v250, s34, v250
	v_mul_f32_e32 v251, s34, v251
	v_fma_f32 v164, v26, v248, v164
	v_fma_f32 v165, v27, v249, v165
	v_fma_f32 v166, v28, v250, v166
	v_fma_f32 v167, v29, v251, v167
	v_mfma_f32_16x16x32_bf16 v[22:25], v[220:223], v[74:77], v[22:25]
	v_cvt_f32_ubyte0_e32 v248, v238
	v_cvt_f32_ubyte1_e32 v249, v238
	v_cvt_f32_ubyte2_e32 v250, v238
	v_cvt_f32_ubyte3_e32 v251, v238
	v_mul_f32_e32 v248, s34, v248
	v_mul_f32_e32 v249, s34, v249
	v_mul_f32_e32 v250, s34, v250
	v_mul_f32_e32 v251, s34, v251
	v_fma_f32 v160, v14, v248, v160
	v_fma_f32 v161, v15, v249, v161
	v_fma_f32 v162, v16, v250, v162
	v_fma_f32 v163, v17, v251, v163
	v_mfma_f32_16x16x32_bf16 v[18:21], v[224:227], v[74:77], v[18:21]
	v_cvt_f32_ubyte0_e32 v248, v239
	v_cvt_f32_ubyte1_e32 v249, v239
	v_cvt_f32_ubyte2_e32 v250, v239
	v_cvt_f32_ubyte3_e32 v251, v239
	v_mul_f32_e32 v248, s34, v248
	v_mul_f32_e32 v249, s34, v249
	v_mul_f32_e32 v250, s34, v250
	v_mul_f32_e32 v251, s34, v251
	v_fma_f32 v156, v10, v248, v156
	v_fma_f32 v157, v11, v249, v157
	v_fma_f32 v158, v12, v250, v158
	v_fma_f32 v159, v13, v251, v159
	v_mfma_f32_16x16x32_bf16 v[62:65], v[228:231], v[74:77], v[62:65]
	v_cvt_f32_ubyte0_e32 v248, v240
	v_cvt_f32_ubyte1_e32 v249, v240
	v_cvt_f32_ubyte2_e32 v250, v240
	v_cvt_f32_ubyte3_e32 v251, v240
	v_mul_f32_e32 v248, s34, v248
	v_mul_f32_e32 v249, s34, v249
	v_mul_f32_e32 v250, s34, v250
	v_mul_f32_e32 v251, s34, v251
	v_fma_f32 v136, v34, v248, v136
	v_fma_f32 v137, v35, v249, v137
	v_fma_f32 v150, v36, v250, v150
	v_fma_f32 v151, v37, v251, v151
	ds_read_b128 v[74:77], v207 offset:4096
	v_mfma_f32_16x16x32_bf16 v[58:61], v[216:219], v[78:81], v[58:61]
	v_cvt_f32_ubyte0_e32 v248, v241
	v_cvt_f32_ubyte1_e32 v249, v241
	v_cvt_f32_ubyte2_e32 v250, v241
	v_cvt_f32_ubyte3_e32 v251, v241
	v_mul_f32_e32 v248, s34, v248
	v_mul_f32_e32 v249, s34, v249
	v_mul_f32_e32 v250, s34, v250
	v_mul_f32_e32 v251, s34, v251
	v_fma_f32 v130, v22, v248, v130
	v_fma_f32 v131, v23, v249, v131
	v_fma_f32 v134, v24, v250, v134
	v_fma_f32 v135, v25, v251, v135
	v_mfma_f32_16x16x32_bf16 v[54:57], v[220:223], v[78:81], v[54:57]
	v_cvt_f32_ubyte0_e32 v248, v242
	v_cvt_f32_ubyte1_e32 v249, v242
	v_cvt_f32_ubyte2_e32 v250, v242
	v_cvt_f32_ubyte3_e32 v251, v242
	v_mul_f32_e32 v248, s34, v248
	v_mul_f32_e32 v249, s34, v249
	v_mul_f32_e32 v250, s34, v250
	v_mul_f32_e32 v251, s34, v251
	v_fma_f32 v124, v18, v248, v124
	v_fma_f32 v125, v19, v249, v125
	v_fma_f32 v126, v20, v250, v126
	v_fma_f32 v127, v21, v251, v127
	v_mfma_f32_16x16x32_bf16 v[50:53], v[224:227], v[78:81], v[50:53]
	v_cvt_f32_ubyte0_e32 v248, v243
	v_cvt_f32_ubyte1_e32 v249, v243
	v_cvt_f32_ubyte2_e32 v250, v243
	v_cvt_f32_ubyte3_e32 v251, v243
	v_mul_f32_e32 v248, s34, v248
	v_mul_f32_e32 v249, s34, v249
	v_mul_f32_e32 v250, s34, v250
	v_mul_f32_e32 v251, s34, v251
	v_fma_f32 v120, v62, v248, v120
	v_fma_f32 v121, v63, v249, v121
	v_fma_f32 v122, v64, v250, v122
	v_fma_f32 v123, v65, v251, v123
	v_mfma_f32_16x16x32_bf16 v[2:5], v[228:231], v[78:81], v[2:5]
	v_cvt_f32_ubyte0_e32 v248, v244
	v_cvt_f32_ubyte1_e32 v249, v244
	v_cvt_f32_ubyte2_e32 v250, v244
	v_cvt_f32_ubyte3_e32 v251, v244
	v_mul_f32_e32 v248, s34, v248
	v_mul_f32_e32 v249, s34, v249
	v_mul_f32_e32 v250, s34, v250
	v_mul_f32_e32 v251, s34, v251
	v_fma_f32 v114, v58, v248, v114
	v_fma_f32 v115, v59, v249, v115
	v_fma_f32 v116, v60, v250, v116
	v_fma_f32 v117, v61, v251, v117
	ds_read_b128 v[78:81], v207 offset:6144
	s_nop 7
	s_nop 3
	v_cvt_f32_ubyte0_e32 v248, v245
	v_cvt_f32_ubyte1_e32 v249, v245
	v_cvt_f32_ubyte2_e32 v250, v245
	v_cvt_f32_ubyte3_e32 v251, v245
	v_mul_f32_e32 v248, s34, v248
	v_mul_f32_e32 v249, s34, v249
	v_mul_f32_e32 v250, s34, v250
	v_mul_f32_e32 v251, s34, v251
	v_fma_f32 v106, v54, v248, v106
	v_fma_f32 v107, v55, v249, v107
	v_fma_f32 v108, v56, v250, v108
	v_fma_f32 v109, v57, v251, v109
	v_cvt_f32_ubyte0_e32 v248, v246
	v_cvt_f32_ubyte1_e32 v249, v246
	v_cvt_f32_ubyte2_e32 v250, v246
	v_cvt_f32_ubyte3_e32 v251, v246
	v_mul_f32_e32 v248, s34, v248
	v_mul_f32_e32 v249, s34, v249
	v_mul_f32_e32 v250, s34, v250
	v_mul_f32_e32 v251, s34, v251
	v_fma_f32 v100, v50, v248, v100
	v_fma_f32 v101, v51, v249, v101
	v_fma_f32 v102, v52, v250, v102
	v_fma_f32 v103, v53, v251, v103
	v_cvt_f32_ubyte0_e32 v248, v247
	v_cvt_f32_ubyte1_e32 v249, v247
	v_cvt_f32_ubyte2_e32 v250, v247
	v_cvt_f32_ubyte3_e32 v251, v247
	v_mul_f32_e32 v248, s34, v248
	v_mul_f32_e32 v249, s34, v249
	v_mul_f32_e32 v250, s34, v250
	v_mul_f32_e32 v251, s34, v251
	v_fma_f32 v96, v2, v248, v96
	v_fma_f32 v97, v3, v249, v97
	v_fma_f32 v98, v4, v250, v98
	v_fma_f32 v99, v5, v251, v99
	s_cmp_eq_u32 s43, 0
	s_cselect_b32 s32, 0x7c00000, 0
	s_add_u32 s98, s86, s32
	s_addc_u32 s99, s87, 0
	s_add_u32 s98, s98, 0xc00
	s_addc_u32 s99, s99, 0
	global_load_dword v92, v93, s[98:99]
	ds_read_b128 v[216:219], v91 offset:0
	ds_read_b128 v[220:223], v91 offset:2048
	ds_read_b128 v[224:227], v91 offset:4096
	ds_read_b128 v[228:231], v91 offset:6144
	s_waitcnt lgkmcnt(7)
	v_mfma_f32_16x16x32_bf16 v[6:9], v[82:85], v[66:69], 0
	v_mfma_f32_16x16x32_bf16 v[30:33], v[86:89], v[66:69], 0
	v_mfma_f32_16x16x32_bf16 v[38:41], v[208:211], v[66:69], 0
	v_mfma_f32_16x16x32_bf16 v[42:45], v[212:215], v[66:69], 0
	ds_read_b128 v[66:69], v119 offset:0
	s_waitcnt lgkmcnt(7)
	v_mfma_f32_16x16x32_bf16 v[46:49], v[82:85], v[70:73], 0
	v_mfma_f32_16x16x32_bf16 v[26:29], v[86:89], v[70:73], 0
	v_mfma_f32_16x16x32_bf16 v[14:17], v[208:211], v[70:73], 0
	v_mfma_f32_16x16x32_bf16 v[10:13], v[212:215], v[70:73], 0
	ds_read_b128 v[70:73], v119 offset:2048
	s_waitcnt lgkmcnt(7)
	v_mfma_f32_16x16x32_bf16 v[34:37], v[82:85], v[74:77], 0
	v_mfma_f32_16x16x32_bf16 v[22:25], v[86:89], v[74:77], 0
	v_mfma_f32_16x16x32_bf16 v[18:21], v[208:211], v[74:77], 0
	v_mfma_f32_16x16x32_bf16 v[62:65], v[212:215], v[74:77], 0
	ds_read_b128 v[74:77], v119 offset:4096
	s_waitcnt lgkmcnt(7)
	v_mfma_f32_16x16x32_bf16 v[58:61], v[82:85], v[78:81], 0
	v_mfma_f32_16x16x32_bf16 v[54:57], v[86:89], v[78:81], 0
	v_mfma_f32_16x16x32_bf16 v[50:53], v[208:211], v[78:81], 0
	v_mfma_f32_16x16x32_bf16 v[2:5], v[212:215], v[78:81], 0
	ds_read_b128 v[78:81], v119 offset:6144
	s_waitcnt lgkmcnt(3)
	v_mfma_f32_16x16x32_bf16 v[6:9], v[216:219], v[66:69], v[6:9]
	v_mfma_f32_16x16x32_bf16 v[30:33], v[220:223], v[66:69], v[30:33]
	v_mfma_f32_16x16x32_bf16 v[38:41], v[224:227], v[66:69], v[38:41]
	v_mfma_f32_16x16x32_bf16 v[42:45], v[228:231], v[66:69], v[42:45]
	s_waitcnt lgkmcnt(2)
	v_mfma_f32_16x16x32_bf16 v[46:49], v[216:219], v[70:73], v[46:49]
	v_mfma_f32_16x16x32_bf16 v[26:29], v[220:223], v[70:73], v[26:29]
	v_mfma_f32_16x16x32_bf16 v[14:17], v[224:227], v[70:73], v[14:17]
	v_mfma_f32_16x16x32_bf16 v[10:13], v[228:231], v[70:73], v[10:13]
	s_waitcnt vmcnt(7)
	s_waitcnt lgkmcnt(0)
	s_barrier
	s_add_i32 m0, s67, 0x0
	s_nop 0
	global_load_lds_dwordx4 v188, s[80:81]
	s_add_i32 m0, s67, 0x2000
	s_nop 0
	global_load_lds_dwordx4 v189, s[80:81]
	s_add_i32 m0, s67, 0x4000
	s_nop 0
	global_load_lds_dwordx4 v190, s[80:81]
	s_add_i32 m0, s67, 0x6000
	s_nop 0
	global_load_lds_dwordx4 v191, s[80:81]
	s_add_i32 m0, s67, 0x18000
	s_nop 0
	global_load_lds_dwordx4 v205, s[96:97]
	s_add_i32 m0, s67, 0x1a000
	s_nop 0
	global_load_lds_dwordx4 v206, s[96:97]
	s_add_u32 s80, s80, 0x80
	s_addc_u32 s81, s81, 0
	s_add_u32 s96, s96, 0x80
	s_addc_u32 s97, s97, 0
	ds_read_b128 v[82:85], v90 offset:16384
	ds_read_b128 v[86:89], v90 offset:18432
	ds_read_b128 v[208:211], v90 offset:20480
	ds_read_b128 v[212:215], v90 offset:22528
	ds_read_b128 v[66:69], v207 offset:32768
	ds_read_b128 v[70:73], v207 offset:34816
	v_mfma_f32_16x16x32_bf16 v[34:37], v[216:219], v[74:77], v[34:37]
	v_mfma_f32_16x16x32_bf16 v[22:25], v[220:223], v[74:77], v[22:25]
	v_mfma_f32_16x16x32_bf16 v[18:21], v[224:227], v[74:77], v[18:21]
	v_mfma_f32_16x16x32_bf16 v[62:65], v[228:231], v[74:77], v[62:65]
	ds_read_b128 v[74:77], v207 offset:36864
	v_mfma_f32_16x16x32_bf16 v[58:61], v[216:219], v[78:81], v[58:61]
	v_mfma_f32_16x16x32_bf16 v[54:57], v[220:223], v[78:81], v[54:57]
	v_mfma_f32_16x16x32_bf16 v[50:53], v[224:227], v[78:81], v[50:53]
	v_mfma_f32_16x16x32_bf16 v[2:5], v[228:231], v[78:81], v[2:5]
	ds_read_b128 v[78:81], v207 offset:38912
	ds_read_b128 v[216:219], v91 offset:16384
	ds_read_b128 v[220:223], v91 offset:18432
	ds_read_b128 v[224:227], v91 offset:20480
	ds_read_b128 v[228:231], v91 offset:22528
	s_waitcnt lgkmcnt(7)
	v_mfma_f32_16x16x32_bf16 v[6:9], v[82:85], v[66:69], v[6:9]
	v_mfma_f32_16x16x32_bf16 v[30:33], v[86:89], v[66:69], v[30:33]
	v_mfma_f32_16x16x32_bf16 v[38:41], v[208:211], v[66:69], v[38:41]
	v_mfma_f32_16x16x32_bf16 v[42:45], v[212:215], v[66:69], v[42:45]
	ds_read_b128 v[66:69], v119 offset:32768
	s_waitcnt lgkmcnt(7)
	v_mfma_f32_16x16x32_bf16 v[46:49], v[82:85], v[70:73], v[46:49]
	v_mfma_f32_16x16x32_bf16 v[26:29], v[86:89], v[70:73], v[26:29]
	v_mfma_f32_16x16x32_bf16 v[14:17], v[208:211], v[70:73], v[14:17]
	v_mfma_f32_16x16x32_bf16 v[10:13], v[212:215], v[70:73], v[10:13]
	ds_read_b128 v[70:73], v119 offset:34816
	s_waitcnt lgkmcnt(7)
	v_mfma_f32_16x16x32_bf16 v[34:37], v[82:85], v[74:77], v[34:37]
	v_mfma_f32_16x16x32_bf16 v[22:25], v[86:89], v[74:77], v[22:25]
	v_mfma_f32_16x16x32_bf16 v[18:21], v[208:211], v[74:77], v[18:21]
	v_mfma_f32_16x16x32_bf16 v[62:65], v[212:215], v[74:77], v[62:65]
	ds_read_b128 v[74:77], v119 offset:36864
	s_waitcnt lgkmcnt(7)
	v_mfma_f32_16x16x32_bf16 v[58:61], v[82:85], v[78:81], v[58:61]
	v_mfma_f32_16x16x32_bf16 v[54:57], v[86:89], v[78:81], v[54:57]
	v_mfma_f32_16x16x32_bf16 v[50:53], v[208:211], v[78:81], v[50:53]
	v_mfma_f32_16x16x32_bf16 v[2:5], v[212:215], v[78:81], v[2:5]
	ds_read_b128 v[78:81], v119 offset:38912
	s_waitcnt lgkmcnt(3)
	v_mfma_f32_16x16x32_bf16 v[6:9], v[216:219], v[66:69], v[6:9]
	v_mfma_f32_16x16x32_bf16 v[30:33], v[220:223], v[66:69], v[30:33]
	v_mfma_f32_16x16x32_bf16 v[38:41], v[224:227], v[66:69], v[38:41]
	v_mfma_f32_16x16x32_bf16 v[42:45], v[228:231], v[66:69], v[42:45]
	s_waitcnt lgkmcnt(2)
	v_mfma_f32_16x16x32_bf16 v[46:49], v[216:219], v[70:73], v[46:49]
	v_mfma_f32_16x16x32_bf16 v[26:29], v[220:223], v[70:73], v[26:29]
	v_mfma_f32_16x16x32_bf16 v[14:17], v[224:227], v[70:73], v[14:17]
	v_mfma_f32_16x16x32_bf16 v[10:13], v[228:231], v[70:73], v[10:13]
	s_waitcnt vmcnt(7)
	s_waitcnt lgkmcnt(0)
	s_barrier
	s_add_i32 m0, s67, 0x8000
	s_nop 0
	global_load_lds_dwordx4 v188, s[80:81]
	s_add_i32 m0, s67, 0xa000
	s_nop 0
	global_load_lds_dwordx4 v189, s[80:81]
	s_add_i32 m0, s67, 0xc000
	s_nop 0
	global_load_lds_dwordx4 v190, s[80:81]
	s_add_i32 m0, s67, 0xe000
	s_nop 0
	global_load_lds_dwordx4 v191, s[80:81]
	s_add_i32 m0, s67, 0x1c000
	s_nop 0
	global_load_lds_dwordx4 v205, s[96:97]
	s_add_i32 m0, s67, 0x1e000
	s_nop 0
	global_load_lds_dwordx4 v206, s[96:97]
	s_add_u32 s80, s80, 0x80
	s_addc_u32 s81, s81, 0
	s_add_u32 s96, s96, 0x80
	s_addc_u32 s97, s97, 0
	ds_read_b128 v[82:85], v90 offset:33792
	ds_read_b128 v[86:89], v90 offset:35840
	ds_read_b128 v[208:211], v90 offset:37888
	ds_read_b128 v[212:215], v90 offset:39936
	ds_read_b128 v[66:69], v0 offset:0
	ds_read_b128 v[70:73], v0 offset:2048
	v_mfma_f32_16x16x32_bf16 v[34:37], v[216:219], v[74:77], v[34:37]
	v_mfma_f32_16x16x32_bf16 v[22:25], v[220:223], v[74:77], v[22:25]
	v_mfma_f32_16x16x32_bf16 v[18:21], v[224:227], v[74:77], v[18:21]
	v_mfma_f32_16x16x32_bf16 v[62:65], v[228:231], v[74:77], v[62:65]
	ds_read_b128 v[74:77], v0 offset:4096
	v_mfma_f32_16x16x32_bf16 v[58:61], v[216:219], v[78:81], v[58:61]
	v_mfma_f32_16x16x32_bf16 v[54:57], v[220:223], v[78:81], v[54:57]
	v_mfma_f32_16x16x32_bf16 v[50:53], v[224:227], v[78:81], v[50:53]
	v_mfma_f32_16x16x32_bf16 v[2:5], v[228:231], v[78:81], v[2:5]
	ds_read_b128 v[78:81], v0 offset:6144
	ds_read_b128 v[216:219], v91 offset:33792
	ds_read_b128 v[220:223], v91 offset:35840
	ds_read_b128 v[224:227], v91 offset:37888
	ds_read_b128 v[228:231], v91 offset:39936
	s_waitcnt lgkmcnt(7)
	v_mfma_f32_16x16x32_bf16 v[6:9], v[82:85], v[66:69], v[6:9]
	v_mfma_f32_16x16x32_bf16 v[30:33], v[86:89], v[66:69], v[30:33]
	v_mfma_f32_16x16x32_bf16 v[38:41], v[208:211], v[66:69], v[38:41]
	v_mfma_f32_16x16x32_bf16 v[42:45], v[212:215], v[66:69], v[42:45]
	ds_read_b128 v[66:69], v255 offset:0
	s_waitcnt lgkmcnt(7)
	v_mfma_f32_16x16x32_bf16 v[46:49], v[82:85], v[70:73], v[46:49]
	v_mfma_f32_16x16x32_bf16 v[26:29], v[86:89], v[70:73], v[26:29]
	v_mfma_f32_16x16x32_bf16 v[14:17], v[208:211], v[70:73], v[14:17]
	v_mfma_f32_16x16x32_bf16 v[10:13], v[212:215], v[70:73], v[10:13]
	ds_read_b128 v[70:73], v255 offset:2048
	s_waitcnt lgkmcnt(7)
	v_mfma_f32_16x16x32_bf16 v[34:37], v[82:85], v[74:77], v[34:37]
	v_mfma_f32_16x16x32_bf16 v[22:25], v[86:89], v[74:77], v[22:25]
	v_mfma_f32_16x16x32_bf16 v[18:21], v[208:211], v[74:77], v[18:21]
	v_mfma_f32_16x16x32_bf16 v[62:65], v[212:215], v[74:77], v[62:65]
	ds_read_b128 v[74:77], v255 offset:4096
	s_waitcnt lgkmcnt(7)
	v_mfma_f32_16x16x32_bf16 v[58:61], v[82:85], v[78:81], v[58:61]
	v_mfma_f32_16x16x32_bf16 v[54:57], v[86:89], v[78:81], v[54:57]
	v_mfma_f32_16x16x32_bf16 v[50:53], v[208:211], v[78:81], v[50:53]
	v_mfma_f32_16x16x32_bf16 v[2:5], v[212:215], v[78:81], v[2:5]
	ds_read_b128 v[78:81], v255 offset:6144
	s_waitcnt lgkmcnt(3)
	v_mfma_f32_16x16x32_bf16 v[6:9], v[216:219], v[66:69], v[6:9]
	v_mfma_f32_16x16x32_bf16 v[30:33], v[220:223], v[66:69], v[30:33]
	v_mfma_f32_16x16x32_bf16 v[38:41], v[224:227], v[66:69], v[38:41]
	v_mfma_f32_16x16x32_bf16 v[42:45], v[228:231], v[66:69], v[42:45]
	s_waitcnt lgkmcnt(2)
	v_mfma_f32_16x16x32_bf16 v[46:49], v[216:219], v[70:73], v[46:49]
	v_mfma_f32_16x16x32_bf16 v[26:29], v[220:223], v[70:73], v[26:29]
	v_mfma_f32_16x16x32_bf16 v[14:17], v[224:227], v[70:73], v[14:17]
	v_mfma_f32_16x16x32_bf16 v[10:13], v[228:231], v[70:73], v[10:13]
	s_waitcnt vmcnt(6)
	s_waitcnt lgkmcnt(0)
	s_barrier
	s_add_i32 m0, s67, 0x10000
	s_nop 0
	global_load_lds_dwordx4 v188, s[80:81]
	s_add_i32 m0, s67, 0x12000
	s_nop 0
	global_load_lds_dwordx4 v189, s[80:81]
	s_add_i32 m0, s67, 0x14000
	s_nop 0
	global_load_lds_dwordx4 v190, s[80:81]
	s_add_i32 m0, s67, 0x16000
	s_nop 0
	global_load_lds_dwordx4 v191, s[80:81]
	s_add_i32 m0, s67, 0x20400
	s_nop 0
	global_load_lds_dwordx4 v205, s[96:97]
	s_add_i32 m0, s67, 0x22400
	s_nop 0
	global_load_lds_dwordx4 v206, s[96:97]
	s_add_u32 s80, s80, 0x80
	s_addc_u32 s81, s81, 0
	s_add_u32 s96, s96, 0x80
	s_addc_u32 s97, s97, 0
	ds_read_b128 v[82:85], v90 offset:0
	ds_read_b128 v[86:89], v90 offset:2048
	ds_read_b128 v[208:211], v90 offset:4096
	ds_read_b128 v[212:215], v90 offset:6144
	ds_read_b128 v[66:69], v207 offset:0
	ds_read_b128 v[70:73], v207 offset:2048
	v_mfma_f32_16x16x32_bf16 v[34:37], v[216:219], v[74:77], v[34:37]
	v_mfma_f32_16x16x32_bf16 v[22:25], v[220:223], v[74:77], v[22:25]
	v_mfma_f32_16x16x32_bf16 v[18:21], v[224:227], v[74:77], v[18:21]
	v_mfma_f32_16x16x32_bf16 v[62:65], v[228:231], v[74:77], v[62:65]
	ds_read_b128 v[74:77], v207 offset:4096
	v_mfma_f32_16x16x32_bf16 v[58:61], v[216:219], v[78:81], v[58:61]
	v_mfma_f32_16x16x32_bf16 v[54:57], v[220:223], v[78:81], v[54:57]
	v_mfma_f32_16x16x32_bf16 v[50:53], v[224:227], v[78:81], v[50:53]
	v_mfma_f32_16x16x32_bf16 v[2:5], v[228:231], v[78:81], v[2:5]
	ds_read_b128 v[78:81], v207 offset:6144
	ds_read_b128 v[216:219], v91 offset:0
	ds_read_b128 v[220:223], v91 offset:2048
	ds_read_b128 v[224:227], v91 offset:4096
	ds_read_b128 v[228:231], v91 offset:6144
	s_waitcnt lgkmcnt(7)
	v_mfma_f32_16x16x32_bf16 v[6:9], v[82:85], v[66:69], v[6:9]
	v_mfma_f32_16x16x32_bf16 v[30:33], v[86:89], v[66:69], v[30:33]
	v_mfma_f32_16x16x32_bf16 v[38:41], v[208:211], v[66:69], v[38:41]
	v_mfma_f32_16x16x32_bf16 v[42:45], v[212:215], v[66:69], v[42:45]
	ds_read_b128 v[66:69], v119 offset:0
	s_waitcnt lgkmcnt(7)
	v_mfma_f32_16x16x32_bf16 v[46:49], v[82:85], v[70:73], v[46:49]
	v_mfma_f32_16x16x32_bf16 v[26:29], v[86:89], v[70:73], v[26:29]
	v_mfma_f32_16x16x32_bf16 v[14:17], v[208:211], v[70:73], v[14:17]
	v_mfma_f32_16x16x32_bf16 v[10:13], v[212:215], v[70:73], v[10:13]
	ds_read_b128 v[70:73], v119 offset:2048
	s_waitcnt lgkmcnt(7)
	v_mfma_f32_16x16x32_bf16 v[34:37], v[82:85], v[74:77], v[34:37]
	v_mfma_f32_16x16x32_bf16 v[22:25], v[86:89], v[74:77], v[22:25]
	v_mfma_f32_16x16x32_bf16 v[18:21], v[208:211], v[74:77], v[18:21]
	v_mfma_f32_16x16x32_bf16 v[62:65], v[212:215], v[74:77], v[62:65]
	ds_read_b128 v[74:77], v119 offset:4096
	s_waitcnt lgkmcnt(7)
	v_mfma_f32_16x16x32_bf16 v[58:61], v[82:85], v[78:81], v[58:61]
	v_mfma_f32_16x16x32_bf16 v[54:57], v[86:89], v[78:81], v[54:57]
	v_mfma_f32_16x16x32_bf16 v[50:53], v[208:211], v[78:81], v[50:53]
	v_mfma_f32_16x16x32_bf16 v[2:5], v[212:215], v[78:81], v[2:5]
	ds_read_b128 v[78:81], v119 offset:6144
	s_waitcnt lgkmcnt(3)
	v_mfma_f32_16x16x32_bf16 v[6:9], v[216:219], v[66:69], v[6:9]
	v_mfma_f32_16x16x32_bf16 v[30:33], v[220:223], v[66:69], v[30:33]
	v_mfma_f32_16x16x32_bf16 v[38:41], v[224:227], v[66:69], v[38:41]
	v_mfma_f32_16x16x32_bf16 v[42:45], v[228:231], v[66:69], v[42:45]
	s_waitcnt lgkmcnt(2)
	v_mfma_f32_16x16x32_bf16 v[46:49], v[216:219], v[70:73], v[46:49]
	v_mfma_f32_16x16x32_bf16 v[26:29], v[220:223], v[70:73], v[26:29]
	v_mfma_f32_16x16x32_bf16 v[14:17], v[224:227], v[70:73], v[14:17]
	v_mfma_f32_16x16x32_bf16 v[10:13], v[228:231], v[70:73], v[10:13]
	s_waitcnt vmcnt(6)
	s_waitcnt lgkmcnt(0)
	s_barrier
	s_add_i32 m0, s67, 0x0
	s_nop 0
	global_load_lds_dwordx4 v188, s[80:81]
	s_add_i32 m0, s67, 0x2000
	s_nop 0
	global_load_lds_dwordx4 v189, s[80:81]
	s_add_i32 m0, s67, 0x4000
	s_nop 0
	global_load_lds_dwordx4 v190, s[80:81]
	s_add_i32 m0, s67, 0x6000
	s_nop 0
	global_load_lds_dwordx4 v191, s[80:81]
	s_add_i32 m0, s67, 0x18000
	s_nop 0
	global_load_lds_dwordx4 v205, s[96:97]
	s_add_i32 m0, s67, 0x1a000
	s_nop 0
	global_load_lds_dwordx4 v206, s[96:97]
	s_add_u32 s80, s80, 0x80
	s_addc_u32 s81, s81, 0
	s_add_u32 s96, s96, 0x80
	s_addc_u32 s97, s97, 0
	s_movk_i32 s10, 0xc00
	s_mov_b32 s11, 0
	v_lshl_add_u64 v[248:249], v[128:129], 0, s[10:11]
	global_load_dwordx2 v[232:233], v[248:249], off
	global_load_dwordx2 v[234:235], v[248:249], off offset:32
	v_lshl_add_u64 v[248:249], v[132:133], 0, s[10:11]
	global_load_dwordx2 v[236:237], v[248:249], off
	global_load_dwordx2 v[238:239], v[248:249], off offset:32
	v_lshl_add_u64 v[248:249], v[152:153], 0, s[10:11]
	global_load_dwordx2 v[240:241], v[248:249], off
	global_load_dwordx2 v[242:243], v[248:249], off offset:32
	v_lshl_add_u64 v[248:249], v[154:155], 0, s[10:11]
	global_load_dwordx2 v[244:245], v[248:249], off
	global_load_dwordx2 v[246:247], v[248:249], off offset:32
	ds_read_b128 v[82:85], v90 offset:16384
	ds_read_b128 v[86:89], v90 offset:18432
	ds_read_b128 v[208:211], v90 offset:20480
	ds_read_b128 v[212:215], v90 offset:22528
	ds_read_b128 v[66:69], v207 offset:32768
	ds_read_b128 v[70:73], v207 offset:34816
	v_mfma_f32_16x16x32_bf16 v[34:37], v[216:219], v[74:77], v[34:37]
	v_mfma_f32_16x16x32_bf16 v[22:25], v[220:223], v[74:77], v[22:25]
	v_mfma_f32_16x16x32_bf16 v[18:21], v[224:227], v[74:77], v[18:21]
	v_mfma_f32_16x16x32_bf16 v[62:65], v[228:231], v[74:77], v[62:65]
	ds_read_b128 v[74:77], v207 offset:36864
	v_mfma_f32_16x16x32_bf16 v[58:61], v[216:219], v[78:81], v[58:61]
	v_mfma_f32_16x16x32_bf16 v[54:57], v[220:223], v[78:81], v[54:57]
	v_mfma_f32_16x16x32_bf16 v[50:53], v[224:227], v[78:81], v[50:53]
	v_mfma_f32_16x16x32_bf16 v[2:5], v[228:231], v[78:81], v[2:5]
	ds_read_b128 v[78:81], v207 offset:38912
	ds_read_b128 v[216:219], v91 offset:16384
	ds_read_b128 v[220:223], v91 offset:18432
	ds_read_b128 v[224:227], v91 offset:20480
	ds_read_b128 v[228:231], v91 offset:22528
	s_waitcnt lgkmcnt(7)
	v_mfma_f32_16x16x32_bf16 v[6:9], v[82:85], v[66:69], v[6:9]
	v_mfma_f32_16x16x32_bf16 v[30:33], v[86:89], v[66:69], v[30:33]
	v_mfma_f32_16x16x32_bf16 v[38:41], v[208:211], v[66:69], v[38:41]
	v_mfma_f32_16x16x32_bf16 v[42:45], v[212:215], v[66:69], v[42:45]
	ds_read_b128 v[66:69], v119 offset:32768
	s_waitcnt lgkmcnt(7)
	v_mfma_f32_16x16x32_bf16 v[46:49], v[82:85], v[70:73], v[46:49]
	v_mfma_f32_16x16x32_bf16 v[26:29], v[86:89], v[70:73], v[26:29]
	v_mfma_f32_16x16x32_bf16 v[14:17], v[208:211], v[70:73], v[14:17]
	v_mfma_f32_16x16x32_bf16 v[10:13], v[212:215], v[70:73], v[10:13]
	ds_read_b128 v[70:73], v119 offset:34816
	s_waitcnt lgkmcnt(7)
	v_mfma_f32_16x16x32_bf16 v[34:37], v[82:85], v[74:77], v[34:37]
	v_mfma_f32_16x16x32_bf16 v[22:25], v[86:89], v[74:77], v[22:25]
	v_mfma_f32_16x16x32_bf16 v[18:21], v[208:211], v[74:77], v[18:21]
	v_mfma_f32_16x16x32_bf16 v[62:65], v[212:215], v[74:77], v[62:65]
	ds_read_b128 v[74:77], v119 offset:36864
	s_waitcnt lgkmcnt(7)
	v_mfma_f32_16x16x32_bf16 v[58:61], v[82:85], v[78:81], v[58:61]
	v_mfma_f32_16x16x32_bf16 v[54:57], v[86:89], v[78:81], v[54:57]
	v_mfma_f32_16x16x32_bf16 v[50:53], v[208:211], v[78:81], v[50:53]
	v_mfma_f32_16x16x32_bf16 v[2:5], v[212:215], v[78:81], v[2:5]
	ds_read_b128 v[78:81], v119 offset:38912
	s_waitcnt lgkmcnt(3)
	v_mfma_f32_16x16x32_bf16 v[6:9], v[216:219], v[66:69], v[6:9]
	v_mfma_f32_16x16x32_bf16 v[30:33], v[220:223], v[66:69], v[30:33]
	v_mfma_f32_16x16x32_bf16 v[38:41], v[224:227], v[66:69], v[38:41]
	v_mfma_f32_16x16x32_bf16 v[42:45], v[228:231], v[66:69], v[42:45]
	s_waitcnt lgkmcnt(2)
	v_mfma_f32_16x16x32_bf16 v[46:49], v[216:219], v[70:73], v[46:49]
	v_mfma_f32_16x16x32_bf16 v[26:29], v[220:223], v[70:73], v[26:29]
	v_mfma_f32_16x16x32_bf16 v[14:17], v[224:227], v[70:73], v[14:17]
	v_mfma_f32_16x16x32_bf16 v[10:13], v[228:231], v[70:73], v[10:13]
	s_waitcnt vmcnt(14)
	s_waitcnt lgkmcnt(0)
	s_barrier
	s_add_i32 m0, s67, 0x8000
	s_nop 0
	global_load_lds_dwordx4 v188, s[80:81]
	s_add_i32 m0, s67, 0xa000
	s_nop 0
	global_load_lds_dwordx4 v189, s[80:81]
	s_add_i32 m0, s67, 0xc000
	s_nop 0
	global_load_lds_dwordx4 v190, s[80:81]
	s_add_i32 m0, s67, 0xe000
	s_nop 0
	global_load_lds_dwordx4 v191, s[80:81]
	s_add_i32 m0, s67, 0x1c000
	s_nop 0
	global_load_lds_dwordx4 v205, s[96:97]
	s_add_i32 m0, s67, 0x1e000
	s_nop 0
	global_load_lds_dwordx4 v206, s[96:97]
	ds_read_b128 v[82:85], v90 offset:33792
	ds_read_b128 v[86:89], v90 offset:35840
	ds_read_b128 v[208:211], v90 offset:37888
	ds_read_b128 v[212:215], v90 offset:39936
	ds_read_b128 v[66:69], v0 offset:0
	ds_read_b128 v[70:73], v0 offset:2048
	v_mfma_f32_16x16x32_bf16 v[34:37], v[216:219], v[74:77], v[34:37]
	v_mfma_f32_16x16x32_bf16 v[22:25], v[220:223], v[74:77], v[22:25]
	v_mfma_f32_16x16x32_bf16 v[18:21], v[224:227], v[74:77], v[18:21]
	v_mfma_f32_16x16x32_bf16 v[62:65], v[228:231], v[74:77], v[62:65]
	ds_read_b128 v[74:77], v0 offset:4096
	v_mfma_f32_16x16x32_bf16 v[58:61], v[216:219], v[78:81], v[58:61]
	v_mfma_f32_16x16x32_bf16 v[54:57], v[220:223], v[78:81], v[54:57]
	v_mfma_f32_16x16x32_bf16 v[50:53], v[224:227], v[78:81], v[50:53]
	v_mfma_f32_16x16x32_bf16 v[2:5], v[228:231], v[78:81], v[2:5]
	ds_read_b128 v[78:81], v0 offset:6144
	ds_read_b128 v[216:219], v91 offset:33792
	ds_read_b128 v[220:223], v91 offset:35840
	ds_read_b128 v[224:227], v91 offset:37888
	ds_read_b128 v[228:231], v91 offset:39936
	s_waitcnt lgkmcnt(7)
	v_mfma_f32_16x16x32_bf16 v[6:9], v[82:85], v[66:69], v[6:9]
	v_mfma_f32_16x16x32_bf16 v[30:33], v[86:89], v[66:69], v[30:33]
	v_mfma_f32_16x16x32_bf16 v[38:41], v[208:211], v[66:69], v[38:41]
	v_mfma_f32_16x16x32_bf16 v[42:45], v[212:215], v[66:69], v[42:45]
	ds_read_b128 v[66:69], v255 offset:0
	s_waitcnt lgkmcnt(7)
	v_mfma_f32_16x16x32_bf16 v[46:49], v[82:85], v[70:73], v[46:49]
	v_mfma_f32_16x16x32_bf16 v[26:29], v[86:89], v[70:73], v[26:29]
	v_mfma_f32_16x16x32_bf16 v[14:17], v[208:211], v[70:73], v[14:17]
	v_mfma_f32_16x16x32_bf16 v[10:13], v[212:215], v[70:73], v[10:13]
	ds_read_b128 v[70:73], v255 offset:2048
	s_waitcnt lgkmcnt(7)
	v_mfma_f32_16x16x32_bf16 v[34:37], v[82:85], v[74:77], v[34:37]
	v_mfma_f32_16x16x32_bf16 v[22:25], v[86:89], v[74:77], v[22:25]
	v_mfma_f32_16x16x32_bf16 v[18:21], v[208:211], v[74:77], v[18:21]
	v_mfma_f32_16x16x32_bf16 v[62:65], v[212:215], v[74:77], v[62:65]
	ds_read_b128 v[74:77], v255 offset:4096
	s_waitcnt lgkmcnt(7)
	v_mfma_f32_16x16x32_bf16 v[58:61], v[82:85], v[78:81], v[58:61]
	v_mfma_f32_16x16x32_bf16 v[54:57], v[86:89], v[78:81], v[54:57]
	v_mfma_f32_16x16x32_bf16 v[50:53], v[208:211], v[78:81], v[50:53]
	v_mfma_f32_16x16x32_bf16 v[2:5], v[212:215], v[78:81], v[2:5]
	ds_read_b128 v[78:81], v255 offset:6144
	s_waitcnt lgkmcnt(3)
	v_mfma_f32_16x16x32_bf16 v[6:9], v[216:219], v[66:69], v[6:9]
	v_mfma_f32_16x16x32_bf16 v[30:33], v[220:223], v[66:69], v[30:33]
	v_mfma_f32_16x16x32_bf16 v[38:41], v[224:227], v[66:69], v[38:41]
	v_mfma_f32_16x16x32_bf16 v[42:45], v[228:231], v[66:69], v[42:45]
	s_waitcnt lgkmcnt(2)
	v_mfma_f32_16x16x32_bf16 v[46:49], v[216:219], v[70:73], v[46:49]
	v_mfma_f32_16x16x32_bf16 v[26:29], v[220:223], v[70:73], v[26:29]
	v_mfma_f32_16x16x32_bf16 v[14:17], v[224:227], v[70:73], v[14:17]
	v_mfma_f32_16x16x32_bf16 v[10:13], v[228:231], v[70:73], v[10:13]
	s_waitcnt vmcnt(14)
	s_waitcnt lgkmcnt(0)
	s_barrier
	ds_read_b128 v[82:85], v90 offset:0
	ds_read_b128 v[86:89], v90 offset:2048
	ds_read_b128 v[208:211], v90 offset:4096
	ds_read_b128 v[212:215], v90 offset:6144
	ds_read_b128 v[66:69], v207 offset:0
	ds_read_b128 v[70:73], v207 offset:2048
	v_mfma_f32_16x16x32_bf16 v[34:37], v[216:219], v[74:77], v[34:37]
	v_mfma_f32_16x16x32_bf16 v[22:25], v[220:223], v[74:77], v[22:25]
	v_mfma_f32_16x16x32_bf16 v[18:21], v[224:227], v[74:77], v[18:21]
	v_mfma_f32_16x16x32_bf16 v[62:65], v[228:231], v[74:77], v[62:65]
	ds_read_b128 v[74:77], v207 offset:4096
	v_mfma_f32_16x16x32_bf16 v[58:61], v[216:219], v[78:81], v[58:61]
	v_mfma_f32_16x16x32_bf16 v[54:57], v[220:223], v[78:81], v[54:57]
	v_mfma_f32_16x16x32_bf16 v[50:53], v[224:227], v[78:81], v[50:53]
	v_mfma_f32_16x16x32_bf16 v[2:5], v[228:231], v[78:81], v[2:5]
	ds_read_b128 v[78:81], v207 offset:6144
	ds_read_b128 v[216:219], v91 offset:0
	ds_read_b128 v[220:223], v91 offset:2048
	ds_read_b128 v[224:227], v91 offset:4096
	ds_read_b128 v[228:231], v91 offset:6144
	s_waitcnt lgkmcnt(7)
	v_mfma_f32_16x16x32_bf16 v[6:9], v[82:85], v[66:69], v[6:9]
	v_mfma_f32_16x16x32_bf16 v[30:33], v[86:89], v[66:69], v[30:33]
	v_mfma_f32_16x16x32_bf16 v[38:41], v[208:211], v[66:69], v[38:41]
	v_mfma_f32_16x16x32_bf16 v[42:45], v[212:215], v[66:69], v[42:45]
	ds_read_b128 v[66:69], v119 offset:0
	s_waitcnt lgkmcnt(7)
	v_mfma_f32_16x16x32_bf16 v[46:49], v[82:85], v[70:73], v[46:49]
	v_mfma_f32_16x16x32_bf16 v[26:29], v[86:89], v[70:73], v[26:29]
	v_mfma_f32_16x16x32_bf16 v[14:17], v[208:211], v[70:73], v[14:17]
	v_mfma_f32_16x16x32_bf16 v[10:13], v[212:215], v[70:73], v[10:13]
	ds_read_b128 v[70:73], v119 offset:2048
	s_waitcnt lgkmcnt(7)
	v_mfma_f32_16x16x32_bf16 v[34:37], v[82:85], v[74:77], v[34:37]
	v_mfma_f32_16x16x32_bf16 v[22:25], v[86:89], v[74:77], v[22:25]
	v_mfma_f32_16x16x32_bf16 v[18:21], v[208:211], v[74:77], v[18:21]
	v_mfma_f32_16x16x32_bf16 v[62:65], v[212:215], v[74:77], v[62:65]
	ds_read_b128 v[74:77], v119 offset:4096
	s_waitcnt lgkmcnt(7)
	v_mfma_f32_16x16x32_bf16 v[58:61], v[82:85], v[78:81], v[58:61]
	v_mfma_f32_16x16x32_bf16 v[54:57], v[86:89], v[78:81], v[54:57]
	v_mfma_f32_16x16x32_bf16 v[50:53], v[208:211], v[78:81], v[50:53]
	v_mfma_f32_16x16x32_bf16 v[2:5], v[212:215], v[78:81], v[2:5]
	ds_read_b128 v[78:81], v119 offset:6144
	s_waitcnt lgkmcnt(3)
	v_mfma_f32_16x16x32_bf16 v[6:9], v[216:219], v[66:69], v[6:9]
	v_mfma_f32_16x16x32_bf16 v[30:33], v[220:223], v[66:69], v[30:33]
	v_mfma_f32_16x16x32_bf16 v[38:41], v[224:227], v[66:69], v[38:41]
	v_mfma_f32_16x16x32_bf16 v[42:45], v[228:231], v[66:69], v[42:45]
	s_waitcnt lgkmcnt(2)
	v_mfma_f32_16x16x32_bf16 v[46:49], v[216:219], v[70:73], v[46:49]
	v_mfma_f32_16x16x32_bf16 v[26:29], v[220:223], v[70:73], v[26:29]
	v_mfma_f32_16x16x32_bf16 v[14:17], v[224:227], v[70:73], v[14:17]
	v_mfma_f32_16x16x32_bf16 v[10:13], v[228:231], v[70:73], v[10:13]
	s_waitcnt vmcnt(0)
	s_waitcnt lgkmcnt(0)
	s_barrier
	ds_read_b128 v[82:85], v90 offset:16384
	ds_read_b128 v[86:89], v90 offset:18432
	ds_read_b128 v[208:211], v90 offset:20480
	ds_read_b128 v[212:215], v90 offset:22528
	ds_read_b128 v[66:69], v207 offset:32768
	ds_read_b128 v[70:73], v207 offset:34816
	v_mfma_f32_16x16x32_bf16 v[34:37], v[216:219], v[74:77], v[34:37]
	v_mfma_f32_16x16x32_bf16 v[22:25], v[220:223], v[74:77], v[22:25]
	v_mfma_f32_16x16x32_bf16 v[18:21], v[224:227], v[74:77], v[18:21]
	v_mfma_f32_16x16x32_bf16 v[62:65], v[228:231], v[74:77], v[62:65]
	ds_read_b128 v[74:77], v207 offset:36864
	v_mfma_f32_16x16x32_bf16 v[58:61], v[216:219], v[78:81], v[58:61]
	v_mfma_f32_16x16x32_bf16 v[54:57], v[220:223], v[78:81], v[54:57]
	v_mfma_f32_16x16x32_bf16 v[50:53], v[224:227], v[78:81], v[50:53]
	v_mfma_f32_16x16x32_bf16 v[2:5], v[228:231], v[78:81], v[2:5]
	ds_read_b128 v[78:81], v207 offset:38912
	ds_read_b128 v[216:219], v91 offset:16384
	ds_read_b128 v[220:223], v91 offset:18432
	ds_read_b128 v[224:227], v91 offset:20480
	ds_read_b128 v[228:231], v91 offset:22528
	s_waitcnt lgkmcnt(7)
	v_mfma_f32_16x16x32_bf16 v[6:9], v[82:85], v[66:69], v[6:9]
	v_mfma_f32_16x16x32_bf16 v[30:33], v[86:89], v[66:69], v[30:33]
	v_mfma_f32_16x16x32_bf16 v[38:41], v[208:211], v[66:69], v[38:41]
	v_mfma_f32_16x16x32_bf16 v[42:45], v[212:215], v[66:69], v[42:45]
	ds_read_b128 v[66:69], v119 offset:32768
	s_waitcnt lgkmcnt(7)
	v_mfma_f32_16x16x32_bf16 v[46:49], v[82:85], v[70:73], v[46:49]
	v_mfma_f32_16x16x32_bf16 v[26:29], v[86:89], v[70:73], v[26:29]
	v_mfma_f32_16x16x32_bf16 v[14:17], v[208:211], v[70:73], v[14:17]
	v_mfma_f32_16x16x32_bf16 v[10:13], v[212:215], v[70:73], v[10:13]
	ds_read_b128 v[70:73], v119 offset:34816
	s_waitcnt lgkmcnt(7)
	v_mfma_f32_16x16x32_bf16 v[34:37], v[82:85], v[74:77], v[34:37]
	v_mfma_f32_16x16x32_bf16 v[22:25], v[86:89], v[74:77], v[22:25]
	v_mfma_f32_16x16x32_bf16 v[18:21], v[208:211], v[74:77], v[18:21]
	v_mfma_f32_16x16x32_bf16 v[62:65], v[212:215], v[74:77], v[62:65]
	ds_read_b128 v[74:77], v119 offset:36864
	s_waitcnt lgkmcnt(7)
	v_mfma_f32_16x16x32_bf16 v[58:61], v[82:85], v[78:81], v[58:61]
	v_mfma_f32_16x16x32_bf16 v[54:57], v[86:89], v[78:81], v[54:57]
	v_mfma_f32_16x16x32_bf16 v[50:53], v[208:211], v[78:81], v[50:53]
	v_mfma_f32_16x16x32_bf16 v[2:5], v[212:215], v[78:81], v[2:5]
	ds_read_b128 v[78:81], v119 offset:38912
	s_waitcnt lgkmcnt(3)
	v_mfma_f32_16x16x32_bf16 v[6:9], v[216:219], v[66:69], v[6:9]
	s_waitcnt vmcnt(6)
	v_mfma_f32_16x16x32_bf16 v[30:33], v[220:223], v[66:69], v[30:33]
	v_mfma_f32_16x16x32_bf16 v[38:41], v[224:227], v[66:69], v[38:41]
	v_mfma_f32_16x16x32_bf16 v[42:45], v[228:231], v[66:69], v[42:45]
	v_cvt_f32_ubyte0_e32 v248, v232
	v_cvt_f32_ubyte1_e32 v249, v232
	v_cvt_f32_ubyte2_e32 v250, v232
	v_cvt_f32_ubyte3_e32 v251, v232
	v_mul_f32_e32 v248, s34, v248
	v_mul_f32_e32 v249, s34, v249
	v_mul_f32_e32 v250, s34, v250
	v_mul_f32_e32 v251, s34, v251
	v_fma_f32 v184, v6, v248, v184
	v_fma_f32 v185, v7, v249, v185
	v_fma_f32 v186, v8, v250, v186
	v_fma_f32 v187, v9, v251, v187
	s_waitcnt lgkmcnt(2)
	v_mfma_f32_16x16x32_bf16 v[46:49], v[216:219], v[70:73], v[46:49]
	v_cvt_f32_ubyte0_e32 v248, v233
	v_cvt_f32_ubyte1_e32 v249, v233
	v_cvt_f32_ubyte2_e32 v250, v233
	v_cvt_f32_ubyte3_e32 v251, v233
	v_mul_f32_e32 v248, s34, v248
	v_mul_f32_e32 v249, s34, v249
	v_mul_f32_e32 v250, s34, v250
	v_mul_f32_e32 v251, s34, v251
	v_fma_f32 v180, v30, v248, v180
	v_fma_f32 v181, v31, v249, v181
	v_fma_f32 v182, v32, v250, v182
	v_fma_f32 v183, v33, v251, v183
	v_mfma_f32_16x16x32_bf16 v[26:29], v[220:223], v[70:73], v[26:29]
	v_cvt_f32_ubyte0_e32 v248, v234
	v_cvt_f32_ubyte1_e32 v249, v234
	v_cvt_f32_ubyte2_e32 v250, v234
	v_cvt_f32_ubyte3_e32 v251, v234
	v_mul_f32_e32 v248, s34, v248
	v_mul_f32_e32 v249, s34, v249
	v_mul_f32_e32 v250, s34, v250
	v_mul_f32_e32 v251, s34, v251
	v_fma_f32 v176, v38, v248, v176
	v_fma_f32 v177, v39, v249, v177
	v_fma_f32 v178, v40, v250, v178
	v_fma_f32 v179, v41, v251, v179
	v_mfma_f32_16x16x32_bf16 v[14:17], v[224:227], v[70:73], v[14:17]
	v_cvt_f32_ubyte0_e32 v248, v235
	v_cvt_f32_ubyte1_e32 v249, v235
	v_cvt_f32_ubyte2_e32 v250, v235
	v_cvt_f32_ubyte3_e32 v251, v235
	v_mul_f32_e32 v248, s34, v248
	v_mul_f32_e32 v249, s34, v249
	v_mul_f32_e32 v250, s34, v250
	v_mul_f32_e32 v251, s34, v251
	v_fma_f32 v172, v42, v248, v172
	v_fma_f32 v173, v43, v249, v173
	v_fma_f32 v174, v44, v250, v174
	v_fma_f32 v175, v45, v251, v175
	v_mfma_f32_16x16x32_bf16 v[10:13], v[228:231], v[70:73], v[10:13]
	v_cvt_f32_ubyte0_e32 v248, v236
	v_cvt_f32_ubyte1_e32 v249, v236
	v_cvt_f32_ubyte2_e32 v250, v236
	v_cvt_f32_ubyte3_e32 v251, v236
	v_mul_f32_e32 v248, s34, v248
	v_mul_f32_e32 v249, s34, v249
	v_mul_f32_e32 v250, s34, v250
	v_mul_f32_e32 v251, s34, v251
	v_fma_f32 v168, v46, v248, v168
	v_fma_f32 v169, v47, v249, v169
	v_fma_f32 v170, v48, v250, v170
	v_fma_f32 v171, v49, v251, v171
	s_waitcnt lgkmcnt(0)
	s_barrier
	v_mfma_f32_16x16x32_bf16 v[34:37], v[216:219], v[74:77], v[34:37]
	v_cvt_f32_ubyte0_e32 v248, v237
	v_cvt_f32_ubyte1_e32 v249, v237
	v_cvt_f32_ubyte2_e32 v250, v237
	v_cvt_f32_ubyte3_e32 v251, v237
	v_mul_f32_e32 v248, s34, v248
	v_mul_f32_e32 v249, s34, v249
	v_mul_f32_e32 v250, s34, v250
	v_mul_f32_e32 v251, s34, v251
	v_fma_f32 v164, v26, v248, v164
	v_fma_f32 v165, v27, v249, v165
	v_fma_f32 v166, v28, v250, v166
	v_fma_f32 v167, v29, v251, v167
	v_mfma_f32_16x16x32_bf16 v[22:25], v[220:223], v[74:77], v[22:25]
	v_cvt_f32_ubyte0_e32 v248, v238
	v_cvt_f32_ubyte1_e32 v249, v238
	v_cvt_f32_ubyte2_e32 v250, v238
	v_cvt_f32_ubyte3_e32 v251, v238
	v_mul_f32_e32 v248, s34, v248
	v_mul_f32_e32 v249, s34, v249
	v_mul_f32_e32 v250, s34, v250
	v_mul_f32_e32 v251, s34, v251
	v_fma_f32 v160, v14, v248, v160
	v_fma_f32 v161, v15, v249, v161
	v_fma_f32 v162, v16, v250, v162
	v_fma_f32 v163, v17, v251, v163
	v_mfma_f32_16x16x32_bf16 v[18:21], v[224:227], v[74:77], v[18:21]
	v_cvt_f32_ubyte0_e32 v248, v239
	v_cvt_f32_ubyte1_e32 v249, v239
	v_cvt_f32_ubyte2_e32 v250, v239
	v_cvt_f32_ubyte3_e32 v251, v239
	v_mul_f32_e32 v248, s34, v248
	v_mul_f32_e32 v249, s34, v249
	v_mul_f32_e32 v250, s34, v250
	v_mul_f32_e32 v251, s34, v251
	v_fma_f32 v156, v10, v248, v156
	v_fma_f32 v157, v11, v249, v157
	v_fma_f32 v158, v12, v250, v158
	v_fma_f32 v159, v13, v251, v159
	v_mfma_f32_16x16x32_bf16 v[62:65], v[228:231], v[74:77], v[62:65]
	v_cvt_f32_ubyte0_e32 v248, v240
	v_cvt_f32_ubyte1_e32 v249, v240
	v_cvt_f32_ubyte2_e32 v250, v240
	v_cvt_f32_ubyte3_e32 v251, v240
	v_mul_f32_e32 v248, s34, v248
	v_mul_f32_e32 v249, s34, v249
	v_mul_f32_e32 v250, s34, v250
	v_mul_f32_e32 v251, s34, v251
	v_fma_f32 v136, v34, v248, v136
	v_fma_f32 v137, v35, v249, v137
	v_fma_f32 v150, v36, v250, v150
	v_fma_f32 v151, v37, v251, v151
	v_mfma_f32_16x16x32_bf16 v[58:61], v[216:219], v[78:81], v[58:61]
	v_cvt_f32_ubyte0_e32 v248, v241
	v_cvt_f32_ubyte1_e32 v249, v241
	v_cvt_f32_ubyte2_e32 v250, v241
	v_cvt_f32_ubyte3_e32 v251, v241
	v_mul_f32_e32 v248, s34, v248
	v_mul_f32_e32 v249, s34, v249
	v_mul_f32_e32 v250, s34, v250
	v_mul_f32_e32 v251, s34, v251
	v_fma_f32 v130, v22, v248, v130
	v_fma_f32 v131, v23, v249, v131
	v_fma_f32 v134, v24, v250, v134
	v_fma_f32 v135, v25, v251, v135
	v_mfma_f32_16x16x32_bf16 v[54:57], v[220:223], v[78:81], v[54:57]
	v_cvt_f32_ubyte0_e32 v248, v242
	v_cvt_f32_ubyte1_e32 v249, v242
	v_cvt_f32_ubyte2_e32 v250, v242
	v_cvt_f32_ubyte3_e32 v251, v242
	v_mul_f32_e32 v248, s34, v248
	v_mul_f32_e32 v249, s34, v249
	v_mul_f32_e32 v250, s34, v250
	v_mul_f32_e32 v251, s34, v251
	v_fma_f32 v124, v18, v248, v124
	v_fma_f32 v125, v19, v249, v125
	v_fma_f32 v126, v20, v250, v126
	v_fma_f32 v127, v21, v251, v127
	v_mfma_f32_16x16x32_bf16 v[50:53], v[224:227], v[78:81], v[50:53]
	v_cvt_f32_ubyte0_e32 v248, v243
	v_cvt_f32_ubyte1_e32 v249, v243
	v_cvt_f32_ubyte2_e32 v250, v243
	v_cvt_f32_ubyte3_e32 v251, v243
	v_mul_f32_e32 v248, s34, v248
	v_mul_f32_e32 v249, s34, v249
	v_mul_f32_e32 v250, s34, v250
	v_mul_f32_e32 v251, s34, v251
	v_fma_f32 v120, v62, v248, v120
	v_fma_f32 v121, v63, v249, v121
	v_fma_f32 v122, v64, v250, v122
	v_fma_f32 v123, v65, v251, v123
	v_mfma_f32_16x16x32_bf16 v[2:5], v[228:231], v[78:81], v[2:5]
	v_cvt_f32_ubyte0_e32 v248, v244
	v_cvt_f32_ubyte1_e32 v249, v244
	v_cvt_f32_ubyte2_e32 v250, v244
	v_cvt_f32_ubyte3_e32 v251, v244
	v_mul_f32_e32 v248, s34, v248
	v_mul_f32_e32 v249, s34, v249
	v_mul_f32_e32 v250, s34, v250
	v_mul_f32_e32 v251, s34, v251
	v_fma_f32 v114, v58, v248, v114
	v_fma_f32 v115, v59, v249, v115
	v_fma_f32 v116, v60, v250, v116
	v_fma_f32 v117, v61, v251, v117
	s_nop 7
	s_nop 3
	v_cvt_f32_ubyte0_e32 v248, v245
	v_cvt_f32_ubyte1_e32 v249, v245
	v_cvt_f32_ubyte2_e32 v250, v245
	v_cvt_f32_ubyte3_e32 v251, v245
	v_mul_f32_e32 v248, s34, v248
	v_mul_f32_e32 v249, s34, v249
	v_mul_f32_e32 v250, s34, v250
	v_mul_f32_e32 v251, s34, v251
	v_fma_f32 v106, v54, v248, v106
	v_fma_f32 v107, v55, v249, v107
	v_fma_f32 v108, v56, v250, v108
	v_fma_f32 v109, v57, v251, v109
	v_cvt_f32_ubyte0_e32 v248, v246
	v_cvt_f32_ubyte1_e32 v249, v246
	v_cvt_f32_ubyte2_e32 v250, v246
	v_cvt_f32_ubyte3_e32 v251, v246
	v_mul_f32_e32 v248, s34, v248
	v_mul_f32_e32 v249, s34, v249
	v_mul_f32_e32 v250, s34, v250
	v_mul_f32_e32 v251, s34, v251
	v_fma_f32 v100, v50, v248, v100
	v_fma_f32 v101, v51, v249, v101
	v_fma_f32 v102, v52, v250, v102
	v_fma_f32 v103, v53, v251, v103
	v_cvt_f32_ubyte0_e32 v248, v247
	v_cvt_f32_ubyte1_e32 v249, v247
	v_cvt_f32_ubyte2_e32 v250, v247
	v_cvt_f32_ubyte3_e32 v251, v247
	v_mul_f32_e32 v248, s34, v248
	v_mul_f32_e32 v249, s34, v249
	v_mul_f32_e32 v250, s34, v250
	v_mul_f32_e32 v251, s34, v251
	v_fma_f32 v96, v2, v248, v96
	v_fma_f32 v97, v3, v249, v97
	v_fma_f32 v98, v4, v250, v98
	v_fma_f32 v99, v5, v251, v99
	s_cmp_eq_u32 0, 0
	s_cbranch_scc0 .LBB0_1004
	v_lshlrev_b32_e32 v0, 1, v118
	v_lshl_add_u64 v[6:7], s[4:5], 0, v[0:1]
	v_lshlrev_b64 v[2:3], 11, v[112:113]
	v_lshl_add_u64 v[8:9], v[6:7], 0, v[2:3]
	v_cvt_pk_bf16_f32 v2, v184, v185
	v_cvt_pk_bf16_f32 v3, v186, v187
	v_cvt_pk_bf16_f32 v4, v180, v181
	v_cvt_pk_bf16_f32 v5, v182, v183
	global_store_dwordx4 v[8:9], v[2:5], off
	v_readlane_b32 s46, v254, 29
	s_mov_b32 s38, 0
	v_cvt_pk_bf16_f32 v2, v176, v177
	v_cvt_pk_bf16_f32 v3, v178, v179
	v_cvt_pk_bf16_f32 v4, v172, v173
	v_cvt_pk_bf16_f32 v5, v174, v175
	global_store_dwordx4 v[8:9], v[2:5], off offset:64
	v_readlane_b32 s47, v254, 30
	s_nop 0
	v_lshlrev_b64 v[2:3], 11, v[110:111]
	v_lshl_add_u64 v[8:9], v[6:7], 0, v[2:3]
	v_cvt_pk_bf16_f32 v2, v168, v169
	v_cvt_pk_bf16_f32 v3, v170, v171
	v_cvt_pk_bf16_f32 v4, v164, v165
	v_cvt_pk_bf16_f32 v5, v166, v167
	global_store_dwordx4 v[8:9], v[2:5], off
	s_nop 1
	v_cvt_pk_bf16_f32 v2, v160, v161
	v_cvt_pk_bf16_f32 v3, v162, v163
	v_cvt_pk_bf16_f32 v4, v156, v157
	v_cvt_pk_bf16_f32 v5, v158, v159
	global_store_dwordx4 v[8:9], v[2:5], off offset:64
	s_nop 1
	v_lshlrev_b64 v[2:3], 11, v[104:105]
	v_lshl_add_u64 v[8:9], v[6:7], 0, v[2:3]
	v_cvt_pk_bf16_f32 v2, v136, v137
	v_cvt_pk_bf16_f32 v3, v150, v151
	v_cvt_pk_bf16_f32 v4, v130, v131
	v_cvt_pk_bf16_f32 v5, v134, v135
	global_store_dwordx4 v[8:9], v[2:5], off
	s_nop 1
	v_cvt_pk_bf16_f32 v2, v124, v125
	v_cvt_pk_bf16_f32 v3, v126, v127
	v_cvt_pk_bf16_f32 v4, v120, v121
	v_cvt_pk_bf16_f32 v5, v122, v123
	global_store_dwordx4 v[8:9], v[2:5], off offset:64
	s_nop 1
	v_lshlrev_b64 v[2:3], 11, v[94:95]
	v_lshl_add_u64 v[6:7], v[6:7], 0, v[2:3]
	v_cvt_pk_bf16_f32 v2, v114, v115
	v_cvt_pk_bf16_f32 v3, v116, v117
	v_cvt_pk_bf16_f32 v4, v106, v107
	v_cvt_pk_bf16_f32 v5, v108, v109
	global_store_dwordx4 v[6:7], v[2:5], off
	s_nop 1
	v_cvt_pk_bf16_f32 v2, v100, v101
	v_cvt_pk_bf16_f32 v3, v102, v103
	v_cvt_pk_bf16_f32 v4, v96, v97
	v_cvt_pk_bf16_f32 v5, v98, v99
	global_store_dwordx4 v[6:7], v[2:5], off offset:64
